# GEMM epilogue tile stores use the non-temporal policy (on top of v73)
# baseline (speedup 1.0000x reference)
; __device__ __forceinline__ unsigned pk2(float a, float b) { return pg8::cvt_pk_bf16(a, b); }
;     __device__ __forceinline__ void operator()(const f32x4 (&acc)[2][2][4][2], const pg8::Unit& u, int wr, int wc, int fr, int fq) const {
;         const int row0 = u.pm * 256 + wr * 64 + fr, col0 = u.pn * 256 + wc * 32 + 8 * fq;
;         float rs[2][4];
; #pragma unroll
;         for (int ai = 0; ai < 2; ++ai)
; #pragma unroll
;             for (int m = 0; m < 4; ++m) rs[ai][m] = RS[row0 + ai * 128 + m * 16];
; #pragma unroll
;         for (int ai = 0; ai < 2; ++ai)
; #pragma unroll
;             for (int m = 0; m < 4; ++m) { bf16_t* rowp = O + (size_t)(row0 + ai * 128 + m * 16) * ldc + col0;
; #pragma unroll
;                 for (int bj = 0; bj < 2; ++bj) { const f32x4 v0 = acc[ai][bj][m][0] * rs[ai][m], v1 = acc[ai][bj][m][1] * rs[ai][m];
;                     u32x4 w; w.x = pk2(v0[0], v0[1]); w.y = pk2(v0[2], v0[3]); w.z = pk2(v1[0], v1[1]); w.w = pk2(v1[2], v1[3]);
;                     *(u32x4*)(rowp + bj * 128) = w; } }
;     }
.LBB0_70:
	v_lshl_add_u32 v146, s22, 8, v149
	v_or_b32_e32 v162, 16, v146
	v_ashrrev_i32_e32 v147, 31, v146
	v_ashrrev_i32_e32 v163, 31, v162
	v_or_b32_e32 v166, 32, v146
	v_lshl_add_u64 v[158:159], v[146:147], 2, s[6:7]
	v_lshl_add_u64 v[144:145], v[162:163], 2, s[6:7]
	v_ashrrev_i32_e32 v167, 31, v166
	global_load_dword v160, v[158:159], off
	global_load_dword v164, v[144:145], off
	v_lshl_add_u64 v[144:145], v[166:167], 2, s[6:7]
	global_load_dword v168, v[144:145], off
	v_or_b32_e32 v170, 48, v146
	v_ashrrev_i32_e32 v171, 31, v170
	v_lshl_add_u64 v[144:145], v[170:171], 2, s[6:7]
	global_load_dword v154, v[144:145], off
	v_lshl_or_b32 v172, s45, 8, v153
	v_mov_b64_e32 v[144:145], s[2:3]
	v_ashrrev_i32_e32 v173, 31, v172
	v_add_u32_e32 v165, 0x80, v146
	v_add_u32_e32 v169, 0x90, v146
	v_add_u32_e32 v171, 0xa0, v146
	v_add_u32_e32 v177, 0xb0, v146
	v_mad_i64_i32 v[174:175], s[24:25], v146, s44, v[144:145]
	v_lshlrev_b64 v[146:147], 1, v[172:173]
	v_lshl_add_u64 v[172:173], v[174:175], 0, v[146:147]
	global_load_dword v174, v[158:159], off offset:512
	global_load_dword v176, v[158:159], off offset:576
	global_load_dword v150, v[158:159], off offset:640
	global_load_dword v148, v[158:159], off offset:704
	v_mad_i64_i32 v[162:163], s[24:25], v162, s44, v[144:145]
	v_lshl_add_u64 v[162:163], v[162:163], 0, v[146:147]
	v_mad_i64_i32 v[166:167], s[24:25], v166, s44, v[144:145]
	v_lshl_add_u64 v[166:167], v[166:167], 0, v[146:147]
	s_andn2_b64 vcc, exec, s[0:1]
	s_mov_b64 s[0:1], -1
	s_waitcnt vmcnt(0)
	v_pk_mul_f32 v[122:123], v[122:123], v[160:161] op_sel_hi:[1,0]
	v_pk_mul_f32 v[126:127], v[126:127], v[160:161] op_sel_hi:[1,0]
	v_pk_mul_f32 v[124:125], v[124:125], v[160:161] op_sel_hi:[1,0]
	v_pk_mul_f32 v[120:121], v[120:121], v[160:161] op_sel_hi:[1,0]
	v_pk_mul_f32 v[110:111], v[110:111], v[160:161] op_sel_hi:[1,0]
	v_pk_mul_f32 v[108:109], v[108:109], v[160:161] op_sel_hi:[1,0]
	v_pk_mul_f32 v[158:159], v[102:103], v[160:161] op_sel_hi:[1,0]
	v_pk_mul_f32 v[160:161], v[100:101], v[160:161] op_sel_hi:[1,0]
	v_cvt_pk_bf16_f32 v100, v124, v125
	v_cvt_pk_bf16_f32 v101, v126, v127
	v_cvt_pk_bf16_f32 v102, v120, v121
	v_cvt_pk_bf16_f32 v103, v122, v123
	v_pk_mul_f32 v[122:123], v[80:81], v[168:169] op_sel_hi:[1,0]
	global_store_dwordx4 v[172:173], v[100:103], off nt
	v_cvt_pk_bf16_f32 v80, v108, v109
	v_cvt_pk_bf16_f32 v81, v110, v111
	v_pk_mul_f32 v[118:119], v[118:119], v[164:165] op_sel_hi:[1,0]
	v_pk_mul_f32 v[116:117], v[116:117], v[164:165] op_sel_hi:[1,0]
	v_pk_mul_f32 v[120:121], v[82:83], v[168:169] op_sel_hi:[1,0]
	v_cvt_pk_bf16_f32 v82, v160, v161
	v_cvt_pk_bf16_f32 v83, v158, v159
	global_store_dwordx4 v[172:173], v[80:83], off offset:256 nt
	v_pk_mul_f32 v[114:115], v[114:115], v[164:165] op_sel_hi:[1,0]
	v_pk_mul_f32 v[112:113], v[112:113], v[164:165] op_sel_hi:[1,0]
	v_cvt_pk_bf16_f32 v80, v116, v117
	v_cvt_pk_bf16_f32 v81, v118, v119
	v_pk_mul_f32 v[94:95], v[94:95], v[164:165] op_sel_hi:[1,0]
	v_pk_mul_f32 v[92:93], v[92:93], v[164:165] op_sel_hi:[1,0]
	v_cvt_pk_bf16_f32 v82, v112, v113
	v_cvt_pk_bf16_f32 v83, v114, v115
	global_store_dwordx4 v[162:163], v[80:83], off nt
	v_pk_mul_f32 v[90:91], v[90:91], v[164:165] op_sel_hi:[1,0]
	v_pk_mul_f32 v[88:89], v[88:89], v[164:165] op_sel_hi:[1,0]
	v_cvt_pk_bf16_f32 v80, v92, v93
	v_cvt_pk_bf16_f32 v81, v94, v95
	v_pk_mul_f32 v[106:107], v[106:107], v[168:169] op_sel_hi:[1,0]
	v_pk_mul_f32 v[104:105], v[104:105], v[168:169] op_sel_hi:[1,0]
	v_cvt_pk_bf16_f32 v82, v88, v89
	v_cvt_pk_bf16_f32 v83, v90, v91
	global_store_dwordx4 v[162:163], v[80:83], off offset:256 nt
	v_pk_mul_f32 v[98:99], v[98:99], v[168:169] op_sel_hi:[1,0]
	v_pk_mul_f32 v[96:97], v[96:97], v[168:169] op_sel_hi:[1,0]
	v_cvt_pk_bf16_f32 v80, v104, v105
	v_cvt_pk_bf16_f32 v81, v106, v107
	v_pk_mul_f32 v[86:87], v[86:87], v[168:169] op_sel_hi:[1,0]
	v_pk_mul_f32 v[84:85], v[84:85], v[168:169] op_sel_hi:[1,0]
	v_cvt_pk_bf16_f32 v82, v96, v97
	v_cvt_pk_bf16_f32 v83, v98, v99
	global_store_dwordx4 v[166:167], v[80:83], off nt
	v_pk_mul_f32 v[78:79], v[78:79], v[154:155] op_sel_hi:[1,0]
	v_pk_mul_f32 v[76:77], v[76:77], v[154:155] op_sel_hi:[1,0]
	v_cvt_pk_bf16_f32 v80, v84, v85
	v_cvt_pk_bf16_f32 v81, v86, v87
	v_cvt_pk_bf16_f32 v82, v122, v123
	v_cvt_pk_bf16_f32 v83, v120, v121
	global_store_dwordx4 v[166:167], v[80:83], off offset:256 nt
	v_pk_mul_f32 v[70:71], v[70:71], v[154:155] op_sel_hi:[1,0]
	v_pk_mul_f32 v[68:69], v[68:69], v[154:155] op_sel_hi:[1,0]
	v_mad_i64_i32 v[80:81], s[24:25], v170, s44, v[144:145]
	v_lshl_add_u64 v[80:81], v[80:81], 0, v[146:147]
	v_pk_mul_f32 v[82:83], v[74:75], v[154:155] op_sel_hi:[1,0]
; #define PG8_BAR __builtin_amdgcn_s_barrier()
; __device__ __forceinline__ unsigned pk2(float a, float b) { return pg8::cvt_pk_bf16(a, b); }
; template <class Epi, class Sched, bool ALIGN_EPI = false, bool SP2 = false>
; __device__ __forceinline__ void gemm_phase(PG8_LAS unsigned char* lds, const Gemm g, const Sched& S, const Epi& E) {
;     ...
;         if constexpr (ALIGN_EPI) { if (wr == 0) PG8_BAR; }
;         if constexpr (!Epi::AFTER_DRAIN) { E(acc, cur, wr, wc, fr, fq); S.done(cur); }
;         if (!has_next) break;
; #pragma unroll
;         for (int a = 0; a < 2; ++a)
; #pragma unroll
;             for (int b = 0; b < 2; ++b)
; #pragma unroll
;                 for (int m = 0; m < 4; ++m)
; #pragma unroll
;                     for (int n = 0; n < 2; ++n) acc[a][b][m][n] = (f32x4){0.f, 0.f, 0.f, 0.f};
;         cur = nxt; cA = nA; cB = nB; ++ui;
;         if constexpr (ALIGN_EPI) { if (wr == 1) PG8_BAR; }
;     __device__ __forceinline__ void operator()(const f32x4 (&acc)[2][2][4][2], const pg8::Unit& u, int wr, int wc, int fr, int fq) const {
;     ...
;         for (int ai = 0; ai < 2; ++ai)
; #pragma unroll
;             for (int m = 0; m < 4; ++m) { bf16_t* rowp = O + (size_t)(row0 + ai * 128 + m * 16) * ldc + col0;
; #pragma unroll
;                 for (int bj = 0; bj < 2; ++bj) { const f32x4 v0 = acc[ai][bj][m][0] * rs[ai][m], v1 = acc[ai][bj][m][1] * rs[ai][m];
;                     u32x4 w; w.x = pk2(v0[0], v0[1]); w.y = pk2(v0[2], v0[3]); w.z = pk2(v1[0], v1[1]); w.w = pk2(v1[2], v1[3]);
;                     *(u32x4*)(rowp + bj * 128) = w; } }
	v_pk_mul_f32 v[74:75], v[72:73], v[154:155] op_sel_hi:[1,0]
	v_cvt_pk_bf16_f32 v72, v76, v77
	v_cvt_pk_bf16_f32 v73, v78, v79
	v_pk_mul_f32 v[62:63], v[62:63], v[174:175] op_sel_hi:[1,0]
	v_cvt_pk_bf16_f32 v74, v74, v75
	v_cvt_pk_bf16_f32 v75, v82, v83
	global_store_dwordx4 v[80:81], v[72:75], off nt
	v_pk_mul_f32 v[60:61], v[60:61], v[174:175] op_sel_hi:[1,0]
	v_pk_mul_f32 v[54:55], v[54:55], v[174:175] op_sel_hi:[1,0]
	v_pk_mul_f32 v[72:73], v[66:67], v[154:155] op_sel_hi:[1,0]
	v_pk_mul_f32 v[66:67], v[64:65], v[154:155] op_sel_hi:[1,0]
	v_cvt_pk_bf16_f32 v64, v68, v69
	v_cvt_pk_bf16_f32 v65, v70, v71
	v_pk_mul_f32 v[52:53], v[52:53], v[174:175] op_sel_hi:[1,0]
	v_cvt_pk_bf16_f32 v66, v66, v67
	v_cvt_pk_bf16_f32 v67, v72, v73
	global_store_dwordx4 v[80:81], v[64:67], off offset:256 nt
	v_pk_mul_f32 v[48:49], v[48:49], v[176:177] op_sel_hi:[1,0]
	v_pk_mul_f32 v[38:39], v[38:39], v[176:177] op_sel_hi:[1,0]
	v_mad_i64_i32 v[64:65], s[24:25], v165, s44, v[144:145]
	v_lshl_add_u64 v[64:65], v[64:65], 0, v[146:147]
	v_pk_mul_f32 v[66:67], v[58:59], v[174:175] op_sel_hi:[1,0]
	v_pk_mul_f32 v[58:59], v[56:57], v[174:175] op_sel_hi:[1,0]
	v_cvt_pk_bf16_f32 v56, v60, v61
	v_cvt_pk_bf16_f32 v57, v62, v63
	v_pk_mul_f32 v[36:37], v[36:37], v[176:177] op_sel_hi:[1,0]
	v_cvt_pk_bf16_f32 v58, v58, v59
	v_cvt_pk_bf16_f32 v59, v66, v67
	global_store_dwordx4 v[64:65], v[56:59], off nt
	v_pk_mul_f32 v[32:33], v[32:33], v[150:151] op_sel_hi:[1,0]
	v_pk_mul_f32 v[22:23], v[22:23], v[150:151] op_sel_hi:[1,0]
	v_pk_mul_f32 v[56:57], v[46:47], v[174:175] op_sel_hi:[1,0]
	v_pk_mul_f32 v[46:47], v[44:45], v[174:175] op_sel_hi:[1,0]
	v_cvt_pk_bf16_f32 v44, v52, v53
	v_cvt_pk_bf16_f32 v45, v54, v55
	v_pk_mul_f32 v[20:21], v[20:21], v[150:151] op_sel_hi:[1,0]
	v_cvt_pk_bf16_f32 v46, v46, v47
	v_cvt_pk_bf16_f32 v47, v56, v57
	global_store_dwordx4 v[64:65], v[44:47], off offset:256 nt
	v_pk_mul_f32 v[16:17], v[16:17], v[148:149] op_sel_hi:[1,0]
	v_pk_mul_f32 v[6:7], v[6:7], v[148:149] op_sel_hi:[1,0]
	v_mad_i64_i32 v[44:45], s[24:25], v169, s44, v[144:145]
	v_lshl_add_u64 v[44:45], v[44:45], 0, v[146:147]
	v_pk_mul_f32 v[46:47], v[50:51], v[176:177] op_sel_hi:[1,0]
	v_pk_mul_f32 v[50:51], v[42:43], v[176:177] op_sel_hi:[1,0]
	v_pk_mul_f32 v[42:43], v[40:41], v[176:177] op_sel_hi:[1,0]
	v_cvt_pk_bf16_f32 v40, v48, v49
	v_cvt_pk_bf16_f32 v41, v46, v47
	v_pk_mul_f32 v[4:5], v[4:5], v[148:149] op_sel_hi:[1,0]
	v_cvt_pk_bf16_f32 v42, v42, v43
	v_cvt_pk_bf16_f32 v43, v50, v51
	global_store_dwordx4 v[44:45], v[40:43], off nt
	s_nop 1
	v_pk_mul_f32 v[40:41], v[30:31], v[176:177] op_sel_hi:[1,0]
	v_pk_mul_f32 v[30:31], v[28:29], v[176:177] op_sel_hi:[1,0]
	v_cvt_pk_bf16_f32 v28, v36, v37
	v_cvt_pk_bf16_f32 v29, v38, v39
	s_nop 0
	v_cvt_pk_bf16_f32 v30, v30, v31
	v_cvt_pk_bf16_f32 v31, v40, v41
	global_store_dwordx4 v[44:45], v[28:31], off offset:256 nt
	s_nop 1
	v_mad_i64_i32 v[28:29], s[24:25], v171, s44, v[144:145]
	v_lshl_add_u64 v[28:29], v[28:29], 0, v[146:147]
	v_pk_mul_f32 v[30:31], v[34:35], v[150:151] op_sel_hi:[1,0]
	v_pk_mul_f32 v[34:35], v[26:27], v[150:151] op_sel_hi:[1,0]
	v_pk_mul_f32 v[26:27], v[24:25], v[150:151] op_sel_hi:[1,0]
	v_cvt_pk_bf16_f32 v24, v32, v33
	v_cvt_pk_bf16_f32 v25, v30, v31
	s_nop 0
	v_cvt_pk_bf16_f32 v26, v26, v27
	v_cvt_pk_bf16_f32 v27, v34, v35
	global_store_dwordx4 v[28:29], v[24:27], off nt
	s_nop 1
	v_pk_mul_f32 v[24:25], v[14:15], v[150:151] op_sel_hi:[1,0]
	v_pk_mul_f32 v[14:15], v[12:13], v[150:151] op_sel_hi:[1,0]
	v_cvt_pk_bf16_f32 v12, v20, v21
	v_cvt_pk_bf16_f32 v13, v22, v23
	s_nop 0
	v_cvt_pk_bf16_f32 v14, v14, v15
	v_cvt_pk_bf16_f32 v15, v24, v25
	global_store_dwordx4 v[28:29], v[12:15], off offset:256 nt
	s_nop 1
	v_mad_i64_i32 v[12:13], s[24:25], v177, s44, v[144:145]
	v_lshl_add_u64 v[12:13], v[12:13], 0, v[146:147]
	v_pk_mul_f32 v[14:15], v[18:19], v[148:149] op_sel_hi:[1,0]
	v_pk_mul_f32 v[18:19], v[10:11], v[148:149] op_sel_hi:[1,0]
	v_pk_mul_f32 v[10:11], v[8:9], v[148:149] op_sel_hi:[1,0]
	v_cvt_pk_bf16_f32 v8, v16, v17
	v_cvt_pk_bf16_f32 v9, v14, v15
	s_nop 0
	v_cvt_pk_bf16_f32 v10, v10, v11
	v_cvt_pk_bf16_f32 v11, v18, v19
	global_store_dwordx4 v[12:13], v[8:11], off nt
	s_nop 1
	v_pk_mul_f32 v[8:9], v[2:3], v[148:149] op_sel_hi:[1,0]
	v_pk_mul_f32 v[2:3], v[0:1], v[148:149] op_sel_hi:[1,0]
	v_cvt_pk_bf16_f32 v0, v4, v5
	v_cvt_pk_bf16_f32 v1, v6, v7
	s_nop 0
	v_cvt_pk_bf16_f32 v2, v2, v3
	v_cvt_pk_bf16_f32 v3, v8, v9
	global_store_dwordx4 v[12:13], v[0:3], off offset:256 nt
	s_cbranch_vccnz .LBB0_63
	s_andn2_b64 vcc, exec, s[4:5]
	s_cbranch_vccnz .LBB0_62
	s_barrier
	s_branch .LBB0_62

; __device__ __forceinline__ unsigned pk2(float a, float b) { return pg8::cvt_pk_bf16(a, b); }
; __device__ __forceinline__ void unpack8(const u32x4 w, float (&f)[8]) { f[0] = bf_lo(w.x); f[1] = bf_hi(w.x); f[2] = bf_lo(w.y); f[3] = bf_hi(w.y); f[4] = bf_lo(w.z); f[5] = bf_hi(w.z); f[6] = bf_lo(w.w); f[7] = bf_hi(w.w); }
;     __device__ __forceinline__ void operator()(f32x4 (&acc)[2][2][4][2], const pg8::Unit& u, int wr, int wc, int fr, int fq) const {
;     ...
;         for (int ai = 0; ai < 2; ++ai) {
;             u32x4 rx[4][2];
; #pragma unroll
;             for (int m = 0; m < 4; ++m)
; #pragma unroll
;                 for (int bj = 0; bj < 2; ++bj) rx[m][bj] = *(const u32x4*)(XB + (size_t)(row0 + ai * 128 + m * 16) * 1024 + col0 + bj * 128);
; #pragma unroll
;             for (int m = 0; m < 4; ++m) { const int row = row0 + ai * 128 + m * 16; float s = 0.f;
; #pragma unroll
;                 for (int bj = 0; bj < 2; ++bj) { float f[8]; unpack8(rx[m][bj], f);
;                     const f32x4 v0 = acc[ai][bj][m][0] + (f32x4){f[0], f[1], f[2], f[3]}, v1 = acc[ai][bj][m][1] + (f32x4){f[4], f[5], f[6], f[7]};
;                     s += (v0[0] * v0[0] + v0[1] * v0[1]) + (v0[2] * v0[2] + v0[3] * v0[3]) + (v1[0] * v1[0] + v1[1] * v1[1]) + (v1[2] * v1[2] + v1[3] * v1[3]);
;                     u32x4 w; w.x = pk2(v0[0], v0[1]); w.y = pk2(v0[2], v0[3]); w.z = pk2(v1[0], v1[1]); w.w = pk2(v1[2], v1[3]);
;                     *(u32x4*)(YB + (size_t)row * 1024 + col0 + bj * 128) = w; }
;                 s += __shfl_xor(s, 16); s += __shfl_xor(s, 32); if (fq == 0) SS[(size_t)row * 16 + u.pn * 4 + wc] = s; }
.LBB0_663:
	v_lshl_or_b32 v170, s8, 8, v190
	v_lshl_add_u32 v174, s36, 8, v188
	v_ashrrev_i32_e32 v171, 31, v170
	v_lshlrev_b64 v[204:205], 1, v[170:171]
	v_ashrrev_i32_e32 v175, 31, v174
	v_lshl_add_u64 v[172:173], s[78:79], 0, v[204:205]
	v_lshlrev_b64 v[206:207], 11, v[174:175]
	v_lshl_add_u64 v[128:129], v[172:173], 0, v[206:207]
	global_load_dwordx4 v[196:199], v[128:129], off
	global_load_dwordx4 v[200:203], v[128:129], off offset:256
	v_or_b32_e32 v184, 16, v174
	v_or_b32_e32 v180, 32, v174
	v_or_b32_e32 v176, 48, v174
	v_ashrrev_i32_e32 v185, 31, v184
	v_ashrrev_i32_e32 v181, 31, v180
	v_ashrrev_i32_e32 v177, 31, v176
	v_lshlrev_b64 v[186:187], 11, v[184:185]
	v_lshlrev_b64 v[182:183], 11, v[180:181]
	v_lshlrev_b64 v[178:179], 11, v[176:177]
	v_lshl_add_u64 v[128:129], v[172:173], 0, v[186:187]
	v_lshl_add_u64 v[130:131], v[172:173], 0, v[182:183]
	v_lshl_add_u64 v[208:209], v[172:173], 0, v[178:179]
	global_load_dwordx4 v[148:151], v[128:129], off
	global_load_dwordx4 v[144:147], v[128:129], off offset:256
	global_load_dwordx4 v[140:143], v[130:131], off
	global_load_dwordx4 v[136:139], v[130:131], off offset:256
	global_load_dwordx4 v[132:135], v[208:209], off
	s_nop 0
	global_load_dwordx4 v[128:131], v[208:209], off offset:256
	v_and_b32_e32 v208, 64, v194
	v_xor_b32_e32 v195, 16, v194
	v_add_u32_e32 v208, 64, v208
	v_xor_b32_e32 v209, 32, v194
	v_cmp_lt_i32_e32 vcc, v195, v208
	v_lshl_add_u64 v[206:207], s[2:3], 0, v[206:207]
	v_lshl_add_u64 v[204:205], v[206:207], 0, v[204:205]
	v_cndmask_b32_e32 v195, v194, v195, vcc
	v_cmp_lt_i32_e32 vcc, v209, v208
	v_lshlrev_b32_e32 v195, 2, v195
	s_lshl_b32 s36, s8, 2
	v_cndmask_b32_e32 v214, v194, v209, vcc
	s_ashr_i32 s37, s36, 31
	s_waitcnt vmcnt(0)
	v_lshlrev_b32_e32 v206, 16, v196
	v_and_b32_e32 v207, 0xffff0000, v196
	v_lshlrev_b32_e32 v196, 16, v197
	v_and_b32_e32 v197, 0xffff0000, v197
	v_lshlrev_b32_e32 v210, 16, v200
	v_and_b32_e32 v211, 0xffff0000, v200
	v_lshlrev_b32_e32 v200, 16, v201
	v_and_b32_e32 v201, 0xffff0000, v201
	v_lshlrev_b32_e32 v208, 16, v198
	v_and_b32_e32 v209, 0xffff0000, v198
	v_lshlrev_b32_e32 v198, 16, v199
	v_and_b32_e32 v199, 0xffff0000, v199
	v_lshlrev_b32_e32 v212, 16, v202
	v_and_b32_e32 v213, 0xffff0000, v202
	v_lshlrev_b32_e32 v202, 16, v203
	v_and_b32_e32 v203, 0xffff0000, v203
	v_pk_add_f32 v[126:127], v[126:127], v[196:197]
	v_pk_add_f32 v[124:125], v[124:125], v[206:207]
	v_pk_add_f32 v[118:119], v[118:119], v[200:201]
	v_pk_add_f32 v[116:117], v[116:117], v[210:211]
	v_pk_add_f32 v[122:123], v[122:123], v[198:199]
	v_pk_add_f32 v[120:121], v[120:121], v[208:209]
	v_pk_add_f32 v[196:197], v[114:115], v[202:203]
	v_pk_add_f32 v[198:199], v[112:113], v[212:213]
	v_mul_f32_e32 v114, v125, v125
	v_mul_f32_e32 v115, v127, v127
	v_cvt_pk_bf16_f32 v112, v124, v125
	v_cvt_pk_bf16_f32 v113, v126, v127
	v_mul_f32_e32 v125, v117, v117
	v_mul_f32_e32 v127, v119, v119
	v_mul_f32_e32 v200, v121, v121
	v_mul_f32_e32 v202, v199, v199
	v_fmac_f32_e32 v114, v124, v124
	v_fmac_f32_e32 v115, v126, v126
	v_fmac_f32_e32 v125, v116, v116
	v_fmac_f32_e32 v127, v118, v118
	v_mul_f32_e32 v201, v123, v123
	v_mul_f32_e32 v203, v197, v197
	v_fmac_f32_e32 v200, v120, v120
	v_fmac_f32_e32 v202, v198, v198
	v_add_f32_e32 v114, v114, v115
	v_add_f32_e32 v115, v125, v127
	v_fmac_f32_e32 v201, v122, v122
	v_fmac_f32_e32 v203, v196, v196
	v_add_f32_e32 v114, v200, v114
	v_add_f32_e32 v115, v202, v115
	v_add_f32_e32 v114, v201, v114
	v_add_f32_e32 v115, v203, v115
	v_add_f32_e32 v124, v114, v115
	ds_bpermute_b32 v125, v195, v124
	v_cvt_pk_bf16_f32 v114, v120, v121
	v_cvt_pk_bf16_f32 v115, v122, v123
	global_store_dwordx4 v[204:205], v[112:115], off nt
	v_cvt_pk_bf16_f32 v116, v116, v117
	v_cvt_pk_bf16_f32 v117, v118, v119
	v_cvt_pk_bf16_f32 v118, v198, v199
	v_cvt_pk_bf16_f32 v119, v196, v197
	global_store_dwordx4 v[204:205], v[116:119], off offset:256 nt
	s_waitcnt lgkmcnt(0)
	v_add_f32_e32 v113, v124, v125
	v_lshlrev_b32_e32 v112, 2, v214
	ds_bpermute_b32 v114, v112, v113
	s_and_saveexec_b64 s[38:39], s[0:1]
	s_cbranch_execz .LBB0_665
	v_lshlrev_b64 v[116:117], 6, v[174:175]
	v_lshl_add_u64 v[116:117], s[20:21], 0, v[116:117]
	v_lshl_add_u64 v[116:117], s[36:37], 2, v[116:117]
	s_lshl_b32 s8, s48, 2
	v_lshl_add_u64 v[116:117], v[116:117], 0, s[8:9]
	s_waitcnt lgkmcnt(0)
	v_add_f32_e32 v113, v113, v114
	global_store_dword v[116:117], v113, off
; __device__ __forceinline__ unsigned pk2(float a, float b) { return pg8::cvt_pk_bf16(a, b); }
; __device__ __forceinline__ void unpack8(const u32x4 w, float (&f)[8]) { f[0] = bf_lo(w.x); f[1] = bf_hi(w.x); f[2] = bf_lo(w.y); f[3] = bf_hi(w.y); f[4] = bf_lo(w.z); f[5] = bf_hi(w.z); f[6] = bf_lo(w.w); f[7] = bf_hi(w.w); }
;     __device__ __forceinline__ void operator()(f32x4 (&acc)[2][2][4][2], const pg8::Unit& u, int wr, int wc, int fr, int fq) const {
;     ...
;             for (int m = 0; m < 4; ++m) { const int row = row0 + ai * 128 + m * 16; float s = 0.f;
; #pragma unroll
;                 for (int bj = 0; bj < 2; ++bj) { float f[8]; unpack8(rx[m][bj], f);
;                     const f32x4 v0 = acc[ai][bj][m][0] + (f32x4){f[0], f[1], f[2], f[3]}, v1 = acc[ai][bj][m][1] + (f32x4){f[4], f[5], f[6], f[7]};
;                     s += (v0[0] * v0[0] + v0[1] * v0[1]) + (v0[2] * v0[2] + v0[3] * v0[3]) + (v1[0] * v1[0] + v1[1] * v1[1]) + (v1[2] * v1[2] + v1[3] * v1[3]);
;                     u32x4 w; w.x = pk2(v0[0], v0[1]); w.y = pk2(v0[2], v0[3]); w.z = pk2(v1[0], v1[1]); w.w = pk2(v1[2], v1[3]);
;                     *(u32x4*)(YB + (size_t)row * 1024 + col0 + bj * 128) = w; }
;                 s += __shfl_xor(s, 16); s += __shfl_xor(s, 32); if (fq == 0) SS[(size_t)row * 16 + u.pn * 4 + wc] = s; }
.LBB0_665:
	s_or_b64 exec, exec, s[38:39]
	s_waitcnt lgkmcnt(0)
	v_lshlrev_b32_e32 v114, 16, v148
	v_and_b32_e32 v115, 0xffff0000, v148
	v_lshlrev_b32_e32 v116, 16, v149
	v_and_b32_e32 v117, 0xffff0000, v149
	v_lshlrev_b32_e32 v118, 16, v150
	v_and_b32_e32 v119, 0xffff0000, v150
	v_lshlrev_b32_e32 v120, 16, v151
	v_and_b32_e32 v121, 0xffff0000, v151
	v_pk_add_f32 v[110:111], v[110:111], v[116:117]
	v_pk_add_f32 v[108:109], v[108:109], v[114:115]
	v_pk_add_f32 v[114:115], v[106:107], v[120:121]
	v_pk_add_f32 v[106:107], v[104:105], v[118:119]
	v_mul_f32_e32 v104, v109, v109
	v_mul_f32_e32 v105, v111, v111
	v_fmac_f32_e32 v104, v108, v108
	v_fmac_f32_e32 v105, v110, v110
	v_add_f32_e32 v104, v104, v105
	v_mul_f32_e32 v105, v107, v107
	v_fmac_f32_e32 v105, v106, v106
	v_lshlrev_b32_e32 v122, 16, v144
	v_and_b32_e32 v123, 0xffff0000, v144
	v_lshlrev_b32_e32 v124, 16, v145
	v_and_b32_e32 v125, 0xffff0000, v145
	v_add_f32_e32 v104, v105, v104
	v_mul_f32_e32 v105, v115, v115
	v_lshlrev_b32_e32 v126, 16, v146
	v_and_b32_e32 v127, 0xffff0000, v146
	v_fmac_f32_e32 v105, v114, v114
	v_pk_add_f32 v[102:103], v[102:103], v[124:125]
	v_pk_add_f32 v[100:101], v[100:101], v[122:123]
	v_add_f32_e32 v113, v105, v104
	v_cvt_pk_bf16_f32 v104, v108, v109
	v_cvt_pk_bf16_f32 v105, v110, v111
	v_pk_add_f32 v[110:111], v[96:97], v[126:127]
	v_mul_f32_e32 v96, v101, v101
	v_mul_f32_e32 v97, v103, v103
	v_fmac_f32_e32 v96, v100, v100
	v_fmac_f32_e32 v97, v102, v102
	v_lshlrev_b32_e32 v144, 16, v147
	v_and_b32_e32 v145, 0xffff0000, v147
	v_add_f32_e32 v96, v96, v97
	v_mul_f32_e32 v97, v111, v111
	v_pk_add_f32 v[108:109], v[98:99], v[144:145]
	v_fmac_f32_e32 v97, v110, v110
	v_add_f32_e32 v96, v97, v96
	v_mul_f32_e32 v97, v109, v109
	v_fmac_f32_e32 v97, v108, v108
	v_add_f32_e32 v96, v97, v96
	v_add_f32_e32 v99, v113, v96
	ds_bpermute_b32 v113, v195, v99
	v_lshl_add_u64 v[96:97], s[2:3], 0, v[186:187]
	v_cvt_pk_bf16_f32 v106, v106, v107
	v_cvt_pk_bf16_f32 v107, v114, v115
	v_lshl_add_u64 v[114:115], v[170:171], 1, v[96:97]
	s_waitcnt lgkmcnt(0)
	v_add_f32_e32 v96, v99, v113
	ds_bpermute_b32 v97, v112, v96
	global_store_dwordx4 v[114:115], v[104:107], off nt
	v_cvt_pk_bf16_f32 v98, v100, v101
	v_cvt_pk_bf16_f32 v99, v102, v103
	v_cvt_pk_bf16_f32 v100, v110, v111
	v_cvt_pk_bf16_f32 v101, v108, v109
	global_store_dwordx4 v[114:115], v[98:101], off offset:256 nt
	s_and_saveexec_b64 s[38:39], s[0:1]
	s_cbranch_execz .LBB0_667
	v_lshlrev_b64 v[98:99], 6, v[184:185]
	v_lshl_add_u64 v[98:99], s[20:21], 0, v[98:99]
	v_lshl_add_u64 v[98:99], s[36:37], 2, v[98:99]
	s_lshl_b32 s8, s48, 2
	v_lshl_add_u64 v[98:99], v[98:99], 0, s[8:9]
	s_waitcnt lgkmcnt(0)
	v_add_f32_e32 v96, v96, v97
	global_store_dword v[98:99], v96, off
.LBB0_667:
	s_or_b64 exec, exec, s[38:39]
	v_lshlrev_b32_e32 v96, 16, v140
	s_waitcnt lgkmcnt(0)
	v_and_b32_e32 v97, 0xffff0000, v140
	v_lshlrev_b32_e32 v98, 16, v141
	v_and_b32_e32 v99, 0xffff0000, v141
	v_lshlrev_b32_e32 v100, 16, v142
	v_and_b32_e32 v101, 0xffff0000, v142
	v_lshlrev_b32_e32 v102, 16, v143
	v_and_b32_e32 v103, 0xffff0000, v143
	v_pk_add_f32 v[94:95], v[94:95], v[98:99]
	v_pk_add_f32 v[92:93], v[92:93], v[96:97]
	v_pk_add_f32 v[96:97], v[90:91], v[102:103]
	v_pk_add_f32 v[90:91], v[88:89], v[100:101]
	v_mul_f32_e32 v88, v93, v93
	v_mul_f32_e32 v89, v95, v95
	v_fmac_f32_e32 v88, v92, v92
	v_fmac_f32_e32 v89, v94, v94
	v_add_f32_e32 v88, v88, v89
	v_mul_f32_e32 v89, v91, v91
	v_fmac_f32_e32 v89, v90, v90
	v_lshlrev_b32_e32 v104, 16, v136
	v_and_b32_e32 v105, 0xffff0000, v136
	v_lshlrev_b32_e32 v106, 16, v137
	v_and_b32_e32 v107, 0xffff0000, v137
	v_add_f32_e32 v88, v89, v88
	v_mul_f32_e32 v89, v97, v97
	v_lshlrev_b32_e32 v108, 16, v138
	v_and_b32_e32 v109, 0xffff0000, v138
	v_fmac_f32_e32 v89, v96, v96
	v_pk_add_f32 v[86:87], v[86:87], v[106:107]
	v_pk_add_f32 v[84:85], v[84:85], v[104:105]
	v_add_f32_e32 v98, v89, v88
	v_cvt_pk_bf16_f32 v88, v92, v93
	v_cvt_pk_bf16_f32 v89, v94, v95
	v_pk_add_f32 v[94:95], v[80:81], v[108:109]
	v_mul_f32_e32 v80, v85, v85
	v_mul_f32_e32 v81, v87, v87
	v_fmac_f32_e32 v80, v84, v84
	v_fmac_f32_e32 v81, v86, v86
	v_lshlrev_b32_e32 v110, 16, v139
	v_and_b32_e32 v111, 0xffff0000, v139
	v_add_f32_e32 v80, v80, v81
	v_mul_f32_e32 v81, v95, v95
	v_pk_add_f32 v[92:93], v[82:83], v[110:111]
	v_fmac_f32_e32 v81, v94, v94
	v_add_f32_e32 v80, v81, v80
	v_mul_f32_e32 v81, v93, v93
	v_fmac_f32_e32 v81, v92, v92
	v_add_f32_e32 v80, v81, v80
	v_add_f32_e32 v83, v98, v80
	ds_bpermute_b32 v98, v195, v83
	v_lshl_add_u64 v[80:81], s[2:3], 0, v[182:183]
	v_cvt_pk_bf16_f32 v90, v90, v91
	v_cvt_pk_bf16_f32 v91, v96, v97
	v_lshl_add_u64 v[96:97], v[170:171], 1, v[80:81]
	s_waitcnt lgkmcnt(0)
	v_add_f32_e32 v80, v83, v98
	ds_bpermute_b32 v81, v112, v80
	global_store_dwordx4 v[96:97], v[88:91], off nt
	v_cvt_pk_bf16_f32 v82, v84, v85
	v_cvt_pk_bf16_f32 v83, v86, v87
	v_cvt_pk_bf16_f32 v84, v94, v95
	v_cvt_pk_bf16_f32 v85, v92, v93
	global_store_dwordx4 v[96:97], v[82:85], off offset:256 nt
	s_and_saveexec_b64 s[38:39], s[0:1]
	s_cbranch_execz .LBB0_669
	v_lshlrev_b64 v[82:83], 6, v[180:181]
	v_lshl_add_u64 v[82:83], s[20:21], 0, v[82:83]
	v_lshl_add_u64 v[82:83], s[36:37], 2, v[82:83]
	s_lshl_b32 s8, s48, 2
	v_lshl_add_u64 v[82:83], v[82:83], 0, s[8:9]
	s_waitcnt lgkmcnt(0)
	v_add_f32_e32 v80, v80, v81
	global_store_dword v[82:83], v80, off
; __device__ __forceinline__ unsigned pk2(float a, float b) { return pg8::cvt_pk_bf16(a, b); }
; __device__ __forceinline__ void unpack8(const u32x4 w, float (&f)[8]) { f[0] = bf_lo(w.x); f[1] = bf_hi(w.x); f[2] = bf_lo(w.y); f[3] = bf_hi(w.y); f[4] = bf_lo(w.z); f[5] = bf_hi(w.z); f[6] = bf_lo(w.w); f[7] = bf_hi(w.w); }
;     __device__ __forceinline__ void operator()(f32x4 (&acc)[2][2][4][2], const pg8::Unit& u, int wr, int wc, int fr, int fq) const {
;     ...
;                 for (int bj = 0; bj < 2; ++bj) rx[m][bj] = *(const u32x4*)(XB + (size_t)(row0 + ai * 128 + m * 16) * 1024 + col0 + bj * 128);
;     ...
;             for (int m = 0; m < 4; ++m) { const int row = row0 + ai * 128 + m * 16; float s = 0.f;
; #pragma unroll
;                 for (int bj = 0; bj < 2; ++bj) { float f[8]; unpack8(rx[m][bj], f);
;                     const f32x4 v0 = acc[ai][bj][m][0] + (f32x4){f[0], f[1], f[2], f[3]}, v1 = acc[ai][bj][m][1] + (f32x4){f[4], f[5], f[6], f[7]};
;                     s += (v0[0] * v0[0] + v0[1] * v0[1]) + (v0[2] * v0[2] + v0[3] * v0[3]) + (v1[0] * v1[0] + v1[1] * v1[1]) + (v1[2] * v1[2] + v1[3] * v1[3]);
;                     u32x4 w; w.x = pk2(v0[0], v0[1]); w.y = pk2(v0[2], v0[3]); w.z = pk2(v1[0], v1[1]); w.w = pk2(v1[2], v1[3]);
;                     *(u32x4*)(YB + (size_t)row * 1024 + col0 + bj * 128) = w; }
;                 s += __shfl_xor(s, 16); s += __shfl_xor(s, 32); if (fq == 0) SS[(size_t)row * 16 + u.pn * 4 + wc] = s; }
.LBB0_669:
	s_or_b64 exec, exec, s[38:39]
	v_lshlrev_b32_e32 v80, 16, v132
	s_waitcnt lgkmcnt(0)
	v_and_b32_e32 v81, 0xffff0000, v132
	v_lshlrev_b32_e32 v82, 16, v133
	v_and_b32_e32 v83, 0xffff0000, v133
	v_lshlrev_b32_e32 v84, 16, v134
	v_and_b32_e32 v85, 0xffff0000, v134
	v_lshlrev_b32_e32 v86, 16, v135
	v_and_b32_e32 v87, 0xffff0000, v135
	v_pk_add_f32 v[78:79], v[78:79], v[82:83]
	v_pk_add_f32 v[76:77], v[76:77], v[80:81]
	v_pk_add_f32 v[80:81], v[74:75], v[86:87]
	v_pk_add_f32 v[74:75], v[72:73], v[84:85]
	v_mul_f32_e32 v72, v77, v77
	v_mul_f32_e32 v73, v79, v79
	v_fmac_f32_e32 v72, v76, v76
	v_fmac_f32_e32 v73, v78, v78
	v_add_f32_e32 v72, v72, v73
	v_mul_f32_e32 v73, v75, v75
	v_fmac_f32_e32 v73, v74, v74
	v_lshlrev_b32_e32 v88, 16, v128
	v_and_b32_e32 v89, 0xffff0000, v128
	v_lshlrev_b32_e32 v90, 16, v129
	v_and_b32_e32 v91, 0xffff0000, v129
	v_add_f32_e32 v72, v73, v72
	v_mul_f32_e32 v73, v81, v81
	v_lshlrev_b32_e32 v92, 16, v130
	v_and_b32_e32 v93, 0xffff0000, v130
	v_fmac_f32_e32 v73, v80, v80
	v_pk_add_f32 v[70:71], v[70:71], v[90:91]
	v_pk_add_f32 v[68:69], v[68:69], v[88:89]
	v_add_f32_e32 v82, v73, v72
	v_cvt_pk_bf16_f32 v72, v76, v77
	v_cvt_pk_bf16_f32 v73, v78, v79
	v_pk_add_f32 v[78:79], v[64:65], v[92:93]
	v_mul_f32_e32 v64, v69, v69
	v_mul_f32_e32 v65, v71, v71
	v_fmac_f32_e32 v64, v68, v68
	v_fmac_f32_e32 v65, v70, v70
	v_lshlrev_b32_e32 v94, 16, v131
	v_and_b32_e32 v95, 0xffff0000, v131
	v_add_f32_e32 v64, v64, v65
	v_mul_f32_e32 v65, v79, v79
	v_pk_add_f32 v[76:77], v[66:67], v[94:95]
	v_fmac_f32_e32 v65, v78, v78
	v_add_f32_e32 v64, v65, v64
	v_mul_f32_e32 v65, v77, v77
	v_fmac_f32_e32 v65, v76, v76
	v_add_f32_e32 v64, v65, v64
	v_add_f32_e32 v67, v82, v64
	ds_bpermute_b32 v82, v195, v67
	v_lshl_add_u64 v[64:65], s[2:3], 0, v[178:179]
	v_cvt_pk_bf16_f32 v74, v74, v75
	v_cvt_pk_bf16_f32 v75, v80, v81
	v_lshl_add_u64 v[80:81], v[170:171], 1, v[64:65]
	s_waitcnt lgkmcnt(0)
	v_add_f32_e32 v64, v67, v82
	ds_bpermute_b32 v65, v112, v64
	global_store_dwordx4 v[80:81], v[72:75], off nt
	v_cvt_pk_bf16_f32 v66, v68, v69
	v_cvt_pk_bf16_f32 v67, v70, v71
	v_cvt_pk_bf16_f32 v68, v78, v79
	v_cvt_pk_bf16_f32 v69, v76, v77
	global_store_dwordx4 v[80:81], v[66:69], off offset:256 nt
	s_and_saveexec_b64 s[38:39], s[0:1]
	s_cbranch_execz .LBB0_671
	v_lshlrev_b64 v[66:67], 6, v[176:177]
	v_lshl_add_u64 v[66:67], s[20:21], 0, v[66:67]
	v_lshl_add_u64 v[66:67], s[36:37], 2, v[66:67]
	s_lshl_b32 s8, s48, 2
	v_lshl_add_u64 v[66:67], v[66:67], 0, s[8:9]
	s_waitcnt lgkmcnt(0)
	v_add_f32_e32 v64, v64, v65
	global_store_dword v[66:67], v64, off
.LBB0_671:
	s_or_b64 exec, exec, s[38:39]
	v_add_u32_e32 v100, 0x80, v174
	v_ashrrev_i32_e32 v101, 31, v100
	v_lshlrev_b64 v[110:111], 11, v[100:101]
	s_waitcnt lgkmcnt(0)
	v_lshl_add_u64 v[64:65], v[172:173], 0, v[110:111]
	global_load_dwordx4 v[102:105], v[64:65], off
	global_load_dwordx4 v[106:109], v[64:65], off offset:256
	v_add_u32_e32 v96, 0x90, v174
	v_add_u32_e32 v92, 0xa0, v174
	v_add_u32_e32 v88, 0xb0, v174
	v_ashrrev_i32_e32 v97, 31, v96
	v_ashrrev_i32_e32 v93, 31, v92
	v_ashrrev_i32_e32 v89, 31, v88
	v_lshlrev_b64 v[98:99], 11, v[96:97]
	v_lshlrev_b64 v[94:95], 11, v[92:93]
	v_lshlrev_b64 v[90:91], 11, v[88:89]
	v_lshl_add_u64 v[64:65], v[172:173], 0, v[98:99]
	v_lshl_add_u64 v[66:67], v[172:173], 0, v[94:95]
	v_lshl_add_u64 v[114:115], v[172:173], 0, v[90:91]
	global_load_dwordx4 v[84:87], v[64:65], off
	global_load_dwordx4 v[80:83], v[64:65], off offset:256
	global_load_dwordx4 v[76:79], v[66:67], off
	global_load_dwordx4 v[72:75], v[66:67], off offset:256
	global_load_dwordx4 v[68:71], v[114:115], off
	s_nop 0
	global_load_dwordx4 v[64:67], v[114:115], off offset:256
	s_waitcnt vmcnt(7)
	v_lshlrev_b32_e32 v114, 16, v102
	v_and_b32_e32 v115, 0xffff0000, v102
	v_lshlrev_b32_e32 v102, 16, v103
	v_and_b32_e32 v103, 0xffff0000, v103
	v_lshlrev_b32_e32 v116, 16, v104
	v_and_b32_e32 v117, 0xffff0000, v104
	v_lshlrev_b32_e32 v104, 16, v105
	v_and_b32_e32 v105, 0xffff0000, v105
	s_waitcnt vmcnt(6)
	v_lshlrev_b32_e32 v118, 16, v106
	v_and_b32_e32 v119, 0xffff0000, v106
	v_lshlrev_b32_e32 v106, 16, v107
	v_and_b32_e32 v107, 0xffff0000, v107
	v_lshlrev_b32_e32 v120, 16, v108
	v_and_b32_e32 v121, 0xffff0000, v108
	v_lshlrev_b32_e32 v108, 16, v109
	v_and_b32_e32 v109, 0xffff0000, v109
	v_pk_add_f32 v[62:63], v[62:63], v[102:103]
	v_pk_add_f32 v[60:61], v[60:61], v[114:115]
	v_pk_add_f32 v[58:59], v[58:59], v[104:105]
	v_pk_add_f32 v[56:57], v[56:57], v[116:117]
	v_pk_add_f32 v[54:55], v[54:55], v[106:107]
	v_pk_add_f32 v[52:53], v[52:53], v[118:119]
	v_pk_add_f32 v[102:103], v[50:51], v[108:109]
	v_pk_add_f32 v[104:105], v[48:49], v[120:121]
	v_mul_f32_e32 v106, v61, v61
	v_mul_f32_e32 v107, v63, v63
	v_mul_f32_e32 v108, v57, v57
	v_mul_f32_e32 v109, v59, v59
	v_cvt_pk_bf16_f32 v48, v60, v61
	v_cvt_pk_bf16_f32 v49, v62, v63
	v_cvt_pk_bf16_f32 v50, v56, v57
	v_cvt_pk_bf16_f32 v51, v58, v59
	v_mul_f32_e32 v57, v53, v53
	v_mul_f32_e32 v59, v55, v55
	v_mul_f32_e32 v61, v105, v105
	v_fmac_f32_e32 v106, v60, v60
	v_fmac_f32_e32 v107, v62, v62
	v_fmac_f32_e32 v57, v52, v52
	v_fmac_f32_e32 v59, v54, v54
	v_mul_f32_e32 v63, v103, v103
	v_fmac_f32_e32 v108, v56, v56
	v_fmac_f32_e32 v61, v104, v104
	v_add_f32_e32 v56, v106, v107
	v_add_f32_e32 v57, v57, v59
	v_fmac_f32_e32 v109, v58, v58
	v_fmac_f32_e32 v63, v102, v102
	v_add_f32_e32 v56, v108, v56
	v_add_f32_e32 v57, v61, v57
	v_add_f32_e32 v56, v109, v56
	v_add_f32_e32 v57, v63, v57
	v_add_f32_e32 v58, v56, v57
	ds_bpermute_b32 v59, v195, v58
	v_lshl_add_u64 v[56:57], s[2:3], 0, v[110:111]
	v_lshl_add_u64 v[56:57], v[170:171], 1, v[56:57]
	global_store_dwordx4 v[56:57], v[48:51], off nt
	s_waitcnt lgkmcnt(0)
	s_nop 0
	v_add_f32_e32 v48, v58, v59
	ds_bpermute_b32 v49, v112, v48
	v_cvt_pk_bf16_f32 v50, v52, v53
	v_cvt_pk_bf16_f32 v51, v54, v55
	v_cvt_pk_bf16_f32 v52, v104, v105
	v_cvt_pk_bf16_f32 v53, v102, v103
	global_store_dwordx4 v[56:57], v[50:53], off offset:256 nt
	s_and_saveexec_b64 s[38:39], s[0:1]
	s_cbranch_execz .LBB0_673
	v_lshlrev_b64 v[50:51], 6, v[100:101]
	v_lshl_add_u64 v[50:51], s[20:21], 0, v[50:51]
	v_lshl_add_u64 v[50:51], s[36:37], 2, v[50:51]
	s_lshl_b32 s8, s48, 2
	v_lshl_add_u64 v[50:51], v[50:51], 0, s[8:9]
	s_waitcnt lgkmcnt(0)
	v_add_f32_e32 v48, v48, v49
	global_store_dword v[50:51], v48, off
; __device__ __forceinline__ unsigned pk2(float a, float b) { return pg8::cvt_pk_bf16(a, b); }
; __device__ __forceinline__ void unpack8(const u32x4 w, float (&f)[8]) { f[0] = bf_lo(w.x); f[1] = bf_hi(w.x); f[2] = bf_lo(w.y); f[3] = bf_hi(w.y); f[4] = bf_lo(w.z); f[5] = bf_hi(w.z); f[6] = bf_lo(w.w); f[7] = bf_hi(w.w); }
;     __device__ __forceinline__ void operator()(f32x4 (&acc)[2][2][4][2], const pg8::Unit& u, int wr, int wc, int fr, int fq) const {
;     ...
;             for (int m = 0; m < 4; ++m) { const int row = row0 + ai * 128 + m * 16; float s = 0.f;
; #pragma unroll
;                 for (int bj = 0; bj < 2; ++bj) { float f[8]; unpack8(rx[m][bj], f);
;                     const f32x4 v0 = acc[ai][bj][m][0] + (f32x4){f[0], f[1], f[2], f[3]}, v1 = acc[ai][bj][m][1] + (f32x4){f[4], f[5], f[6], f[7]};
;                     s += (v0[0] * v0[0] + v0[1] * v0[1]) + (v0[2] * v0[2] + v0[3] * v0[3]) + (v1[0] * v1[0] + v1[1] * v1[1]) + (v1[2] * v1[2] + v1[3] * v1[3]);
;                     u32x4 w; w.x = pk2(v0[0], v0[1]); w.y = pk2(v0[2], v0[3]); w.z = pk2(v1[0], v1[1]); w.w = pk2(v1[2], v1[3]);
;                     *(u32x4*)(YB + (size_t)row * 1024 + col0 + bj * 128) = w; }
;                 s += __shfl_xor(s, 16); s += __shfl_xor(s, 32); if (fq == 0) SS[(size_t)row * 16 + u.pn * 4 + wc] = s; }
.LBB0_673:
	s_or_b64 exec, exec, s[38:39]
	s_waitcnt vmcnt(7)
	v_lshlrev_b32_e32 v48, 16, v84
	s_waitcnt lgkmcnt(0)
	v_and_b32_e32 v49, 0xffff0000, v84
	v_lshlrev_b32_e32 v50, 16, v85
	v_and_b32_e32 v51, 0xffff0000, v85
	v_lshlrev_b32_e32 v52, 16, v86
	v_and_b32_e32 v53, 0xffff0000, v86
	v_lshlrev_b32_e32 v54, 16, v87
	v_and_b32_e32 v55, 0xffff0000, v87
	v_pk_add_f32 v[46:47], v[46:47], v[50:51]
	v_pk_add_f32 v[44:45], v[44:45], v[48:49]
	v_pk_add_f32 v[48:49], v[42:43], v[54:55]
	v_pk_add_f32 v[42:43], v[40:41], v[52:53]
	v_mul_f32_e32 v40, v45, v45
	v_mul_f32_e32 v41, v47, v47
	v_fmac_f32_e32 v40, v44, v44
	v_fmac_f32_e32 v41, v46, v46
	v_add_f32_e32 v40, v40, v41
	v_mul_f32_e32 v41, v43, v43
	v_fmac_f32_e32 v41, v42, v42
	s_waitcnt vmcnt(6)
	v_lshlrev_b32_e32 v56, 16, v80
	v_and_b32_e32 v57, 0xffff0000, v80
	v_lshlrev_b32_e32 v58, 16, v81
	v_and_b32_e32 v59, 0xffff0000, v81
	v_add_f32_e32 v40, v41, v40
	v_mul_f32_e32 v41, v49, v49
	v_lshlrev_b32_e32 v60, 16, v82
	v_and_b32_e32 v61, 0xffff0000, v82
	v_fmac_f32_e32 v41, v48, v48
	v_pk_add_f32 v[38:39], v[38:39], v[58:59]
	v_pk_add_f32 v[36:37], v[36:37], v[56:57]
	v_add_f32_e32 v50, v41, v40
	v_cvt_pk_bf16_f32 v40, v44, v45
	v_cvt_pk_bf16_f32 v41, v46, v47
	v_pk_add_f32 v[46:47], v[32:33], v[60:61]
	v_mul_f32_e32 v32, v37, v37
	v_mul_f32_e32 v33, v39, v39
	v_fmac_f32_e32 v32, v36, v36
	v_fmac_f32_e32 v33, v38, v38
	v_lshlrev_b32_e32 v62, 16, v83
	v_and_b32_e32 v63, 0xffff0000, v83
	v_add_f32_e32 v32, v32, v33
	v_mul_f32_e32 v33, v47, v47
	v_pk_add_f32 v[44:45], v[34:35], v[62:63]
	v_fmac_f32_e32 v33, v46, v46
	v_add_f32_e32 v32, v33, v32
	v_mul_f32_e32 v33, v45, v45
	v_fmac_f32_e32 v33, v44, v44
	v_add_f32_e32 v32, v33, v32
	v_add_f32_e32 v35, v50, v32
	ds_bpermute_b32 v50, v195, v35
	v_lshl_add_u64 v[32:33], s[2:3], 0, v[98:99]
	v_cvt_pk_bf16_f32 v42, v42, v43
	v_cvt_pk_bf16_f32 v43, v48, v49
	v_lshl_add_u64 v[48:49], v[170:171], 1, v[32:33]
	s_waitcnt lgkmcnt(0)
	v_add_f32_e32 v32, v35, v50
	ds_bpermute_b32 v33, v112, v32
	global_store_dwordx4 v[48:49], v[40:43], off nt
	v_cvt_pk_bf16_f32 v34, v36, v37
	v_cvt_pk_bf16_f32 v35, v38, v39
	v_cvt_pk_bf16_f32 v36, v46, v47
	v_cvt_pk_bf16_f32 v37, v44, v45
	global_store_dwordx4 v[48:49], v[34:37], off offset:256 nt
	s_and_saveexec_b64 s[38:39], s[0:1]
	s_cbranch_execz .LBB0_675
	v_lshlrev_b64 v[34:35], 6, v[96:97]
	v_lshl_add_u64 v[34:35], s[20:21], 0, v[34:35]
	v_lshl_add_u64 v[34:35], s[36:37], 2, v[34:35]
	s_lshl_b32 s8, s48, 2
	v_lshl_add_u64 v[34:35], v[34:35], 0, s[8:9]
	s_waitcnt lgkmcnt(0)
	v_add_f32_e32 v32, v32, v33
	global_store_dword v[34:35], v32, off
; __device__ __forceinline__ unsigned pk2(float a, float b) { return pg8::cvt_pk_bf16(a, b); }
; __device__ __forceinline__ void unpack8(const u32x4 w, float (&f)[8]) { f[0] = bf_lo(w.x); f[1] = bf_hi(w.x); f[2] = bf_lo(w.y); f[3] = bf_hi(w.y); f[4] = bf_lo(w.z); f[5] = bf_hi(w.z); f[6] = bf_lo(w.w); f[7] = bf_hi(w.w); }
;     __device__ __forceinline__ void operator()(f32x4 (&acc)[2][2][4][2], const pg8::Unit& u, int wr, int wc, int fr, int fq) const {
;     ...
;             for (int m = 0; m < 4; ++m) { const int row = row0 + ai * 128 + m * 16; float s = 0.f;
; #pragma unroll
;                 for (int bj = 0; bj < 2; ++bj) { float f[8]; unpack8(rx[m][bj], f);
;                     const f32x4 v0 = acc[ai][bj][m][0] + (f32x4){f[0], f[1], f[2], f[3]}, v1 = acc[ai][bj][m][1] + (f32x4){f[4], f[5], f[6], f[7]};
;                     s += (v0[0] * v0[0] + v0[1] * v0[1]) + (v0[2] * v0[2] + v0[3] * v0[3]) + (v1[0] * v1[0] + v1[1] * v1[1]) + (v1[2] * v1[2] + v1[3] * v1[3]);
;                     u32x4 w; w.x = pk2(v0[0], v0[1]); w.y = pk2(v0[2], v0[3]); w.z = pk2(v1[0], v1[1]); w.w = pk2(v1[2], v1[3]);
;                     *(u32x4*)(YB + (size_t)row * 1024 + col0 + bj * 128) = w; }
;                 s += __shfl_xor(s, 16); s += __shfl_xor(s, 32); if (fq == 0) SS[(size_t)row * 16 + u.pn * 4 + wc] = s; }
.LBB0_675:
	s_or_b64 exec, exec, s[38:39]
	s_waitcnt vmcnt(7)
	v_lshlrev_b32_e32 v32, 16, v76
	s_waitcnt lgkmcnt(0)
	v_and_b32_e32 v33, 0xffff0000, v76
	v_lshlrev_b32_e32 v34, 16, v77
	v_and_b32_e32 v35, 0xffff0000, v77
	v_lshlrev_b32_e32 v36, 16, v78
	v_and_b32_e32 v37, 0xffff0000, v78
	v_lshlrev_b32_e32 v38, 16, v79
	v_and_b32_e32 v39, 0xffff0000, v79
	v_pk_add_f32 v[30:31], v[30:31], v[34:35]
	v_pk_add_f32 v[28:29], v[28:29], v[32:33]
	v_pk_add_f32 v[32:33], v[26:27], v[38:39]
	v_pk_add_f32 v[26:27], v[24:25], v[36:37]
	v_mul_f32_e32 v24, v29, v29
	v_mul_f32_e32 v25, v31, v31
	v_fmac_f32_e32 v24, v28, v28
	v_fmac_f32_e32 v25, v30, v30
	v_add_f32_e32 v24, v24, v25
	v_mul_f32_e32 v25, v27, v27
	v_fmac_f32_e32 v25, v26, v26
	s_waitcnt vmcnt(6)
	v_lshlrev_b32_e32 v40, 16, v72
	v_and_b32_e32 v41, 0xffff0000, v72
	v_lshlrev_b32_e32 v42, 16, v73
	v_and_b32_e32 v43, 0xffff0000, v73
	v_add_f32_e32 v24, v25, v24
	v_mul_f32_e32 v25, v33, v33
	v_lshlrev_b32_e32 v44, 16, v74
	v_and_b32_e32 v45, 0xffff0000, v74
	v_fmac_f32_e32 v25, v32, v32
	v_pk_add_f32 v[22:23], v[22:23], v[42:43]
	v_pk_add_f32 v[20:21], v[20:21], v[40:41]
	v_add_f32_e32 v34, v25, v24
	v_cvt_pk_bf16_f32 v24, v28, v29
	v_cvt_pk_bf16_f32 v25, v30, v31
	v_pk_add_f32 v[30:31], v[16:17], v[44:45]
	v_mul_f32_e32 v16, v21, v21
	v_mul_f32_e32 v17, v23, v23
	v_fmac_f32_e32 v16, v20, v20
	v_fmac_f32_e32 v17, v22, v22
	v_lshlrev_b32_e32 v46, 16, v75
	v_and_b32_e32 v47, 0xffff0000, v75
	v_add_f32_e32 v16, v16, v17
	v_mul_f32_e32 v17, v31, v31
	v_pk_add_f32 v[28:29], v[18:19], v[46:47]
	v_fmac_f32_e32 v17, v30, v30
	v_add_f32_e32 v16, v17, v16
	v_mul_f32_e32 v17, v29, v29
	v_fmac_f32_e32 v17, v28, v28
	v_add_f32_e32 v16, v17, v16
	v_add_f32_e32 v19, v34, v16
	ds_bpermute_b32 v34, v195, v19
	v_lshl_add_u64 v[16:17], s[2:3], 0, v[94:95]
	v_cvt_pk_bf16_f32 v26, v26, v27
	v_cvt_pk_bf16_f32 v27, v32, v33
	v_lshl_add_u64 v[32:33], v[170:171], 1, v[16:17]
	s_waitcnt lgkmcnt(0)
	v_add_f32_e32 v16, v19, v34
	ds_bpermute_b32 v17, v112, v16
	global_store_dwordx4 v[32:33], v[24:27], off nt
	v_cvt_pk_bf16_f32 v18, v20, v21
	v_cvt_pk_bf16_f32 v19, v22, v23
	v_cvt_pk_bf16_f32 v20, v30, v31
	v_cvt_pk_bf16_f32 v21, v28, v29
	global_store_dwordx4 v[32:33], v[18:21], off offset:256 nt
	s_and_saveexec_b64 s[38:39], s[0:1]
	s_cbranch_execz .LBB0_677
	v_lshlrev_b64 v[18:19], 6, v[92:93]
	v_lshl_add_u64 v[18:19], s[20:21], 0, v[18:19]
	v_lshl_add_u64 v[18:19], s[36:37], 2, v[18:19]
	s_lshl_b32 s8, s48, 2
	v_lshl_add_u64 v[18:19], v[18:19], 0, s[8:9]
	s_waitcnt lgkmcnt(0)
	v_add_f32_e32 v16, v16, v17
	global_store_dword v[18:19], v16, off
.LBB0_677:
	s_or_b64 exec, exec, s[38:39]
	s_waitcnt vmcnt(7)
	v_lshlrev_b32_e32 v16, 16, v68
	s_waitcnt lgkmcnt(0)
	v_and_b32_e32 v17, 0xffff0000, v68
	v_lshlrev_b32_e32 v18, 16, v69
	v_and_b32_e32 v19, 0xffff0000, v69
	v_lshlrev_b32_e32 v20, 16, v70
	v_and_b32_e32 v21, 0xffff0000, v70
	v_lshlrev_b32_e32 v22, 16, v71
	v_and_b32_e32 v23, 0xffff0000, v71
	v_pk_add_f32 v[14:15], v[14:15], v[18:19]
	v_pk_add_f32 v[12:13], v[12:13], v[16:17]
	v_pk_add_f32 v[16:17], v[10:11], v[22:23]
	v_pk_add_f32 v[10:11], v[8:9], v[20:21]
	v_mul_f32_e32 v8, v13, v13
	v_mul_f32_e32 v9, v15, v15
	v_fmac_f32_e32 v8, v12, v12
	v_fmac_f32_e32 v9, v14, v14
	v_add_f32_e32 v8, v8, v9
	v_mul_f32_e32 v9, v11, v11
	v_fmac_f32_e32 v9, v10, v10
	s_waitcnt vmcnt(6)
	v_lshlrev_b32_e32 v24, 16, v64
	v_and_b32_e32 v25, 0xffff0000, v64
	v_lshlrev_b32_e32 v26, 16, v65
	v_and_b32_e32 v27, 0xffff0000, v65
	v_add_f32_e32 v8, v9, v8
	v_mul_f32_e32 v9, v17, v17
	v_lshlrev_b32_e32 v28, 16, v66
	v_and_b32_e32 v29, 0xffff0000, v66
	v_fmac_f32_e32 v9, v16, v16
	v_pk_add_f32 v[6:7], v[6:7], v[26:27]
	v_pk_add_f32 v[4:5], v[4:5], v[24:25]
	v_add_f32_e32 v18, v9, v8
	v_cvt_pk_bf16_f32 v8, v12, v13
	v_cvt_pk_bf16_f32 v9, v14, v15
	v_pk_add_f32 v[14:15], v[0:1], v[28:29]
	v_mul_f32_e32 v0, v5, v5
	v_mul_f32_e32 v1, v7, v7
	v_fmac_f32_e32 v0, v4, v4
	v_fmac_f32_e32 v1, v6, v6
	v_lshlrev_b32_e32 v30, 16, v67
	v_and_b32_e32 v31, 0xffff0000, v67
	v_add_f32_e32 v0, v0, v1
	v_mul_f32_e32 v1, v15, v15
	v_pk_add_f32 v[12:13], v[2:3], v[30:31]
	v_fmac_f32_e32 v1, v14, v14
	v_add_f32_e32 v0, v1, v0
	v_mul_f32_e32 v1, v13, v13
	v_fmac_f32_e32 v1, v12, v12
	v_add_f32_e32 v0, v1, v0
	v_add_f32_e32 v3, v18, v0
	ds_bpermute_b32 v18, v195, v3
	v_lshl_add_u64 v[0:1], s[2:3], 0, v[90:91]
	v_cvt_pk_bf16_f32 v10, v10, v11
	v_cvt_pk_bf16_f32 v11, v16, v17
	v_lshl_add_u64 v[16:17], v[170:171], 1, v[0:1]
	s_waitcnt lgkmcnt(0)
	v_add_f32_e32 v0, v3, v18
	ds_bpermute_b32 v1, v112, v0
	global_store_dwordx4 v[16:17], v[8:11], off nt
	v_cvt_pk_bf16_f32 v2, v4, v5
	v_cvt_pk_bf16_f32 v3, v6, v7
	v_cvt_pk_bf16_f32 v4, v14, v15
	v_cvt_pk_bf16_f32 v5, v12, v13
	global_store_dwordx4 v[16:17], v[2:5], off offset:256 nt
	s_and_saveexec_b64 s[38:39], s[0:1]
	s_cbranch_execz .LBB0_679
	v_lshlrev_b64 v[2:3], 6, v[88:89]
	v_lshl_add_u64 v[2:3], s[20:21], 0, v[2:3]
	v_lshl_add_u64 v[2:3], s[36:37], 2, v[2:3]
	s_lshl_b32 s8, s48, 2
	v_lshl_add_u64 v[2:3], v[2:3], 0, s[8:9]
	s_waitcnt lgkmcnt(0)
	v_add_f32_e32 v0, v0, v1
	global_store_dword v[2:3], v0, off

; #define PG8_LAS __attribute__((address_space(3)))
; __device__ __forceinline__ float row_up1(float v) { return dpp_mov<0x111>(v); }
;     __device__ __forceinline__ void operator()(f32x4 (&acc)[2][2][4][2], const pg8::Unit& u, int wr, int wc, int fr, int fq) const {
;         const int colj = u.pn * 128 + wc * 32 + 8 * fq;
;         PG8_LAS unsigned char* wl = WL + (wr * 4 + wc) * 1024;
;         {
;             const int l = fq * 16 + fr, p = l >> 4, bj = (l >> 3) & 1, c4 = (l & 7) * 4;
;             const float* srcp = (p < 3 ? FW + p * NUP : FB) + bj * DFF + u.pn * 128 + wc * 32 + c4;
;             *(PG8_LAS f32x4*)(wl + l * 16) = *(const f32x4*)srcp;
;         }
; #pragma unroll
;         for (int ai = 0; ai < 2; ++ai) {
;             const int tb = u.pm * 256 + ai * 128 + wr * 64 + 4 * fr;
;             float rstd[4];
; #pragma unroll
;             for (int m = 0; m < 4; ++m) { const f32x4 sv = *(const f32x4*)(SS + (size_t)(tb + m) * 16 + 4 * fq); float s = (sv[0] + sv[1]) + (sv[2] + sv[3]); s += __shfl_xor(s, 16); s += __shfl_xor(s, 32);
;                 rstd[m] = rsqrtf(s * (1.0f / 1024.0f) + EPS); }
;             u32x2 pk[2][4];
; #pragma unroll
;             for (int n = 0; n < 2; ++n) {
;                 f32x4 g[4];
;                 {   const PG8_LAS unsigned char* wq = wl + (8 * fq + 4 * n) * 4;
;                     const f32x4 w0 = *(const PG8_LAS f32x4*)(wq), w1 = *(const PG8_LAS f32x4*)(wq + 256), w2 = *(const PG8_LAS f32x4*)(wq + 512), bb = *(const PG8_LAS f32x4*)(wq + 768);
;                     const f32x4 x0 = acc[ai][0][0][n] * rstd[0], x1 = acc[ai][0][1][n] * rstd[1], x2 = acc[ai][0][2][n] * rstd[2], x3 = acc[ai][0][3][n] * rstd[3];
;                     acc[ai][0][0][n] = x0; acc[ai][0][1][n] = x1; acc[ai][0][2][n] = x2; acc[ai][0][3][n] = x3;
;                     f32x4 p1, p2;
; #pragma unroll
;                     for (int c = 0; c < 4; ++c) { p1[c] = row_up1(x3[c]); p2[c] = row_up1(x2[c]); }
;                     g[0] = bb + w2 * x0 + w1 * p1 + w0 * p2; g[1] = bb + w2 * x1 + w1 * x0 + w0 * p1;
;                     g[2] = bb + w2 * x2 + w1 * x1 + w0 * x0; g[3] = bb + w2 * x3 + w1 * x2 + w0 * x1;
; #pragma unroll
;                     for (int m = 0; m < 4; ++m)
; #pragma unroll
;                         for (int c = 0; c < 4; ++c) g[m][c] = siluf_(g[m][c]);
.LBB0_748:
	v_lshl_add_u32 v148, s34, 8, v187
	v_ashrrev_i32_e32 v149, 31, v148
	v_lshlrev_b64 v[150:151], 6, v[148:149]
	v_lshl_add_u64 v[154:155], v[138:139], 0, v[150:151]
	v_or_b32_e32 v150, 1, v148
	v_ashrrev_i32_e32 v151, 31, v150
	v_lshlrev_b64 v[156:157], 6, v[150:151]
	v_lshl_add_u64 v[156:157], v[138:139], 0, v[156:157]
	global_load_dwordx4 v[160:163], v[154:155], off
	global_load_dwordx4 v[164:167], v[156:157], off
	v_or_b32_e32 v154, 2, v148
	v_ashrrev_i32_e32 v155, 31, v154
	v_lshlrev_b64 v[156:157], 6, v[154:155]
	v_lshl_add_u64 v[156:157], v[138:139], 0, v[156:157]
	global_load_dwordx4 v[172:175], v[156:157], off
	v_or_b32_e32 v156, 3, v148
	v_ashrrev_i32_e32 v157, 31, v156
	v_lshlrev_b64 v[158:159], 6, v[156:157]
	v_lshl_add_u64 v[158:159], v[138:139], 0, v[158:159]
	global_load_dwordx4 v[176:179], v[158:159], off
	s_lshl_b32 s8, s66, 7
	s_ashr_i32 s9, s8, 31
	v_lshl_add_u64 v[158:159], s[8:9], 2, v[136:137]
	global_load_dwordx4 v[180:183], v[158:159], off
	v_and_b32_e32 v151, 64, v194
	v_xor_b32_e32 v149, 16, v194
	v_add_u32_e32 v151, 64, v151
	v_cmp_lt_i32_e32 vcc, v149, v151
	v_xor_b32_e32 v155, 32, v194
	v_mov_b64_e32 v[184:185], s[38:39]
	v_cndmask_b32_e32 v149, v194, v149, vcc
	v_lshlrev_b32_e32 v149, 2, v149
	v_cmp_lt_i32_e32 vcc, v155, v151
	v_or_b32_e32 v158, s8, v186
	v_ashrrev_i32_e32 v159, 31, v158
	v_cndmask_b32_e32 v151, v194, v155, vcc
	v_lshlrev_b32_e32 v151, 2, v151
	s_waitcnt vmcnt(0)
	v_mov_b32_e32 v196, v161
	v_mov_b32_e32 v197, v162
	v_mov_b32_e32 v161, v163
	v_mov_b32_e32 v162, v165
	v_mov_b32_e32 v163, v166
	v_mov_b32_e32 v165, v167
	v_mov_b32_e32 v166, v173
	v_mov_b32_e32 v167, v174
	v_mov_b32_e32 v173, v175
	v_pk_add_f32 v[160:161], v[196:197], v[160:161]
	v_pk_add_f32 v[162:163], v[162:163], v[164:165]
	v_mov_b32_e32 v174, v177
	v_mov_b32_e32 v175, v178
	v_mov_b32_e32 v177, v179
	v_pk_add_f32 v[166:167], v[166:167], v[172:173]
	v_pk_add_f32 v[172:173], v[174:175], v[176:177]
	v_mov_b32_e32 v165, v160
	v_mov_b32_e32 v164, v162
	v_mov_b32_e32 v160, v163
	v_mov_b32_e32 v162, v172
	v_mov_b32_e32 v163, v166
	v_mov_b32_e32 v166, v173
	v_pk_add_f32 v[160:161], v[164:165], v[160:161]
	v_pk_add_f32 v[162:163], v[162:163], v[166:167]
	ds_bpermute_b32 v165, v149, v161
	ds_bpermute_b32 v164, v149, v160
	ds_bpermute_b32 v167, v149, v163
	ds_bpermute_b32 v166, v149, v162
	ds_write_b128 v193, v[180:183]
	s_waitcnt lgkmcnt(3)
	v_pk_add_f32 v[172:173], v[160:161], v[164:165]
	ds_bpermute_b32 v197, v151, v173
	s_waitcnt lgkmcnt(2)
	v_pk_add_f32 v[174:175], v[162:163], v[166:167]
	ds_bpermute_b32 v196, v151, v172
	ds_bpermute_b32 v199, v151, v175
	ds_bpermute_b32 v198, v151, v174
	ds_read_b128 v[160:163], v195
	ds_read_b128 v[164:167], v195 offset:256
	ds_read_b128 v[176:179], v195 offset:512
	ds_read_b128 v[180:183], v195 offset:768
	s_waitcnt lgkmcnt(6)
	v_pk_add_f32 v[172:173], v[172:173], v[196:197]
	s_nop 0
	v_pk_fma_f32 v[172:173], v[172:173], s[24:25], v[184:185] op_sel_hi:[1,0,0]
	s_waitcnt lgkmcnt(4)
	v_pk_add_f32 v[174:175], v[174:175], v[198:199]
	v_mul_f32_e32 v155, 0x4b800000, v173
	v_pk_fma_f32 v[174:175], v[174:175], s[24:25], v[184:185] op_sel_hi:[1,0,0]
	v_cmp_gt_f32_e32 vcc, s63, v173
	v_mul_f32_e32 v168, 0x4b800000, v175
	v_mul_f32_e32 v170, 0x4b800000, v174
	v_cmp_gt_f32_e64 s[10:11], s63, v175
	v_cmp_gt_f32_e64 s[12:13], s63, v174
	v_cndmask_b32_e32 v155, v173, v155, vcc
	v_cndmask_b32_e64 v168, v175, v168, s[10:11]
	v_cndmask_b32_e64 v170, v174, v170, s[12:13]
	v_rsq_f32_e32 v155, v155
	v_rsq_f32_e32 v168, v168
	v_rsq_f32_e32 v173, v170
	v_mul_f32_e32 v157, 0x4b800000, v172
	v_cmp_gt_f32_e64 s[8:9], s63, v172
	v_mul_f32_e32 v170, 0x45800000, v155
	v_mul_f32_e32 v175, 0x45800000, v168
	v_cndmask_b32_e64 v157, v172, v157, s[8:9]
	v_mul_f32_e32 v184, 0x45800000, v173
	v_rsq_f32_e32 v157, v157
	v_cndmask_b32_e32 v174, v155, v170, vcc
	v_cndmask_b32_e64 v170, v168, v175, s[10:11]
	v_cndmask_b32_e64 v168, v173, v184, s[12:13]
	v_pk_mul_f32 v[124:125], v[124:125], v[174:175] op_sel_hi:[1,0]
	v_pk_mul_f32 v[112:113], v[112:113], v[168:169] op_sel_hi:[1,0]
	v_pk_mul_f32 v[116:117], v[116:117], v[170:171] op_sel_hi:[1,0]
	s_waitcnt lgkmcnt(0)
	v_pk_fma_f32 v[204:205], v[176:177], v[124:125], v[180:181]
	v_mov_b32_dpp v184, v112 row_shr:1 row_mask:0xf bank_mask:0xf bound_ctrl:1
	v_mov_b32_dpp v185, v113 row_shr:1 row_mask:0xf bank_mask:0xf bound_ctrl:1
	v_mov_b32_dpp v196, v116 row_shr:1 row_mask:0xf bank_mask:0xf bound_ctrl:1
	v_mov_b32_dpp v197, v117 row_shr:1 row_mask:0xf bank_mask:0xf bound_ctrl:1
	v_pk_fma_f32 v[204:205], v[164:165], v[184:185], v[204:205]
	v_mul_f32_e32 v172, 0x45800000, v157
	v_pk_fma_f32 v[196:197], v[160:161], v[196:197], v[204:205]
	v_cndmask_b32_e64 v172, v157, v172, s[8:9]
	v_mul_f32_e32 v155, 0xbfb8aa3b, v196
	v_pk_mul_f32 v[126:127], v[126:127], v[174:175] op_sel_hi:[1,0]
	v_pk_mul_f32 v[120:121], v[120:121], v[172:173] op_sel_hi:[1,0]
	v_pk_mul_f32 v[114:115], v[114:115], v[168:169] op_sel_hi:[1,0]
	v_exp_f32_e32 v155, v155
	v_mul_f32_e32 v157, 0xbfb8aa3b, v197
	v_pk_mul_f32 v[118:119], v[118:119], v[170:171] op_sel_hi:[1,0]
	v_mov_b32_dpp v198, v114 row_shr:1 row_mask:0xf bank_mask:0xf bound_ctrl:1
	v_mov_b32_dpp v199, v115 row_shr:1 row_mask:0xf bank_mask:0xf bound_ctrl:1
	v_pk_fma_f32 v[202:203], v[178:179], v[126:127], v[182:183]
	v_pk_fma_f32 v[204:205], v[176:177], v[120:121], v[180:181]
	v_exp_f32_e32 v157, v157
	v_pk_mul_f32 v[122:123], v[122:123], v[172:173] op_sel_hi:[1,0]
	v_mov_b32_dpp v200, v118 row_shr:1 row_mask:0xf bank_mask:0xf bound_ctrl:1
	v_mov_b32_dpp v201, v119 row_shr:1 row_mask:0xf bank_mask:0xf bound_ctrl:1
	v_pk_fma_f32 v[202:203], v[166:167], v[198:199], v[202:203]
; #define PG8_LAS __attribute__((address_space(3)))
;     __device__ __forceinline__ void operator()(f32x4 (&acc)[2][2][4][2], const pg8::Unit& u, int wr, int wc, int fr, int fq) const {
;     ...
;             for (int n = 0; n < 2; ++n) {
;                 f32x4 g[4];
;                 {   const PG8_LAS unsigned char* wq = wl + (8 * fq + 4 * n) * 4;
;                     const f32x4 w0 = *(const PG8_LAS f32x4*)(wq), w1 = *(const PG8_LAS f32x4*)(wq + 256), w2 = *(const PG8_LAS f32x4*)(wq + 512), bb = *(const PG8_LAS f32x4*)(wq + 768);
;                     const f32x4 x0 = acc[ai][0][0][n] * rstd[0], x1 = acc[ai][0][1][n] * rstd[1], x2 = acc[ai][0][2][n] * rstd[2], x3 = acc[ai][0][3][n] * rstd[3];
;                     acc[ai][0][0][n] = x0; acc[ai][0][1][n] = x1; acc[ai][0][2][n] = x2; acc[ai][0][3][n] = x3;
;                     f32x4 p1, p2;
; #pragma unroll
;                     for (int c = 0; c < 4; ++c) { p1[c] = row_up1(x3[c]); p2[c] = row_up1(x2[c]); }
;                     g[0] = bb + w2 * x0 + w1 * p1 + w0 * p2; g[1] = bb + w2 * x1 + w1 * x0 + w0 * p1;
;                     g[2] = bb + w2 * x2 + w1 * x1 + w0 * x0; g[3] = bb + w2 * x3 + w1 * x2 + w0 * x1;
; #pragma unroll
;                     for (int m = 0; m < 4; ++m)
; #pragma unroll
;                         for (int c = 0; c < 4; ++c) g[m][c] = siluf_(g[m][c]);
;                 }
;                 __builtin_amdgcn_sched_barrier(0);
;                 {   const PG8_LAS unsigned char* wq = wl + 128 + (8 * fq + 4 * n) * 4;
;                     const f32x4 w0 = *(const PG8_LAS f32x4*)(wq), w1 = *(const PG8_LAS f32x4*)(wq + 256), w2 = *(const PG8_LAS f32x4*)(wq + 512), bb = *(const PG8_LAS f32x4*)(wq + 768);
;                     const f32x4 x0 = acc[ai][1][0][n] * rstd[0], x1 = acc[ai][1][1][n] * rstd[1], x2 = acc[ai][1][2][n] * rstd[2], x3 = acc[ai][1][3][n] * rstd[3];
;                     acc[ai][1][0][n] = x0; acc[ai][1][1][n] = x1; acc[ai][1][2][n] = x2; acc[ai][1][3][n] = x3;
;                     f32x4 p1, p2;
; #pragma unroll
;                     for (int c = 0; c < 4; ++c) { p1[c] = row_up1(x3[c]); p2[c] = row_up1(x2[c]); }
;                     g[0] *= bb + w2 * x0 + w1 * p1 + w0 * p2; g[1] *= bb + w2 * x1 + w1 * x0 + w0 * p1;
;                     g[2] *= bb + w2 * x2 + w1 * x1 + w0 * x0; g[3] *= bb + w2 * x3 + w1 * x2 + w0 * x1;
;                 }
; #pragma unroll
	v_pk_fma_f32 v[204:205], v[164:165], v[124:125], v[204:205]
	v_pk_fma_f32 v[200:201], v[162:163], v[200:201], v[202:203]
	v_pk_fma_f32 v[202:203], v[178:179], v[122:123], v[182:183]
	v_pk_fma_f32 v[184:185], v[160:161], v[184:185], v[204:205]
	v_pk_fma_f32 v[204:205], v[176:177], v[116:117], v[180:181]
	v_pk_fma_f32 v[176:177], v[176:177], v[112:113], v[180:181]
	v_pk_fma_f32 v[202:203], v[166:167], v[126:127], v[202:203]
	v_pk_fma_f32 v[204:205], v[164:165], v[120:121], v[204:205]
	v_pk_fma_f32 v[164:165], v[164:165], v[116:117], v[176:177]
	v_add_f32_e32 v155, 1.0, v155
	v_pk_fma_f32 v[198:199], v[162:163], v[198:199], v[202:203]
	v_pk_fma_f32 v[202:203], v[178:179], v[118:119], v[182:183]
	v_pk_fma_f32 v[204:205], v[160:161], v[124:125], v[204:205]
	v_pk_fma_f32 v[178:179], v[178:179], v[114:115], v[182:183]
	v_pk_fma_f32 v[214:215], v[160:161], v[120:121], v[164:165]
	v_rcp_f32_e32 v160, v155
	v_add_f32_e32 v155, 1.0, v157
	v_mul_f32_e32 v157, 0xbfb8aa3b, v200
	v_pk_fma_f32 v[202:203], v[166:167], v[122:123], v[202:203]
	v_pk_fma_f32 v[166:167], v[166:167], v[118:119], v[178:179]
	v_exp_f32_e32 v157, v157
	v_mul_f32_e32 v161, 0xbfb8aa3b, v201
	v_pk_fma_f32 v[202:203], v[162:163], v[126:127], v[202:203]
	v_pk_fma_f32 v[212:213], v[162:163], v[122:123], v[166:167]
	v_exp_f32_e32 v163, v161
	v_rcp_f32_e32 v161, v155
	v_add_f32_e32 v155, 1.0, v157
	v_rcp_f32_e32 v162, v155
	v_add_f32_e32 v155, 1.0, v163
	v_rcp_f32_e32 v163, v155
	v_mul_f32_e32 v155, 0xbfb8aa3b, v184
	v_exp_f32_e32 v155, v155
	v_mul_f32_e32 v157, 0xbfb8aa3b, v185
	v_exp_f32_e32 v157, v157
	v_pk_mul_f32 v[216:217], v[196:197], v[160:161]
	v_add_f32_e32 v155, 1.0, v155
	v_rcp_f32_e32 v160, v155
	v_add_f32_e32 v155, 1.0, v157
	v_mul_f32_e32 v157, 0xbfb8aa3b, v198
	v_exp_f32_e32 v157, v157
	v_mul_f32_e32 v161, 0xbfb8aa3b, v199
	v_pk_mul_f32 v[218:219], v[200:201], v[162:163]
	v_exp_f32_e32 v163, v161
	v_rcp_f32_e32 v161, v155
	v_add_f32_e32 v155, 1.0, v157
	v_rcp_f32_e32 v162, v155
	v_add_f32_e32 v155, 1.0, v163
	v_rcp_f32_e32 v163, v155
	v_mul_f32_e32 v155, 0xbfb8aa3b, v204
	v_exp_f32_e32 v155, v155
	v_mul_f32_e32 v157, 0xbfb8aa3b, v205
	v_exp_f32_e32 v157, v157
	v_pk_mul_f32 v[184:185], v[184:185], v[160:161]
	v_add_f32_e32 v155, 1.0, v155
	v_rcp_f32_e32 v160, v155
	v_add_f32_e32 v155, 1.0, v157
	v_mul_f32_e32 v157, 0xbfb8aa3b, v202
	v_exp_f32_e32 v157, v157
	v_mul_f32_e32 v161, 0xbfb8aa3b, v203
	v_exp_f32_e32 v165, v161
	v_rcp_f32_e32 v161, v155
	v_add_f32_e32 v155, 1.0, v157
	v_mul_f32_e32 v157, 0xbfb8aa3b, v214
	v_rcp_f32_e32 v164, v155
	v_add_f32_e32 v155, 1.0, v165
	v_exp_f32_e32 v157, v157
	v_mul_f32_e32 v165, 0xbfb8aa3b, v215
	v_exp_f32_e32 v166, v165
	v_rcp_f32_e32 v165, v155
	v_add_f32_e32 v155, 1.0, v157
	v_mul_f32_e32 v157, 0xbfb8aa3b, v212
	v_rcp_f32_e32 v220, v155
	v_add_f32_e32 v155, 1.0, v166
	v_exp_f32_e32 v157, v157
	v_mul_f32_e32 v166, 0xbfb8aa3b, v213
	v_exp_f32_e32 v166, v166
	v_rcp_f32_e32 v221, v155
	v_add_f32_e32 v155, 1.0, v157
	v_rcp_f32_e32 v222, v155
	v_add_f32_e32 v155, 1.0, v166
	v_rcp_f32_e32 v223, v155
	v_pk_mul_f32 v[224:225], v[198:199], v[162:163]
	v_pk_mul_f32 v[226:227], v[204:205], v[160:161]
	v_pk_mul_f32 v[228:229], v[202:203], v[164:165]
	ds_read_b128 v[196:199], v195 offset:128
	ds_read_b128 v[200:203], v195 offset:384
	ds_read_b128 v[204:207], v195 offset:640
	ds_read_b128 v[208:211], v195 offset:896
	v_pk_mul_f32 v[176:177], v[108:109], v[174:175] op_sel_hi:[1,0]
	v_pk_mul_f32 v[164:165], v[96:97], v[168:169] op_sel_hi:[1,0]
	v_pk_mul_f32 v[180:181], v[100:101], v[170:171] op_sel_hi:[1,0]
	v_pk_mul_f32 v[160:161], v[104:105], v[172:173] op_sel_hi:[1,0]
	v_mov_b32_dpp v96, v164 row_shr:1 row_mask:0xf bank_mask:0xf bound_ctrl:1
	v_mov_b32_dpp v97, v165 row_shr:1 row_mask:0xf bank_mask:0xf bound_ctrl:1
	s_waitcnt lgkmcnt(0)
	v_pk_fma_f32 v[108:109], v[176:177], v[204:205], v[208:209]
	v_pk_mul_f32 v[166:167], v[98:99], v[168:169] op_sel_hi:[1,0]
	v_mov_b32_dpp v98, v180 row_shr:1 row_mask:0xf bank_mask:0xf bound_ctrl:1
	v_mov_b32_dpp v99, v181 row_shr:1 row_mask:0xf bank_mask:0xf bound_ctrl:1
	v_pk_fma_f32 v[108:109], v[200:201], v[96:97], v[108:109]
	v_pk_mul_f32 v[178:179], v[110:111], v[174:175] op_sel_hi:[1,0]
	v_pk_fma_f32 v[98:99], v[196:197], v[98:99], v[108:109]
	v_pk_fma_f32 v[108:109], v[160:161], v[204:205], v[208:209]
	v_pk_mul_f32 v[182:183], v[102:103], v[170:171] op_sel_hi:[1,0]
	v_mov_b32_dpp v100, v166 row_shr:1 row_mask:0xf bank_mask:0xf bound_ctrl:1
	v_mov_b32_dpp v101, v167 row_shr:1 row_mask:0xf bank_mask:0xf bound_ctrl:1
	v_pk_fma_f32 v[110:111], v[178:179], v[206:207], v[210:211]
	v_pk_fma_f32 v[108:109], v[176:177], v[200:201], v[108:109]
	v_pk_mul_f32 v[162:163], v[106:107], v[172:173] op_sel_hi:[1,0]
	v_mov_b32_dpp v102, v182 row_shr:1 row_mask:0xf bank_mask:0xf bound_ctrl:1
	v_mov_b32_dpp v103, v183 row_shr:1 row_mask:0xf bank_mask:0xf bound_ctrl:1
	v_pk_fma_f32 v[110:111], v[202:203], v[100:101], v[110:111]
	v_pk_fma_f32 v[96:97], v[196:197], v[96:97], v[108:109]
	v_pk_fma_f32 v[108:109], v[180:181], v[204:205], v[208:209]
	v_pk_fma_f32 v[102:103], v[198:199], v[102:103], v[110:111]
	v_pk_fma_f32 v[110:111], v[162:163], v[206:207], v[210:211]
	v_pk_fma_f32 v[108:109], v[160:161], v[200:201], v[108:109]
	v_pk_fma_f32 v[110:111], v[178:179], v[202:203], v[110:111]
	v_pk_fma_f32 v[108:109], v[176:177], v[196:197], v[108:109]
	v_pk_fma_f32 v[100:101], v[198:199], v[100:101], v[110:111]
	v_pk_mul_f32 v[96:97], v[184:185], v[96:97]
	v_pk_fma_f32 v[110:111], v[182:183], v[206:207], v[210:211]
	v_pk_mul_f32 v[184:185], v[108:109], v[226:227]
	v_pk_fma_f32 v[108:109], v[164:165], v[204:205], v[208:209]
; #define PG8_LAS __attribute__((address_space(3)))
;     __device__ __forceinline__ void operator()(f32x4 (&acc)[2][2][4][2], const pg8::Unit& u, int wr, int wc, int fr, int fq) const {
;     ...
;             for (int n = 0; n < 2; ++n) {
;                 f32x4 g[4];
;                 {   const PG8_LAS unsigned char* wq = wl + (8 * fq + 4 * n) * 4;
;                     const f32x4 w0 = *(const PG8_LAS f32x4*)(wq), w1 = *(const PG8_LAS f32x4*)(wq + 256), w2 = *(const PG8_LAS f32x4*)(wq + 512), bb = *(const PG8_LAS f32x4*)(wq + 768);
;                     const f32x4 x0 = acc[ai][0][0][n] * rstd[0], x1 = acc[ai][0][1][n] * rstd[1], x2 = acc[ai][0][2][n] * rstd[2], x3 = acc[ai][0][3][n] * rstd[3];
;                     acc[ai][0][0][n] = x0; acc[ai][0][1][n] = x1; acc[ai][0][2][n] = x2; acc[ai][0][3][n] = x3;
;                     f32x4 p1, p2;
; #pragma unroll
;                     for (int c = 0; c < 4; ++c) { p1[c] = row_up1(x3[c]); p2[c] = row_up1(x2[c]); }
;                     g[0] = bb + w2 * x0 + w1 * p1 + w0 * p2; g[1] = bb + w2 * x1 + w1 * x0 + w0 * p1;
;                     g[2] = bb + w2 * x2 + w1 * x1 + w0 * x0; g[3] = bb + w2 * x3 + w1 * x2 + w0 * x1;
; #pragma unroll
;                     for (int m = 0; m < 4; ++m)
; #pragma unroll
;                         for (int c = 0; c < 4; ++c) g[m][c] = siluf_(g[m][c]);
;                 }
;                 __builtin_amdgcn_sched_barrier(0);
;                 {   const PG8_LAS unsigned char* wq = wl + 128 + (8 * fq + 4 * n) * 4;
;                     const f32x4 w0 = *(const PG8_LAS f32x4*)(wq), w1 = *(const PG8_LAS f32x4*)(wq + 256), w2 = *(const PG8_LAS f32x4*)(wq + 512), bb = *(const PG8_LAS f32x4*)(wq + 768);
;                     const f32x4 x0 = acc[ai][1][0][n] * rstd[0], x1 = acc[ai][1][1][n] * rstd[1], x2 = acc[ai][1][2][n] * rstd[2], x3 = acc[ai][1][3][n] * rstd[3];
;                     acc[ai][1][0][n] = x0; acc[ai][1][1][n] = x1; acc[ai][1][2][n] = x2; acc[ai][1][3][n] = x3;
;                     f32x4 p1, p2;
; #pragma unroll
;                     for (int c = 0; c < 4; ++c) { p1[c] = row_up1(x3[c]); p2[c] = row_up1(x2[c]); }
;                     g[0] *= bb + w2 * x0 + w1 * p1 + w0 * p2; g[1] *= bb + w2 * x1 + w1 * x0 + w0 * p1;
;                     g[2] *= bb + w2 * x2 + w1 * x1 + w0 * x0; g[3] *= bb + w2 * x3 + w1 * x2 + w0 * x1;
;                 }
; #pragma unroll
	v_pk_fma_f32 v[204:205], v[166:167], v[206:207], v[210:211]
	v_pk_fma_f32 v[110:111], v[162:163], v[202:203], v[110:111]
	v_pk_fma_f32 v[202:203], v[182:183], v[202:203], v[204:205]
	v_pk_fma_f32 v[108:109], v[180:181], v[200:201], v[108:109]
	v_pk_mul_f32 v[106:107], v[212:213], v[222:223]
	v_pk_fma_f32 v[110:111], v[178:179], v[198:199], v[110:111]
	v_pk_fma_f32 v[108:109], v[160:161], v[196:197], v[108:109]
	v_pk_fma_f32 v[196:197], v[162:163], v[198:199], v[202:203]
	v_pk_mul_f32 v[104:105], v[214:215], v[220:221]
	v_pk_mul_f32 v[102:103], v[218:219], v[102:103]
	v_pk_mul_f32 v[98:99], v[216:217], v[98:99]
	v_pk_mul_f32 v[100:101], v[224:225], v[100:101]
	v_pk_mul_f32 v[110:111], v[110:111], v[228:229]
	v_pk_mul_f32 v[106:107], v[196:197], v[106:107]
	v_pk_mul_f32 v[196:197], v[108:109], v[104:105]
	v_cvt_pk_bf16_f32 v108, v98, v99
	v_cvt_pk_bf16_f32 v109, v102, v103
	v_cvt_pk_bf16_f32 v104, v96, v97
	v_cvt_pk_bf16_f32 v105, v100, v101
	v_cvt_pk_bf16_f32 v100, v184, v185
	v_cvt_pk_bf16_f32 v101, v110, v111
	s_nop 0
	v_cvt_pk_bf16_f32 v96, v196, v197
	v_cvt_pk_bf16_f32 v97, v106, v107
	ds_read_b128 v[196:199], v195 offset:16
	ds_read_b128 v[200:203], v195 offset:272
	ds_read_b128 v[204:207], v195 offset:528
	ds_read_b128 v[208:211], v195 offset:784
	v_pk_mul_f32 v[92:93], v[92:93], v[174:175] op_sel_hi:[1,0]
	v_pk_mul_f32 v[84:85], v[84:85], v[168:169] op_sel_hi:[1,0]
	v_pk_mul_f32 v[88:89], v[88:89], v[170:171] op_sel_hi:[1,0]
	v_pk_mul_f32 v[80:81], v[80:81], v[172:173] op_sel_hi:[1,0]
	v_mov_b32_dpp v98, v84 row_shr:1 row_mask:0xf bank_mask:0xf bound_ctrl:1
	v_mov_b32_dpp v99, v85 row_shr:1 row_mask:0xf bank_mask:0xf bound_ctrl:1
	s_waitcnt lgkmcnt(0)
	v_pk_fma_f32 v[212:213], v[92:93], v[204:205], v[208:209]
	v_mov_b32_dpp v102, v88 row_shr:1 row_mask:0xf bank_mask:0xf bound_ctrl:1
	v_mov_b32_dpp v103, v89 row_shr:1 row_mask:0xf bank_mask:0xf bound_ctrl:1
	v_pk_fma_f32 v[212:213], v[200:201], v[98:99], v[212:213]
	v_pk_mul_f32 v[94:95], v[94:95], v[174:175] op_sel_hi:[1,0]
	v_pk_fma_f32 v[102:103], v[196:197], v[102:103], v[212:213]
	v_pk_mul_f32 v[86:87], v[86:87], v[168:169] op_sel_hi:[1,0]
	v_mul_f32_e32 v155, 0xbfb8aa3b, v102
	v_exp_f32_e32 v155, v155
	v_mul_f32_e32 v157, 0xbfb8aa3b, v103
	v_pk_fma_f32 v[212:213], v[80:81], v[204:205], v[208:209]
	v_exp_f32_e32 v157, v157
	v_pk_mul_f32 v[90:91], v[90:91], v[170:171] op_sel_hi:[1,0]
	v_mov_b32_dpp v106, v86 row_shr:1 row_mask:0xf bank_mask:0xf bound_ctrl:1
	v_mov_b32_dpp v107, v87 row_shr:1 row_mask:0xf bank_mask:0xf bound_ctrl:1
	v_pk_fma_f32 v[184:185], v[94:95], v[206:207], v[210:211]
	v_pk_fma_f32 v[212:213], v[92:93], v[200:201], v[212:213]
	v_mov_b32_dpp v110, v90 row_shr:1 row_mask:0xf bank_mask:0xf bound_ctrl:1
	v_mov_b32_dpp v111, v91 row_shr:1 row_mask:0xf bank_mask:0xf bound_ctrl:1
	v_pk_fma_f32 v[184:185], v[202:203], v[106:107], v[184:185]
	v_pk_fma_f32 v[98:99], v[196:197], v[98:99], v[212:213]
	v_pk_fma_f32 v[212:213], v[88:89], v[204:205], v[208:209]
	v_pk_fma_f32 v[204:205], v[84:85], v[204:205], v[208:209]
	v_pk_fma_f32 v[110:111], v[198:199], v[110:111], v[184:185]
	v_pk_fma_f32 v[212:213], v[80:81], v[200:201], v[212:213]
	v_pk_fma_f32 v[200:201], v[88:89], v[200:201], v[204:205]
	v_add_f32_e32 v155, 1.0, v155
	v_pk_fma_f32 v[212:213], v[92:93], v[196:197], v[212:213]
	v_pk_fma_f32 v[216:217], v[80:81], v[196:197], v[200:201]
	v_rcp_f32_e32 v196, v155
	v_add_f32_e32 v155, 1.0, v157
	v_mul_f32_e32 v157, 0xbfb8aa3b, v110
	v_pk_mul_f32 v[82:83], v[82:83], v[172:173] op_sel_hi:[1,0]
	v_exp_f32_e32 v157, v157
	v_mul_f32_e32 v173, 0xbfb8aa3b, v111
	v_pk_fma_f32 v[184:185], v[82:83], v[206:207], v[210:211]
	v_exp_f32_e32 v173, v173
	v_pk_fma_f32 v[184:185], v[94:95], v[202:203], v[184:185]
	v_rcp_f32_e32 v197, v155
	v_pk_fma_f32 v[106:107], v[198:199], v[106:107], v[184:185]
	v_pk_fma_f32 v[184:185], v[90:91], v[206:207], v[210:211]
	v_pk_fma_f32 v[206:207], v[86:87], v[206:207], v[210:211]
	v_pk_fma_f32 v[184:185], v[82:83], v[202:203], v[184:185]
	v_pk_fma_f32 v[202:203], v[90:91], v[202:203], v[206:207]
	v_add_f32_e32 v155, 1.0, v157
	v_pk_fma_f32 v[184:185], v[94:95], v[198:199], v[184:185]
	v_pk_fma_f32 v[214:215], v[82:83], v[198:199], v[202:203]
	v_rcp_f32_e32 v198, v155
	v_add_f32_e32 v155, 1.0, v173
	v_rcp_f32_e32 v199, v155
	v_mul_f32_e32 v155, 0xbfb8aa3b, v98
	v_exp_f32_e32 v155, v155
	v_mul_f32_e32 v157, 0xbfb8aa3b, v99
	v_exp_f32_e32 v157, v157
	v_pk_mul_f32 v[102:103], v[102:103], v[196:197]
	v_add_f32_e32 v155, 1.0, v155
	v_rcp_f32_e32 v196, v155
	v_add_f32_e32 v155, 1.0, v157
	v_mul_f32_e32 v157, 0xbfb8aa3b, v106
	v_exp_f32_e32 v157, v157
	v_mul_f32_e32 v173, 0xbfb8aa3b, v107
	v_exp_f32_e32 v173, v173
	v_rcp_f32_e32 v197, v155
	v_add_f32_e32 v155, 1.0, v157
	v_pk_mul_f32 v[110:111], v[110:111], v[198:199]
	v_rcp_f32_e32 v198, v155
	v_add_f32_e32 v155, 1.0, v173
	v_rcp_f32_e32 v199, v155
	v_mul_f32_e32 v155, 0xbfb8aa3b, v212
	v_exp_f32_e32 v155, v155
	v_mul_f32_e32 v157, 0xbfb8aa3b, v213
	v_exp_f32_e32 v157, v157
	v_pk_mul_f32 v[98:99], v[98:99], v[196:197]
	v_add_f32_e32 v155, 1.0, v155
	v_rcp_f32_e32 v196, v155
	v_add_f32_e32 v155, 1.0, v157
	v_mul_f32_e32 v157, 0xbfb8aa3b, v184
	v_exp_f32_e32 v157, v157
	v_mul_f32_e32 v173, 0xbfb8aa3b, v185
	v_exp_f32_e32 v173, v173
	v_rcp_f32_e32 v197, v155
	v_add_f32_e32 v155, 1.0, v157
	v_mul_f32_e32 v157, 0xbfb8aa3b, v216
	v_rcp_f32_e32 v200, v155
	v_add_f32_e32 v155, 1.0, v173
	v_exp_f32_e32 v157, v157
	v_mul_f32_e32 v173, 0xbfb8aa3b, v217
	v_exp_f32_e32 v173, v173
	v_rcp_f32_e32 v201, v155
	v_add_f32_e32 v155, 1.0, v157
	v_mul_f32_e32 v157, 0xbfb8aa3b, v214
	v_rcp_f32_e32 v218, v155
	v_add_f32_e32 v155, 1.0, v173
	v_exp_f32_e32 v157, v157
	v_mul_f32_e32 v173, 0xbfb8aa3b, v215
	v_exp_f32_e32 v173, v173
	v_rcp_f32_e32 v219, v155
	v_add_f32_e32 v155, 1.0, v157
	v_rcp_f32_e32 v220, v155
	v_add_f32_e32 v155, 1.0, v173
	v_pk_mul_f32 v[106:107], v[106:107], v[198:199]
	v_rcp_f32_e32 v221, v155
	v_pk_mul_f32 v[212:213], v[212:213], v[196:197]
	v_pk_mul_f32 v[222:223], v[184:185], v[200:201]
	ds_read_b128 v[196:199], v195 offset:144
	ds_read_b128 v[200:203], v195 offset:400
	ds_read_b128 v[204:207], v195 offset:656
	ds_read_b128 v[208:211], v195 offset:912
	v_pk_mul_f32 v[184:185], v[66:67], v[174:175] op_sel_hi:[1,0]
	v_pk_mul_f32 v[174:175], v[64:65], v[174:175] op_sel_hi:[1,0]
	v_pk_mul_f32 v[66:67], v[68:69], v[172:173] op_sel_hi:[1,0]
	v_pk_mul_f32 v[68:69], v[76:77], v[168:169] op_sel_hi:[1,0]
	v_pk_mul_f32 v[70:71], v[70:71], v[172:173] op_sel_hi:[1,0]
	v_pk_mul_f32 v[172:173], v[74:75], v[170:171] op_sel_hi:[1,0]
	v_pk_mul_f32 v[74:75], v[72:73], v[170:171] op_sel_hi:[1,0]
	v_mov_b32_dpp v64, v68 row_shr:1 row_mask:0xf bank_mask:0xf bound_ctrl:1
	v_mov_b32_dpp v65, v69 row_shr:1 row_mask:0xf bank_mask:0xf bound_ctrl:1
	v_pk_mul_f32 v[216:217], v[216:217], v[218:219]
	s_waitcnt lgkmcnt(0)
; __device__ __forceinline__ unsigned pk2(float a, float b) { return pg8::cvt_pk_bf16(a, b); }
;     __device__ __forceinline__ void operator()(f32x4 (&acc)[2][2][4][2], const pg8::Unit& u, int wr, int wc, int fr, int fq) const {
;     ...
;                     g[0] *= bb + w2 * x0 + w1 * p1 + w0 * p2; g[1] *= bb + w2 * x1 + w1 * x0 + w0 * p1;
;                     g[2] *= bb + w2 * x2 + w1 * x1 + w0 * x0; g[3] *= bb + w2 * x3 + w1 * x2 + w0 * x1;
;                 }
; #pragma unroll
;                 for (int m = 0; m < 4; ++m) { pk[n][m].x = pk2(g[m][0], g[m][1]); pk[n][m].y = pk2(g[m][2], g[m][3]); }
;                 __builtin_amdgcn_sched_barrier(0);
;             }
; #pragma unroll
;             for (int m = 0; m < 4; ++m) if (fr != 0 || m >= 2) {
;                 u32x4 w; w.x = pk[0][m].x; w.y = pk[0][m].y; w.z = pk[1][m].x; w.w = pk[1][m].y;
;                 *(u32x4*)(ACT + (size_t)(tb + m) * DFF + colj) = w; }
;             const int seg = u.pm * 4 + ai * 2 + wr;
;             if (fr == 0 || fr == 15) {
; #pragma unroll
;                 for (int mm = 0; mm < 2; ++mm) { const int m = (fr == 0) ? mm : 2 + mm;
; #pragma unroll
;                     for (int bj = 0; bj < 2; ++bj) { const f32x4 v0 = (fr == 0) ? acc[ai][bj][mm][0] : acc[ai][bj][2 + mm][0], v1 = (fr == 0) ? acc[ai][bj][mm][1] : acc[ai][bj][2 + mm][1];
;                         u32x4 w; w.x = pk2(v0[0], v0[1]); w.y = pk2(v0[2], v0[3]); w.z = pk2(v1[0], v1[1]); w.w = pk2(v1[2], v1[3]);
;                         *(u32x4*)(HALO + ((size_t)(seg * 4 + m) * 2 + bj) * DFF + colj) = w; } }
	v_pk_fma_f32 v[218:219], v[174:175], v[204:205], v[208:209]
	v_pk_mul_f32 v[72:73], v[78:79], v[168:169] op_sel_hi:[1,0]
	v_mov_b32_dpp v76, v74 row_shr:1 row_mask:0xf bank_mask:0xf bound_ctrl:1
	v_mov_b32_dpp v77, v75 row_shr:1 row_mask:0xf bank_mask:0xf bound_ctrl:1
	v_pk_fma_f32 v[218:219], v[200:201], v[64:65], v[218:219]
	v_mov_b32_dpp v78, v72 row_shr:1 row_mask:0xf bank_mask:0xf bound_ctrl:1
	v_mov_b32_dpp v79, v73 row_shr:1 row_mask:0xf bank_mask:0xf bound_ctrl:1
	v_pk_mul_f32 v[214:215], v[214:215], v[220:221]
	v_pk_fma_f32 v[220:221], v[184:185], v[206:207], v[210:211]
	v_pk_fma_f32 v[76:77], v[196:197], v[76:77], v[218:219]
	v_mov_b32_dpp v224, v172 row_shr:1 row_mask:0xf bank_mask:0xf bound_ctrl:1
	v_mov_b32_dpp v225, v173 row_shr:1 row_mask:0xf bank_mask:0xf bound_ctrl:1
	v_pk_fma_f32 v[220:221], v[202:203], v[78:79], v[220:221]
	v_pk_mul_f32 v[76:77], v[102:103], v[76:77]
	v_pk_fma_f32 v[102:103], v[66:67], v[204:205], v[208:209]
	v_pk_fma_f32 v[218:219], v[198:199], v[224:225], v[220:221]
	v_pk_fma_f32 v[102:103], v[174:175], v[200:201], v[102:103]
	v_pk_mul_f32 v[218:219], v[110:111], v[218:219]
	v_pk_fma_f32 v[110:111], v[70:71], v[206:207], v[210:211]
	v_pk_fma_f32 v[64:65], v[196:197], v[64:65], v[102:103]
	v_pk_fma_f32 v[102:103], v[172:173], v[206:207], v[210:211]
	v_pk_fma_f32 v[110:111], v[184:185], v[202:203], v[110:111]
	v_pk_fma_f32 v[102:103], v[70:71], v[202:203], v[102:103]
	v_pk_fma_f32 v[78:79], v[198:199], v[78:79], v[110:111]
	v_pk_mul_f32 v[64:65], v[98:99], v[64:65]
	v_pk_fma_f32 v[98:99], v[74:75], v[204:205], v[208:209]
	v_pk_fma_f32 v[102:103], v[184:185], v[198:199], v[102:103]
	v_pk_mul_f32 v[78:79], v[106:107], v[78:79]
	v_pk_fma_f32 v[98:99], v[66:67], v[200:201], v[98:99]
	v_pk_mul_f32 v[220:221], v[222:223], v[102:103]
	v_pk_fma_f32 v[102:103], v[68:69], v[204:205], v[208:209]
	v_pk_fma_f32 v[106:107], v[72:73], v[206:207], v[210:211]
	v_pk_fma_f32 v[98:99], v[174:175], v[196:197], v[98:99]
	v_pk_fma_f32 v[106:107], v[172:173], v[202:203], v[106:107]
	v_pk_fma_f32 v[102:103], v[74:75], v[200:201], v[102:103]
	v_pk_mul_f32 v[98:99], v[212:213], v[98:99]
	v_pk_fma_f32 v[102:103], v[66:67], v[196:197], v[102:103]
	v_pk_fma_f32 v[106:107], v[70:71], v[198:199], v[106:107]
	v_pk_mul_f32 v[198:199], v[216:217], v[102:103]
	v_pk_mul_f32 v[196:197], v[214:215], v[106:107]
	v_cvt_pk_bf16_f32 v110, v76, v77
	v_cvt_pk_bf16_f32 v111, v218, v219
	v_cvt_pk_bf16_f32 v106, v64, v65
	v_cvt_pk_bf16_f32 v107, v78, v79
	v_cvt_pk_bf16_f32 v102, v98, v99
	v_cvt_pk_bf16_f32 v103, v220, v221
	v_cvt_pk_bf16_f32 v98, v198, v199
	s_nop 0
	v_cvt_pk_bf16_f32 v99, v196, v197
	v_lshlrev_b64 v[64:65], 1, v[158:159]
	s_and_saveexec_b64 s[8:9], s[0:1]
	s_cbranch_execz .LBB0_750
	v_mov_b64_e32 v[76:77], s[22:23]
	v_mad_i64_i32 v[78:79], s[10:11], v148, s56, v[76:77]
	v_mad_i64_i32 v[76:77], s[10:11], v150, s56, v[76:77]
	v_lshl_add_u64 v[78:79], v[78:79], 0, v[64:65]
	v_lshl_add_u64 v[76:77], v[76:77], 0, v[64:65]
	global_store_dwordx4 v[78:79], v[108:111], off nt
	global_store_dwordx4 v[76:77], v[104:107], off nt
.LBB0_750:
	s_or_b64 exec, exec, s[8:9]
	v_mov_b64_e32 v[76:77], s[22:23]
	v_mad_i64_i32 v[78:79], s[8:9], v154, s56, v[76:77]
	v_mad_i64_i32 v[76:77], s[8:9], v156, s56, v[76:77]
	v_lshl_add_u64 v[78:79], v[78:79], 0, v[64:65]
	v_lshl_add_u64 v[76:77], v[76:77], 0, v[64:65]
	v_cmp_gt_i32_e32 vcc, 15, v169
	s_mov_b64 s[10:11], -1
	global_store_dwordx4 v[78:79], v[100:103], off nt
	global_store_dwordx4 v[76:77], v[96:99], off nt
	s_and_saveexec_b64 s[8:9], vcc
	v_cmp_eq_u32_e32 vcc, 0, v169
	s_orn2_b64 s[10:11], vcc, exec
	s_or_b64 exec, exec, s[8:9]
	s_and_saveexec_b64 s[8:9], s[10:11]
	s_cbranch_execz .LBB0_754
	s_lshl_b32 s10, s34, 4
	s_add_i32 s12, s10, s57
	v_cndmask_b32_e64 v77, v118, v126, s[6:7]
	v_cndmask_b32_e64 v78, v119, v127, s[6:7]
	v_cndmask_b32_e64 v76, v116, v124, s[6:7]
	v_cndmask_b32_e64 v88, v88, v92, s[6:7]
	v_cndmask_b32_e64 v89, v89, v93, s[6:7]
	v_or_b32_e32 v96, s12, v188
	v_cndmask_b32_e64 v79, v117, v125, s[6:7]
	v_cndmask_b32_e64 v90, v90, v94, s[6:7]
	v_cndmask_b32_e64 v91, v91, v95, s[6:7]
	v_cvt_pk_bf16_f32 v76, v76, v79
	v_cvt_pk_bf16_f32 v77, v77, v78
	v_cvt_pk_bf16_f32 v78, v88, v89
	v_mov_b64_e32 v[88:89], s[28:29]
	v_cvt_pk_bf16_f32 v79, v90, v91
	v_mad_i64_i32 v[90:91], s[10:11], v96, s64, v[88:89]
	v_lshl_add_u64 v[90:91], v[90:91], 0, v[64:65]
	global_store_dwordx4 v[90:91], v[76:79], off nt
	v_cndmask_b32_e64 v94, v74, v174, s[6:7]
	v_cndmask_b32_e64 v92, v172, v184, s[6:7]
	v_cndmask_b32_e64 v78, v180, v176, s[6:7]
	v_cndmask_b32_e64 v76, v182, v178, s[6:7]
	v_cndmask_b32_e64 v77, v183, v179, s[6:7]
	v_cndmask_b32_e64 v79, v181, v177, s[6:7]
	v_cvt_pk_bf16_f32 v74, v78, v79
	v_add_co_u32_e32 v78, vcc, s65, v90
	v_cndmask_b32_e64 v93, v173, v185, s[6:7]
	v_cndmask_b32_e64 v95, v75, v175, s[6:7]
	v_cvt_pk_bf16_f32 v75, v76, v77
	v_cvt_pk_bf16_f32 v76, v94, v95
	v_cvt_pk_bf16_f32 v77, v92, v93
	v_addc_co_u32_e32 v79, vcc, 0, v91, vcc
	global_store_dwordx4 v[78:79], v[74:77], off offset:1536 nt
	v_or_b32_e32 v78, s12, v189
	v_cndmask_b32_e64 v79, v86, v82, s[6:7]
	v_cndmask_b32_e64 v75, v114, v122, s[6:7]
	v_cndmask_b32_e64 v76, v115, v123, s[6:7]
	v_cndmask_b32_e64 v74, v112, v120, s[6:7]
	v_cndmask_b32_e64 v77, v113, v121, s[6:7]
	v_cndmask_b32_e64 v82, v87, v83, s[6:7]
	v_cndmask_b32_e64 v80, v84, v80, s[6:7]
	v_cndmask_b32_e64 v81, v85, v81, s[6:7]
	v_cvt_pk_bf16_f32 v74, v74, v77
	v_cvt_pk_bf16_f32 v75, v75, v76
	v_cvt_pk_bf16_f32 v76, v80, v81
	v_cvt_pk_bf16_f32 v77, v79, v82
	v_mad_i64_i32 v[78:79], s[10:11], v78, s64, v[88:89]
	v_lshl_add_u64 v[78:79], v[78:79], 0, v[64:65]
	v_cndmask_b32_e64 v70, v72, v70, s[6:7]
	v_cndmask_b32_e64 v68, v68, v66, s[6:7]
	v_cndmask_b32_e64 v69, v69, v67, s[6:7]
	global_store_dwordx4 v[78:79], v[74:77], off nt
	v_cndmask_b32_e64 v71, v73, v71, s[6:7]
	s_nop 0
	v_cndmask_b32_e64 v74, v166, v162, s[6:7]
	v_cndmask_b32_e64 v75, v167, v163, s[6:7]
	v_cndmask_b32_e64 v76, v164, v160, s[6:7]
	v_cndmask_b32_e64 v77, v165, v161, s[6:7]
	v_cvt_pk_bf16_f32 v66, v76, v77
	v_cvt_pk_bf16_f32 v67, v74, v75
	v_cvt_pk_bf16_f32 v68, v68, v69
	v_cvt_pk_bf16_f32 v69, v70, v71
	v_add_co_u32_e32 v70, vcc, 0x1000, v78
	s_nop 1
	v_addc_co_u32_e32 v71, vcc, 0, v79, vcc
	global_store_dwordx4 v[70:71], v[66:69], off offset:1536 nt
; #define PG8_LAS __attribute__((address_space(3)))
; __device__ __forceinline__ float row_up1(float v) { return dpp_mov<0x111>(v); }
; __device__ __forceinline__ float siluf_(float x) { return x * __builtin_amdgcn_rcpf(1.0f + __builtin_amdgcn_exp2f(x * -1.4426950408889634f)); }
;     __device__ __forceinline__ void operator()(f32x4 (&acc)[2][2][4][2], const pg8::Unit& u, int wr, int wc, int fr, int fq) const {
;     ...
;             const int tb = u.pm * 256 + ai * 128 + wr * 64 + 4 * fr;
;             float rstd[4];
; #pragma unroll
;             for (int m = 0; m < 4; ++m) { const f32x4 sv = *(const f32x4*)(SS + (size_t)(tb + m) * 16 + 4 * fq); float s = (sv[0] + sv[1]) + (sv[2] + sv[3]); s += __shfl_xor(s, 16); s += __shfl_xor(s, 32);
;                 rstd[m] = rsqrtf(s * (1.0f / 1024.0f) + EPS); }
;             u32x2 pk[2][4];
; #pragma unroll
;             for (int n = 0; n < 2; ++n) {
;                 f32x4 g[4];
;                 {   const PG8_LAS unsigned char* wq = wl + (8 * fq + 4 * n) * 4;
;                     const f32x4 w0 = *(const PG8_LAS f32x4*)(wq), w1 = *(const PG8_LAS f32x4*)(wq + 256), w2 = *(const PG8_LAS f32x4*)(wq + 512), bb = *(const PG8_LAS f32x4*)(wq + 768);
;                     const f32x4 x0 = acc[ai][0][0][n] * rstd[0], x1 = acc[ai][0][1][n] * rstd[1], x2 = acc[ai][0][2][n] * rstd[2], x3 = acc[ai][0][3][n] * rstd[3];
;                     acc[ai][0][0][n] = x0; acc[ai][0][1][n] = x1; acc[ai][0][2][n] = x2; acc[ai][0][3][n] = x3;
;                     f32x4 p1, p2;
; #pragma unroll
;                     for (int c = 0; c < 4; ++c) { p1[c] = row_up1(x3[c]); p2[c] = row_up1(x2[c]); }
;                     g[0] = bb + w2 * x0 + w1 * p1 + w0 * p2; g[1] = bb + w2 * x1 + w1 * x0 + w0 * p1;
;                     g[2] = bb + w2 * x2 + w1 * x1 + w0 * x0; g[3] = bb + w2 * x3 + w1 * x2 + w0 * x1;
; #pragma unroll
;                     for (int m = 0; m < 4; ++m)
; #pragma unroll
;                         for (int c = 0; c < 4; ++c) g[m][c] = siluf_(g[m][c]);
.LBB0_754:
	s_or_b64 exec, exec, s[8:9]
	s_nop 0
	v_add_u32_e32 v66, 0x80, v148
	v_ashrrev_i32_e32 v67, 31, v66
	v_lshlrev_b64 v[68:69], 6, v[66:67]
	v_lshl_add_u64 v[70:71], v[138:139], 0, v[68:69]
	v_add_u32_e32 v68, 0x81, v148
	v_ashrrev_i32_e32 v69, 31, v68
	v_lshlrev_b64 v[72:73], 6, v[68:69]
	v_lshl_add_u64 v[72:73], v[138:139], 0, v[72:73]
	global_load_dwordx4 v[74:77], v[70:71], off
	global_load_dwordx4 v[78:81], v[72:73], off
	v_add_u32_e32 v70, 0x82, v148
	v_ashrrev_i32_e32 v71, 31, v70
	v_lshlrev_b64 v[72:73], 6, v[70:71]
	v_lshl_add_u64 v[72:73], v[138:139], 0, v[72:73]
	global_load_dwordx4 v[82:85], v[72:73], off
	v_add_u32_e32 v72, 0x83, v148
	v_ashrrev_i32_e32 v73, 31, v72
	v_lshlrev_b64 v[86:87], 6, v[72:73]
	v_lshl_add_u64 v[86:87], v[138:139], 0, v[86:87]
	global_load_dwordx4 v[86:89], v[86:87], off
	s_waitcnt vmcnt(3)
	v_mov_b32_e32 v90, v75
	v_mov_b32_e32 v91, v76
	v_mov_b32_e32 v75, v77
	s_waitcnt vmcnt(2)
	v_mov_b32_e32 v76, v79
	v_mov_b32_e32 v77, v80
	v_mov_b32_e32 v79, v81
	s_waitcnt vmcnt(1)
	v_mov_b32_e32 v80, v83
	v_mov_b32_e32 v81, v84
	v_mov_b32_e32 v83, v85
	v_pk_add_f32 v[74:75], v[90:91], v[74:75]
	v_pk_add_f32 v[76:77], v[76:77], v[78:79]
	s_waitcnt vmcnt(0)
	v_mov_b32_e32 v84, v87
	v_mov_b32_e32 v85, v88
	v_mov_b32_e32 v87, v89
	v_pk_add_f32 v[78:79], v[80:81], v[82:83]
	v_pk_add_f32 v[80:81], v[84:85], v[86:87]
	v_mov_b32_e32 v82, v76
	v_mov_b32_e32 v83, v74
	v_mov_b32_e32 v74, v77
	v_mov_b32_e32 v76, v80
	v_mov_b32_e32 v77, v78
	v_mov_b32_e32 v78, v81
	v_pk_add_f32 v[74:75], v[82:83], v[74:75]
	v_pk_add_f32 v[76:77], v[76:77], v[78:79]
	ds_bpermute_b32 v79, v149, v75
	ds_bpermute_b32 v78, v149, v74
	ds_bpermute_b32 v81, v149, v77
	ds_bpermute_b32 v80, v149, v76
	v_mov_b64_e32 v[82:83], s[38:39]
	s_waitcnt lgkmcnt(2)
	v_pk_add_f32 v[84:85], v[74:75], v[78:79]
	ds_bpermute_b32 v89, v151, v85
	s_waitcnt lgkmcnt(1)
	v_pk_add_f32 v[86:87], v[76:77], v[80:81]
	ds_bpermute_b32 v88, v151, v84
	ds_bpermute_b32 v99, v151, v87
	ds_bpermute_b32 v98, v151, v86
	ds_read_b128 v[74:77], v195
	ds_read_b128 v[78:81], v195 offset:256
	ds_read_b128 v[90:93], v195 offset:512
	ds_read_b128 v[94:97], v195 offset:768
	s_waitcnt lgkmcnt(6)
	v_pk_add_f32 v[84:85], v[84:85], v[88:89]
	s_nop 0
	v_pk_fma_f32 v[84:85], v[84:85], s[24:25], v[82:83] op_sel_hi:[1,0,0]
	s_waitcnt lgkmcnt(4)
	v_pk_add_f32 v[86:87], v[86:87], v[98:99]
	v_mul_f32_e32 v67, 0x4b800000, v85
	v_pk_fma_f32 v[82:83], v[86:87], s[24:25], v[82:83] op_sel_hi:[1,0,0]
	v_cmp_gt_f32_e32 vcc, s63, v85
	v_mul_f32_e32 v73, 0x4b800000, v82
	v_cmp_gt_f32_e64 s[12:13], s63, v82
	v_mul_f32_e32 v69, 0x4b800000, v84
	v_mul_f32_e32 v71, 0x4b800000, v83
	v_cndmask_b32_e32 v67, v85, v67, vcc
	v_cmp_gt_f32_e64 s[8:9], s63, v84
	v_cmp_gt_f32_e64 s[10:11], s63, v83
	v_cndmask_b32_e64 v73, v82, v73, s[12:13]
	v_cndmask_b32_e64 v69, v84, v69, s[8:9]
	v_cndmask_b32_e64 v71, v83, v71, s[10:11]
	v_rsq_f32_e32 v67, v67
	v_rsq_f32_e32 v73, v73
	v_rsq_f32_e32 v69, v69
	v_rsq_f32_e32 v71, v71
	v_mul_f32_e32 v82, 0x45800000, v67
	v_mul_f32_e32 v85, 0x45800000, v73
	v_mul_f32_e32 v83, 0x45800000, v69
	v_mul_f32_e32 v84, 0x45800000, v71
	v_cndmask_b32_e32 v88, v67, v82, vcc
	v_cndmask_b32_e64 v82, v73, v85, s[12:13]
	v_cndmask_b32_e64 v84, v71, v84, s[10:11]
	v_pk_mul_f32 v[60:61], v[60:61], v[88:89] op_sel_hi:[1,0]
	v_pk_mul_f32 v[48:49], v[48:49], v[82:83] op_sel_hi:[1,0]
	v_pk_mul_f32 v[52:53], v[52:53], v[84:85] op_sel_hi:[1,0]
	s_waitcnt lgkmcnt(0)
	v_pk_fma_f32 v[108:109], v[90:91], v[60:61], v[94:95]
	v_mov_b32_dpp v98, v48 row_shr:1 row_mask:0xf bank_mask:0xf bound_ctrl:1
	v_mov_b32_dpp v99, v49 row_shr:1 row_mask:0xf bank_mask:0xf bound_ctrl:1
	v_mov_b32_dpp v100, v52 row_shr:1 row_mask:0xf bank_mask:0xf bound_ctrl:1
	v_mov_b32_dpp v101, v53 row_shr:1 row_mask:0xf bank_mask:0xf bound_ctrl:1
	v_pk_fma_f32 v[108:109], v[78:79], v[98:99], v[108:109]
	v_cndmask_b32_e64 v86, v69, v83, s[8:9]
	v_pk_fma_f32 v[100:101], v[74:75], v[100:101], v[108:109]
	v_pk_mul_f32 v[62:63], v[62:63], v[88:89] op_sel_hi:[1,0]
	v_mul_f32_e32 v67, 0xbfb8aa3b, v100
	v_exp_f32_e32 v67, v67
	v_mul_f32_e32 v69, 0xbfb8aa3b, v101
	v_pk_mul_f32 v[50:51], v[50:51], v[82:83] op_sel_hi:[1,0]
	v_exp_f32_e32 v69, v69
	v_pk_mul_f32 v[56:57], v[56:57], v[86:87] op_sel_hi:[1,0]
	v_pk_mul_f32 v[54:55], v[54:55], v[84:85] op_sel_hi:[1,0]
	v_mov_b32_dpp v102, v50 row_shr:1 row_mask:0xf bank_mask:0xf bound_ctrl:1
	v_mov_b32_dpp v103, v51 row_shr:1 row_mask:0xf bank_mask:0xf bound_ctrl:1
	v_pk_fma_f32 v[106:107], v[92:93], v[62:63], v[96:97]
	v_mov_b32_dpp v104, v54 row_shr:1 row_mask:0xf bank_mask:0xf bound_ctrl:1
	v_mov_b32_dpp v105, v55 row_shr:1 row_mask:0xf bank_mask:0xf bound_ctrl:1
	v_pk_fma_f32 v[112:113], v[90:91], v[56:57], v[94:95]
	v_pk_fma_f32 v[106:107], v[80:81], v[102:103], v[106:107]
	v_pk_fma_f32 v[108:109], v[90:91], v[52:53], v[94:95]
	v_pk_fma_f32 v[90:91], v[90:91], v[48:49], v[94:95]
	v_pk_fma_f32 v[112:113], v[78:79], v[60:61], v[112:113]
	v_pk_fma_f32 v[104:105], v[76:77], v[104:105], v[106:107]
	v_pk_fma_f32 v[108:109], v[78:79], v[56:57], v[108:109]
	v_pk_fma_f32 v[78:79], v[78:79], v[52:53], v[90:91]
	v_add_f32_e32 v67, 1.0, v67
	v_pk_fma_f32 v[98:99], v[74:75], v[98:99], v[112:113]
	v_pk_fma_f32 v[108:109], v[74:75], v[60:61], v[108:109]
	v_pk_fma_f32 v[116:117], v[74:75], v[56:57], v[78:79]
	v_rcp_f32_e32 v74, v67
	v_add_f32_e32 v67, 1.0, v69
	v_mul_f32_e32 v69, 0xbfb8aa3b, v104
	v_exp_f32_e32 v69, v69
	v_mul_f32_e32 v71, 0xbfb8aa3b, v105
	v_exp_f32_e32 v71, v71
	v_pk_mul_f32 v[58:59], v[58:59], v[86:87] op_sel_hi:[1,0]
	v_pk_fma_f32 v[106:107], v[92:93], v[54:55], v[96:97]
; #define PG8_LAS __attribute__((address_space(3)))
;     __device__ __forceinline__ void operator()(f32x4 (&acc)[2][2][4][2], const pg8::Unit& u, int wr, int wc, int fr, int fq) const {
;     ...
;             for (int n = 0; n < 2; ++n) {
;                 f32x4 g[4];
;                 {   const PG8_LAS unsigned char* wq = wl + (8 * fq + 4 * n) * 4;
;                     const f32x4 w0 = *(const PG8_LAS f32x4*)(wq), w1 = *(const PG8_LAS f32x4*)(wq + 256), w2 = *(const PG8_LAS f32x4*)(wq + 512), bb = *(const PG8_LAS f32x4*)(wq + 768);
;                     const f32x4 x0 = acc[ai][0][0][n] * rstd[0], x1 = acc[ai][0][1][n] * rstd[1], x2 = acc[ai][0][2][n] * rstd[2], x3 = acc[ai][0][3][n] * rstd[3];
;                     acc[ai][0][0][n] = x0; acc[ai][0][1][n] = x1; acc[ai][0][2][n] = x2; acc[ai][0][3][n] = x3;
;                     f32x4 p1, p2;
; #pragma unroll
;                     for (int c = 0; c < 4; ++c) { p1[c] = row_up1(x3[c]); p2[c] = row_up1(x2[c]); }
;                     g[0] = bb + w2 * x0 + w1 * p1 + w0 * p2; g[1] = bb + w2 * x1 + w1 * x0 + w0 * p1;
;                     g[2] = bb + w2 * x2 + w1 * x1 + w0 * x0; g[3] = bb + w2 * x3 + w1 * x2 + w0 * x1;
; #pragma unroll
;                     for (int m = 0; m < 4; ++m)
; #pragma unroll
;                         for (int c = 0; c < 4; ++c) g[m][c] = siluf_(g[m][c]);
;                 }
;                 __builtin_amdgcn_sched_barrier(0);
;                 {   const PG8_LAS unsigned char* wq = wl + 128 + (8 * fq + 4 * n) * 4;
;                     const f32x4 w0 = *(const PG8_LAS f32x4*)(wq), w1 = *(const PG8_LAS f32x4*)(wq + 256), w2 = *(const PG8_LAS f32x4*)(wq + 512), bb = *(const PG8_LAS f32x4*)(wq + 768);
;                     const f32x4 x0 = acc[ai][1][0][n] * rstd[0], x1 = acc[ai][1][1][n] * rstd[1], x2 = acc[ai][1][2][n] * rstd[2], x3 = acc[ai][1][3][n] * rstd[3];
;                     acc[ai][1][0][n] = x0; acc[ai][1][1][n] = x1; acc[ai][1][2][n] = x2; acc[ai][1][3][n] = x3;
;                     f32x4 p1, p2;
; #pragma unroll
;                     for (int c = 0; c < 4; ++c) { p1[c] = row_up1(x3[c]); p2[c] = row_up1(x2[c]); }
;                     g[0] *= bb + w2 * x0 + w1 * p1 + w0 * p2; g[1] *= bb + w2 * x1 + w1 * x0 + w0 * p1;
;                     g[2] *= bb + w2 * x2 + w1 * x1 + w0 * x0; g[3] *= bb + w2 * x3 + w1 * x2 + w0 * x1;
;                 }
; #pragma unroll
	v_pk_fma_f32 v[110:111], v[92:93], v[58:59], v[96:97]
	v_pk_fma_f32 v[92:93], v[92:93], v[50:51], v[96:97]
	v_pk_fma_f32 v[110:111], v[80:81], v[62:63], v[110:111]
	v_pk_fma_f32 v[106:107], v[80:81], v[58:59], v[106:107]
	v_pk_fma_f32 v[80:81], v[80:81], v[54:55], v[92:93]
	v_rcp_f32_e32 v75, v67
	v_add_f32_e32 v67, 1.0, v69
	v_pk_fma_f32 v[102:103], v[76:77], v[102:103], v[110:111]
	v_pk_fma_f32 v[106:107], v[76:77], v[62:63], v[106:107]
	v_pk_fma_f32 v[114:115], v[76:77], v[58:59], v[80:81]
	v_rcp_f32_e32 v76, v67
	v_add_f32_e32 v67, 1.0, v71
	v_rcp_f32_e32 v77, v67
	v_mul_f32_e32 v67, 0xbfb8aa3b, v98
	v_exp_f32_e32 v67, v67
	v_mul_f32_e32 v69, 0xbfb8aa3b, v99
	v_exp_f32_e32 v69, v69
	v_pk_mul_f32 v[118:119], v[100:101], v[74:75]
	v_add_f32_e32 v67, 1.0, v67
	v_rcp_f32_e32 v74, v67
	v_add_f32_e32 v67, 1.0, v69
	v_mul_f32_e32 v69, 0xbfb8aa3b, v102
	v_exp_f32_e32 v69, v69
	v_mul_f32_e32 v71, 0xbfb8aa3b, v103
	v_exp_f32_e32 v71, v71
	v_rcp_f32_e32 v75, v67
	v_add_f32_e32 v67, 1.0, v69
	v_pk_mul_f32 v[120:121], v[104:105], v[76:77]
	v_rcp_f32_e32 v76, v67
	v_add_f32_e32 v67, 1.0, v71
	v_rcp_f32_e32 v77, v67
	v_mul_f32_e32 v67, 0xbfb8aa3b, v108
	v_exp_f32_e32 v67, v67
	v_mul_f32_e32 v69, 0xbfb8aa3b, v109
	v_exp_f32_e32 v69, v69
	v_pk_mul_f32 v[122:123], v[98:99], v[74:75]
	v_add_f32_e32 v67, 1.0, v67
	v_rcp_f32_e32 v74, v67
	v_add_f32_e32 v67, 1.0, v69
	v_mul_f32_e32 v69, 0xbfb8aa3b, v106
	v_exp_f32_e32 v69, v69
	v_mul_f32_e32 v71, 0xbfb8aa3b, v107
	v_exp_f32_e32 v71, v71
	v_rcp_f32_e32 v75, v67
	v_add_f32_e32 v67, 1.0, v69
	v_mul_f32_e32 v69, 0xbfb8aa3b, v116
	v_rcp_f32_e32 v78, v67
	v_add_f32_e32 v67, 1.0, v71
	v_exp_f32_e32 v69, v69
	v_mul_f32_e32 v71, 0xbfb8aa3b, v117
	v_exp_f32_e32 v71, v71
	v_rcp_f32_e32 v79, v67
	v_add_f32_e32 v67, 1.0, v69
	v_mul_f32_e32 v69, 0xbfb8aa3b, v114
	v_rcp_f32_e32 v124, v67
	v_add_f32_e32 v67, 1.0, v71
	v_exp_f32_e32 v69, v69
	v_mul_f32_e32 v71, 0xbfb8aa3b, v115
	v_exp_f32_e32 v71, v71
	v_rcp_f32_e32 v125, v67
	v_add_f32_e32 v67, 1.0, v69
	v_rcp_f32_e32 v126, v67
	v_add_f32_e32 v67, 1.0, v71
	v_rcp_f32_e32 v127, v67
	v_pk_mul_f32 v[148:149], v[102:103], v[76:77]
	v_pk_mul_f32 v[150:151], v[108:109], v[74:75]
	v_pk_mul_f32 v[154:155], v[106:107], v[78:79]
	ds_read_b128 v[98:101], v195 offset:128
	ds_read_b128 v[102:105], v195 offset:384
	ds_read_b128 v[106:109], v195 offset:640
	ds_read_b128 v[110:113], v195 offset:896
	v_pk_mul_f32 v[90:91], v[44:45], v[88:89] op_sel_hi:[1,0]
	v_pk_mul_f32 v[78:79], v[32:33], v[82:83] op_sel_hi:[1,0]
	v_pk_mul_f32 v[94:95], v[36:37], v[84:85] op_sel_hi:[1,0]
	v_pk_mul_f32 v[74:75], v[40:41], v[86:87] op_sel_hi:[1,0]
	v_mov_b32_dpp v32, v78 row_shr:1 row_mask:0xf bank_mask:0xf bound_ctrl:1
	v_mov_b32_dpp v33, v79 row_shr:1 row_mask:0xf bank_mask:0xf bound_ctrl:1
	s_waitcnt lgkmcnt(0)
	v_pk_fma_f32 v[44:45], v[90:91], v[106:107], v[110:111]
	v_pk_mul_f32 v[80:81], v[34:35], v[82:83] op_sel_hi:[1,0]
	v_mov_b32_dpp v34, v94 row_shr:1 row_mask:0xf bank_mask:0xf bound_ctrl:1
	v_mov_b32_dpp v35, v95 row_shr:1 row_mask:0xf bank_mask:0xf bound_ctrl:1
	v_pk_fma_f32 v[44:45], v[102:103], v[32:33], v[44:45]
	v_pk_mul_f32 v[92:93], v[46:47], v[88:89] op_sel_hi:[1,0]
	v_pk_fma_f32 v[34:35], v[98:99], v[34:35], v[44:45]
	v_pk_fma_f32 v[44:45], v[74:75], v[106:107], v[110:111]
	v_pk_mul_f32 v[96:97], v[38:39], v[84:85] op_sel_hi:[1,0]
	v_mov_b32_dpp v36, v80 row_shr:1 row_mask:0xf bank_mask:0xf bound_ctrl:1
	v_mov_b32_dpp v37, v81 row_shr:1 row_mask:0xf bank_mask:0xf bound_ctrl:1
	v_pk_fma_f32 v[46:47], v[92:93], v[108:109], v[112:113]
	v_pk_fma_f32 v[44:45], v[90:91], v[102:103], v[44:45]
	v_pk_mul_f32 v[76:77], v[42:43], v[86:87] op_sel_hi:[1,0]
	v_mov_b32_dpp v38, v96 row_shr:1 row_mask:0xf bank_mask:0xf bound_ctrl:1
	v_mov_b32_dpp v39, v97 row_shr:1 row_mask:0xf bank_mask:0xf bound_ctrl:1
	v_pk_fma_f32 v[46:47], v[104:105], v[36:37], v[46:47]
	v_pk_fma_f32 v[32:33], v[98:99], v[32:33], v[44:45]
	v_pk_fma_f32 v[44:45], v[94:95], v[106:107], v[110:111]
	v_pk_fma_f32 v[38:39], v[100:101], v[38:39], v[46:47]
	v_pk_fma_f32 v[46:47], v[76:77], v[108:109], v[112:113]
	v_pk_fma_f32 v[44:45], v[74:75], v[102:103], v[44:45]
	v_pk_fma_f32 v[46:47], v[92:93], v[104:105], v[46:47]
	v_pk_fma_f32 v[44:45], v[90:91], v[98:99], v[44:45]
	v_pk_mul_f32 v[42:43], v[114:115], v[126:127]
	v_pk_fma_f32 v[36:37], v[100:101], v[36:37], v[46:47]
	v_pk_fma_f32 v[46:47], v[96:97], v[108:109], v[112:113]
	v_pk_mul_f32 v[114:115], v[44:45], v[150:151]
	v_pk_fma_f32 v[44:45], v[78:79], v[106:107], v[110:111]
	v_pk_fma_f32 v[106:107], v[80:81], v[108:109], v[112:113]
	v_pk_fma_f32 v[46:47], v[76:77], v[104:105], v[46:47]
	v_pk_fma_f32 v[104:105], v[96:97], v[104:105], v[106:107]
	v_pk_fma_f32 v[44:45], v[94:95], v[102:103], v[44:45]
	v_pk_mul_f32 v[40:41], v[116:117], v[124:125]
	v_pk_fma_f32 v[46:47], v[92:93], v[100:101], v[46:47]
	v_pk_fma_f32 v[44:45], v[74:75], v[98:99], v[44:45]
	v_pk_fma_f32 v[98:99], v[76:77], v[100:101], v[104:105]
	v_pk_mul_f32 v[38:39], v[120:121], v[38:39]
	v_pk_mul_f32 v[34:35], v[118:119], v[34:35]
	v_pk_mul_f32 v[36:37], v[148:149], v[36:37]
	v_pk_mul_f32 v[32:33], v[122:123], v[32:33]
	v_pk_mul_f32 v[46:47], v[46:47], v[154:155]
	v_pk_mul_f32 v[42:43], v[98:99], v[42:43]
	v_pk_mul_f32 v[98:99], v[44:45], v[40:41]
	v_cvt_pk_bf16_f32 v44, v34, v35
	v_cvt_pk_bf16_f32 v45, v38, v39
	v_cvt_pk_bf16_f32 v40, v32, v33
	v_cvt_pk_bf16_f32 v41, v36, v37
	v_cvt_pk_bf16_f32 v36, v114, v115
	v_cvt_pk_bf16_f32 v37, v46, v47
	s_nop 0
	v_cvt_pk_bf16_f32 v32, v98, v99
	v_cvt_pk_bf16_f32 v33, v42, v43
	ds_read_b128 v[102:105], v195 offset:16
	ds_read_b128 v[106:109], v195 offset:272
	ds_read_b128 v[110:113], v195 offset:528
	ds_read_b128 v[114:117], v195 offset:784
	v_pk_mul_f32 v[98:99], v[16:17], v[88:89] op_sel_hi:[1,0]
	v_pk_mul_f32 v[16:17], v[20:21], v[86:87] op_sel_hi:[1,0]
	v_pk_mul_f32 v[20:21], v[28:29], v[82:83] op_sel_hi:[1,0]
	v_pk_mul_f32 v[24:25], v[24:25], v[84:85] op_sel_hi:[1,0]
	s_waitcnt lgkmcnt(0)
; #define PG8_LAS __attribute__((address_space(3)))
;     __device__ __forceinline__ void operator()(f32x4 (&acc)[2][2][4][2], const pg8::Unit& u, int wr, int wc, int fr, int fq) const {
;     ...
;             for (int n = 0; n < 2; ++n) {
;                 f32x4 g[4];
;                 {   const PG8_LAS unsigned char* wq = wl + (8 * fq + 4 * n) * 4;
;                     const f32x4 w0 = *(const PG8_LAS f32x4*)(wq), w1 = *(const PG8_LAS f32x4*)(wq + 256), w2 = *(const PG8_LAS f32x4*)(wq + 512), bb = *(const PG8_LAS f32x4*)(wq + 768);
;                     const f32x4 x0 = acc[ai][0][0][n] * rstd[0], x1 = acc[ai][0][1][n] * rstd[1], x2 = acc[ai][0][2][n] * rstd[2], x3 = acc[ai][0][3][n] * rstd[3];
;                     acc[ai][0][0][n] = x0; acc[ai][0][1][n] = x1; acc[ai][0][2][n] = x2; acc[ai][0][3][n] = x3;
;                     f32x4 p1, p2;
; #pragma unroll
;                     for (int c = 0; c < 4; ++c) { p1[c] = row_up1(x3[c]); p2[c] = row_up1(x2[c]); }
;                     g[0] = bb + w2 * x0 + w1 * p1 + w0 * p2; g[1] = bb + w2 * x1 + w1 * x0 + w0 * p1;
;                     g[2] = bb + w2 * x2 + w1 * x1 + w0 * x0; g[3] = bb + w2 * x3 + w1 * x2 + w0 * x1;
; #pragma unroll
;                     for (int m = 0; m < 4; ++m)
; #pragma unroll
;                         for (int c = 0; c < 4; ++c) g[m][c] = siluf_(g[m][c]);
;                 }
;                 __builtin_amdgcn_sched_barrier(0);
;                 {   const PG8_LAS unsigned char* wq = wl + 128 + (8 * fq + 4 * n) * 4;
;                     const f32x4 w0 = *(const PG8_LAS f32x4*)(wq), w1 = *(const PG8_LAS f32x4*)(wq + 256), w2 = *(const PG8_LAS f32x4*)(wq + 512), bb = *(const PG8_LAS f32x4*)(wq + 768);
;                     const f32x4 x0 = acc[ai][1][0][n] * rstd[0], x1 = acc[ai][1][1][n] * rstd[1], x2 = acc[ai][1][2][n] * rstd[2], x3 = acc[ai][1][3][n] * rstd[3];
;                     acc[ai][1][0][n] = x0; acc[ai][1][1][n] = x1; acc[ai][1][2][n] = x2; acc[ai][1][3][n] = x3;
;                     f32x4 p1, p2;
; #pragma unroll
;                     for (int c = 0; c < 4; ++c) { p1[c] = row_up1(x3[c]); p2[c] = row_up1(x2[c]); }
;                     g[0] *= bb + w2 * x0 + w1 * p1 + w0 * p2; g[1] *= bb + w2 * x1 + w1 * x0 + w0 * p1;
;                     g[2] *= bb + w2 * x2 + w1 * x1 + w0 * x0; g[3] *= bb + w2 * x3 + w1 * x2 + w0 * x1;
;                 }
; #pragma unroll
	v_pk_fma_f32 v[46:47], v[98:99], v[110:111], v[114:115]
	v_mov_b32_dpp v28, v20 row_shr:1 row_mask:0xf bank_mask:0xf bound_ctrl:1
	v_mov_b32_dpp v29, v21 row_shr:1 row_mask:0xf bank_mask:0xf bound_ctrl:1
	v_pk_mul_f32 v[100:101], v[18:19], v[88:89] op_sel_hi:[1,0]
	v_pk_mul_f32 v[18:19], v[22:23], v[86:87] op_sel_hi:[1,0]
	v_pk_mul_f32 v[22:23], v[30:31], v[82:83] op_sel_hi:[1,0]
	v_mov_b32_dpp v30, v24 row_shr:1 row_mask:0xf bank_mask:0xf bound_ctrl:1
	v_mov_b32_dpp v31, v25 row_shr:1 row_mask:0xf bank_mask:0xf bound_ctrl:1
	v_pk_fma_f32 v[46:47], v[106:107], v[28:29], v[46:47]
	v_pk_mul_f32 v[26:27], v[26:27], v[84:85] op_sel_hi:[1,0]
	v_pk_fma_f32 v[30:31], v[102:103], v[30:31], v[46:47]
	v_pk_fma_f32 v[46:47], v[16:17], v[110:111], v[114:115]
	v_mul_f32_e32 v67, 0xbfb8aa3b, v30
	v_exp_f32_e32 v67, v67
	v_mul_f32_e32 v69, 0xbfb8aa3b, v31
	v_exp_f32_e32 v69, v69
	v_mov_b32_dpp v34, v22 row_shr:1 row_mask:0xf bank_mask:0xf bound_ctrl:1
	v_mov_b32_dpp v35, v23 row_shr:1 row_mask:0xf bank_mask:0xf bound_ctrl:1
	v_pk_fma_f32 v[42:43], v[100:101], v[112:113], v[116:117]
	v_pk_fma_f32 v[46:47], v[98:99], v[106:107], v[46:47]
	v_mov_b32_dpp v38, v26 row_shr:1 row_mask:0xf bank_mask:0xf bound_ctrl:1
	v_mov_b32_dpp v39, v27 row_shr:1 row_mask:0xf bank_mask:0xf bound_ctrl:1
	v_pk_fma_f32 v[42:43], v[108:109], v[34:35], v[42:43]
	v_pk_fma_f32 v[28:29], v[102:103], v[28:29], v[46:47]
	v_pk_fma_f32 v[46:47], v[24:25], v[110:111], v[114:115]
	v_pk_fma_f32 v[110:111], v[20:21], v[110:111], v[114:115]
	v_pk_fma_f32 v[38:39], v[104:105], v[38:39], v[42:43]
	v_pk_fma_f32 v[46:47], v[16:17], v[106:107], v[46:47]
	v_pk_fma_f32 v[106:107], v[24:25], v[106:107], v[110:111]
	v_add_f32_e32 v67, 1.0, v67
	v_pk_fma_f32 v[46:47], v[98:99], v[102:103], v[46:47]
	v_pk_fma_f32 v[120:121], v[16:17], v[102:103], v[106:107]
	v_rcp_f32_e32 v102, v67
	v_add_f32_e32 v67, 1.0, v69
	v_mul_f32_e32 v69, 0xbfb8aa3b, v38
	v_exp_f32_e32 v69, v69
	v_mul_f32_e32 v71, 0xbfb8aa3b, v39
	v_pk_fma_f32 v[42:43], v[18:19], v[112:113], v[116:117]
	v_exp_f32_e32 v71, v71
	v_pk_fma_f32 v[42:43], v[100:101], v[108:109], v[42:43]
	v_rcp_f32_e32 v103, v67
	v_pk_fma_f32 v[34:35], v[104:105], v[34:35], v[42:43]
	v_pk_fma_f32 v[42:43], v[26:27], v[112:113], v[116:117]
	v_pk_fma_f32 v[112:113], v[22:23], v[112:113], v[116:117]
	v_pk_fma_f32 v[42:43], v[18:19], v[108:109], v[42:43]
	v_pk_fma_f32 v[108:109], v[26:27], v[108:109], v[112:113]
	v_add_f32_e32 v67, 1.0, v69
	v_pk_fma_f32 v[42:43], v[100:101], v[104:105], v[42:43]
	v_pk_fma_f32 v[118:119], v[18:19], v[104:105], v[108:109]
	v_rcp_f32_e32 v104, v67
	v_add_f32_e32 v67, 1.0, v71
	v_rcp_f32_e32 v105, v67
	v_mul_f32_e32 v67, 0xbfb8aa3b, v34
	v_exp_f32_e32 v67, v67
	v_mul_f32_e32 v69, 0xbfb8aa3b, v35
	v_pk_mul_f32 v[122:123], v[30:31], v[102:103]
	v_mul_f32_e32 v30, 0xbfb8aa3b, v28
	v_mul_f32_e32 v31, 0xbfb8aa3b, v29
	v_exp_f32_e32 v69, v69
	v_exp_f32_e32 v30, v30
	v_exp_f32_e32 v31, v31
	v_add_f32_e32 v67, 1.0, v67
	v_rcp_f32_e32 v102, v67
	v_add_f32_e32 v67, 1.0, v69
	v_add_f32_e32 v30, 1.0, v30
	v_add_f32_e32 v31, 1.0, v31
	v_rcp_f32_e32 v103, v67
	v_mul_f32_e32 v67, 0xbfb8aa3b, v46
	v_rcp_f32_e32 v30, v30
	v_rcp_f32_e32 v31, v31
	v_exp_f32_e32 v67, v67
	v_mul_f32_e32 v69, 0xbfb8aa3b, v47
	v_exp_f32_e32 v69, v69
	v_pk_mul_f32 v[124:125], v[28:29], v[30:31]
	v_add_f32_e32 v28, 1.0, v67
	v_mul_f32_e32 v67, 0xbfb8aa3b, v120
	v_add_f32_e32 v29, 1.0, v69
	v_exp_f32_e32 v67, v67
	v_mul_f32_e32 v69, 0xbfb8aa3b, v121
	v_mul_f32_e32 v30, 0xbfb8aa3b, v42
	v_mul_f32_e32 v31, 0xbfb8aa3b, v43
	v_exp_f32_e32 v69, v69
	v_exp_f32_e32 v30, v30
	v_exp_f32_e32 v31, v31
	v_add_f32_e32 v67, 1.0, v67
	v_rcp_f32_e32 v126, v67
	v_add_f32_e32 v67, 1.0, v69
	v_mul_f32_e32 v69, 0xbfb8aa3b, v118
	v_add_f32_e32 v30, 1.0, v30
	v_add_f32_e32 v31, 1.0, v31
	v_exp_f32_e32 v69, v69
	v_mul_f32_e32 v71, 0xbfb8aa3b, v119
	v_rcp_f32_e32 v28, v28
	v_rcp_f32_e32 v29, v29
	v_rcp_f32_e32 v30, v30
	v_rcp_f32_e32 v31, v31
	v_exp_f32_e32 v71, v71
	v_rcp_f32_e32 v127, v67
	v_add_f32_e32 v67, 1.0, v69
	v_pk_mul_f32 v[38:39], v[38:39], v[104:105]
	v_rcp_f32_e32 v148, v67
	v_add_f32_e32 v67, 1.0, v71
	v_pk_mul_f32 v[34:35], v[34:35], v[102:103]
	v_pk_mul_f32 v[46:47], v[46:47], v[28:29]
	v_pk_mul_f32 v[42:43], v[42:43], v[30:31]
	v_rcp_f32_e32 v149, v67
	ds_read_b128 v[102:105], v195 offset:144
	ds_read_b128 v[106:109], v195 offset:400
	ds_read_b128 v[110:113], v195 offset:656
	ds_read_b128 v[114:117], v195 offset:912
	v_pk_mul_f32 v[30:31], v[2:3], v[88:89] op_sel_hi:[1,0]
	v_pk_mul_f32 v[28:29], v[0:1], v[88:89] op_sel_hi:[1,0]
	v_pk_mul_f32 v[2:3], v[6:7], v[86:87] op_sel_hi:[1,0]
	v_pk_mul_f32 v[0:1], v[4:5], v[86:87] op_sel_hi:[1,0]
	v_pk_mul_f32 v[6:7], v[14:15], v[82:83] op_sel_hi:[1,0]
	v_pk_mul_f32 v[4:5], v[12:13], v[82:83] op_sel_hi:[1,0]
	v_pk_mul_f32 v[10:11], v[10:11], v[84:85] op_sel_hi:[1,0]
	v_pk_mul_f32 v[8:9], v[8:9], v[84:85] op_sel_hi:[1,0]
	v_mov_b32_dpp v12, v4 row_shr:1 row_mask:0xf bank_mask:0xf bound_ctrl:1
	v_mov_b32_dpp v13, v5 row_shr:1 row_mask:0xf bank_mask:0xf bound_ctrl:1
	v_mov_b32_dpp v82, v6 row_shr:1 row_mask:0xf bank_mask:0xf bound_ctrl:1
	v_mov_b32_dpp v83, v7 row_shr:1 row_mask:0xf bank_mask:0xf bound_ctrl:1
	v_pk_mul_f32 v[86:87], v[120:121], v[126:127]
	v_pk_mul_f32 v[88:89], v[118:119], v[148:149]
	s_waitcnt lgkmcnt(0)
; __device__ __forceinline__ unsigned pk2(float a, float b) { return pg8::cvt_pk_bf16(a, b); }
;     __device__ __forceinline__ void operator()(f32x4 (&acc)[2][2][4][2], const pg8::Unit& u, int wr, int wc, int fr, int fq) const {
;     ...
;                     g[0] *= bb + w2 * x0 + w1 * p1 + w0 * p2; g[1] *= bb + w2 * x1 + w1 * x0 + w0 * p1;
;                     g[2] *= bb + w2 * x2 + w1 * x1 + w0 * x0; g[3] *= bb + w2 * x3 + w1 * x2 + w0 * x1;
;                 }
; #pragma unroll
;                 for (int m = 0; m < 4; ++m) { pk[n][m].x = pk2(g[m][0], g[m][1]); pk[n][m].y = pk2(g[m][2], g[m][3]); }
;                 __builtin_amdgcn_sched_barrier(0);
;             }
; #pragma unroll
;             for (int m = 0; m < 4; ++m) if (fr != 0 || m >= 2) {
;                 u32x4 w; w.x = pk[0][m].x; w.y = pk[0][m].y; w.z = pk[1][m].x; w.w = pk[1][m].y;
;                 *(u32x4*)(ACT + (size_t)(tb + m) * DFF + colj) = w; }
	v_pk_fma_f32 v[118:119], v[28:29], v[110:111], v[114:115]
	v_pk_fma_f32 v[120:121], v[30:31], v[112:113], v[116:117]
	v_mov_b32_dpp v14, v8 row_shr:1 row_mask:0xf bank_mask:0xf bound_ctrl:1
	v_mov_b32_dpp v15, v9 row_shr:1 row_mask:0xf bank_mask:0xf bound_ctrl:1
	v_mov_b32_dpp v84, v10 row_shr:1 row_mask:0xf bank_mask:0xf bound_ctrl:1
	v_mov_b32_dpp v85, v11 row_shr:1 row_mask:0xf bank_mask:0xf bound_ctrl:1
	v_pk_fma_f32 v[120:121], v[108:109], v[82:83], v[120:121]
	v_pk_fma_f32 v[118:119], v[106:107], v[12:13], v[118:119]
	v_pk_fma_f32 v[84:85], v[104:105], v[84:85], v[120:121]
	v_pk_fma_f32 v[14:15], v[102:103], v[14:15], v[118:119]
	v_pk_fma_f32 v[118:119], v[2:3], v[112:113], v[116:117]
	v_pk_mul_f32 v[38:39], v[38:39], v[84:85]
	v_pk_fma_f32 v[84:85], v[0:1], v[110:111], v[114:115]
	v_pk_fma_f32 v[118:119], v[30:31], v[108:109], v[118:119]
	v_pk_fma_f32 v[84:85], v[28:29], v[106:107], v[84:85]
	v_pk_fma_f32 v[82:83], v[104:105], v[82:83], v[118:119]
	v_pk_fma_f32 v[12:13], v[102:103], v[12:13], v[84:85]
	v_pk_mul_f32 v[34:35], v[34:35], v[82:83]
	v_pk_fma_f32 v[82:83], v[8:9], v[110:111], v[114:115]
	v_pk_fma_f32 v[84:85], v[10:11], v[112:113], v[116:117]
	v_pk_fma_f32 v[82:83], v[0:1], v[106:107], v[82:83]
	v_pk_fma_f32 v[84:85], v[2:3], v[108:109], v[84:85]
	v_pk_fma_f32 v[82:83], v[28:29], v[102:103], v[82:83]
	v_pk_fma_f32 v[84:85], v[30:31], v[104:105], v[84:85]
	v_pk_mul_f32 v[82:83], v[46:47], v[82:83]
	v_pk_mul_f32 v[84:85], v[42:43], v[84:85]
	v_pk_fma_f32 v[42:43], v[4:5], v[110:111], v[114:115]
	v_pk_fma_f32 v[46:47], v[6:7], v[112:113], v[116:117]
	v_pk_fma_f32 v[42:43], v[8:9], v[106:107], v[42:43]
	v_pk_fma_f32 v[46:47], v[10:11], v[108:109], v[46:47]
	v_pk_fma_f32 v[42:43], v[0:1], v[102:103], v[42:43]
	v_pk_fma_f32 v[46:47], v[2:3], v[104:105], v[46:47]
	v_pk_mul_f32 v[14:15], v[122:123], v[14:15]
	v_pk_mul_f32 v[12:13], v[124:125], v[12:13]
	v_pk_mul_f32 v[88:89], v[88:89], v[46:47]
	v_pk_mul_f32 v[86:87], v[86:87], v[42:43]
	v_cvt_pk_bf16_f32 v46, v14, v15
	v_cvt_pk_bf16_f32 v47, v38, v39
	v_cvt_pk_bf16_f32 v42, v12, v13
	v_cvt_pk_bf16_f32 v43, v34, v35
	v_cvt_pk_bf16_f32 v38, v82, v83
	v_cvt_pk_bf16_f32 v39, v84, v85
	s_nop 0
	v_cvt_pk_bf16_f32 v34, v86, v87
	v_cvt_pk_bf16_f32 v35, v88, v89
	s_and_saveexec_b64 s[8:9], s[0:1]
	s_cbranch_execz .LBB0_756
	v_mov_b64_e32 v[12:13], s[22:23]
	v_mad_i64_i32 v[14:15], s[10:11], v66, s56, v[12:13]
	v_mad_i64_i32 v[12:13], s[10:11], v68, s56, v[12:13]
	v_lshl_add_u64 v[14:15], v[14:15], 0, v[64:65]
	v_lshl_add_u64 v[12:13], v[12:13], 0, v[64:65]
	global_store_dwordx4 v[14:15], v[44:47], off nt
	global_store_dwordx4 v[12:13], v[40:43], off nt
.LBB0_756:
	s_or_b64 exec, exec, s[8:9]
	v_mov_b64_e32 v[12:13], s[22:23]
	v_mad_i64_i32 v[14:15], s[8:9], v70, s56, v[12:13]
	v_mad_i64_i32 v[12:13], s[8:9], v72, s56, v[12:13]
	v_lshl_add_u64 v[14:15], v[14:15], 0, v[64:65]
	v_lshl_add_u64 v[12:13], v[12:13], 0, v[64:65]
	v_cmp_gt_i32_e32 vcc, 15, v169
	s_mov_b64 s[10:11], -1
	global_store_dwordx4 v[14:15], v[36:39], off nt
	global_store_dwordx4 v[12:13], v[32:35], off nt
	s_and_saveexec_b64 s[8:9], vcc
	s_cbranch_execz .LBB0_759
	v_cmp_eq_u32_e32 vcc, 0, v169
	s_orn2_b64 s[10:11], vcc, exec
	s_or_b64 exec, exec, s[8:9]
	s_and_saveexec_b64 s[8:9], s[10:11]
	s_cbranch_execnz .LBB0_760

; __device__ __forceinline__ unsigned pk2(float a, float b) { return pg8::cvt_pk_bf16(a, b); }
;     __device__ __forceinline__ void operator()(f32x4 (&acc)[2][2][4][2], const pg8::Unit& u, int wr, int wc, int fr, int fq) const {
;     ...
;             const int seg = u.pm * 4 + ai * 2 + wr;
;             if (fr == 0 || fr == 15) {
; #pragma unroll
;                 for (int mm = 0; mm < 2; ++mm) { const int m = (fr == 0) ? mm : 2 + mm;
; #pragma unroll
;                     for (int bj = 0; bj < 2; ++bj) { const f32x4 v0 = (fr == 0) ? acc[ai][bj][mm][0] : acc[ai][bj][2 + mm][0], v1 = (fr == 0) ? acc[ai][bj][mm][1] : acc[ai][bj][2 + mm][1];
;                         u32x4 w; w.x = pk2(v0[0], v0[1]); w.y = pk2(v0[2], v0[3]); w.z = pk2(v1[0], v1[1]); w.w = pk2(v1[2], v1[3]);
;                         *(u32x4*)(HALO + ((size_t)(seg * 4 + m) * 2 + bj) * DFF + colj) = w; } }
.LBB0_760:
	s_lshl_b32 s10, s34, 4
	s_add_i32 s12, s58, s10
	v_cndmask_b32_e64 v13, v54, v62, s[6:7]
	v_cndmask_b32_e64 v14, v55, v63, s[6:7]
	v_cndmask_b32_e64 v12, v52, v60, s[6:7]
	v_cndmask_b32_e64 v24, v24, v98, s[6:7]
	v_cndmask_b32_e64 v25, v25, v99, s[6:7]
	v_or_b32_e32 v32, s12, v188
	v_cndmask_b32_e64 v15, v53, v61, s[6:7]
	v_cndmask_b32_e64 v26, v26, v100, s[6:7]
	v_cndmask_b32_e64 v27, v27, v101, s[6:7]
	v_cvt_pk_bf16_f32 v12, v12, v15
	v_cvt_pk_bf16_f32 v13, v13, v14
	v_cvt_pk_bf16_f32 v14, v24, v25
	v_mov_b64_e32 v[24:25], s[28:29]
	v_cvt_pk_bf16_f32 v15, v26, v27
	v_mad_i64_i32 v[26:27], s[10:11], v32, s64, v[24:25]
	v_lshl_add_u64 v[26:27], v[26:27], 0, v[64:65]
	global_store_dwordx4 v[26:27], v[12:15], off nt
	v_cndmask_b32_e64 v30, v10, v30, s[6:7]
	v_cndmask_b32_e64 v11, v11, v31, s[6:7]
	v_cndmask_b32_e64 v12, v96, v92, s[6:7]
	v_cndmask_b32_e64 v13, v97, v93, s[6:7]
	v_cndmask_b32_e64 v14, v94, v90, s[6:7]
	v_cndmask_b32_e64 v15, v95, v91, s[6:7]
	v_cndmask_b32_e64 v10, v8, v28, s[6:7]
	v_cndmask_b32_e64 v28, v9, v29, s[6:7]
	v_cvt_pk_bf16_f32 v8, v14, v15
	v_cvt_pk_bf16_f32 v9, v12, v13
	v_add_co_u32_e32 v12, vcc, s65, v26
	v_cvt_pk_bf16_f32 v10, v10, v28
	v_cvt_pk_bf16_f32 v11, v30, v11
	v_cndmask_b32_e64 v14, v23, v19, s[6:7]
	s_nop 0
	v_addc_co_u32_e32 v13, vcc, 0, v27, vcc
	global_store_dwordx4 v[12:13], v[8:11], off offset:1536 nt
	v_or_b32_e32 v12, s12, v189
	v_cndmask_b32_e64 v13, v22, v18, s[6:7]
	v_cndmask_b32_e64 v9, v50, v58, s[6:7]
	v_cndmask_b32_e64 v10, v51, v59, s[6:7]
	v_cndmask_b32_e64 v8, v48, v56, s[6:7]
	v_cndmask_b32_e64 v11, v49, v57, s[6:7]
	v_cndmask_b32_e64 v15, v20, v16, s[6:7]
	v_cndmask_b32_e64 v16, v21, v17, s[6:7]
	v_cvt_pk_bf16_f32 v8, v8, v11
	v_cvt_pk_bf16_f32 v9, v9, v10
	v_cvt_pk_bf16_f32 v10, v15, v16
	v_cvt_pk_bf16_f32 v11, v13, v14
	v_mad_i64_i32 v[12:13], s[10:11], v12, s64, v[24:25]
	v_lshl_add_u64 v[12:13], v[12:13], 0, v[64:65]
	v_cndmask_b32_e64 v6, v6, v2, s[6:7]
	v_cndmask_b32_e64 v2, v4, v0, s[6:7]
	v_cndmask_b32_e64 v4, v5, v1, s[6:7]
	global_store_dwordx4 v[12:13], v[8:11], off nt
	v_cndmask_b32_e64 v3, v7, v3, s[6:7]
	s_nop 0
	v_cndmask_b32_e64 v8, v80, v76, s[6:7]
	v_cndmask_b32_e64 v9, v81, v77, s[6:7]
	v_cndmask_b32_e64 v10, v78, v74, s[6:7]
	v_cndmask_b32_e64 v11, v79, v75, s[6:7]
	v_cvt_pk_bf16_f32 v0, v10, v11
	v_cvt_pk_bf16_f32 v1, v8, v9
	v_cvt_pk_bf16_f32 v2, v2, v4
	v_add_co_u32_e32 v4, vcc, 0x1000, v12
	v_cvt_pk_bf16_f32 v3, v6, v3
	s_nop 1
	v_addc_co_u32_e32 v5, vcc, 0, v13, vcc
	global_store_dwordx4 v[4:5], v[0:3], off offset:1536 nt
	s_or_b64 exec, exec, s[8:9]
	s_andn2_b64 vcc, exec, s[4:5]
	s_mov_b64 s[4:5], -1
	s_cbranch_vccnz .LBB0_741

; __device__ __forceinline__ unsigned pk2(float a, float b) { return pg8::cvt_pk_bf16(a, b); }
; __device__ __forceinline__ void unpack8(const u32x4 w, float (&f)[8]) { f[0] = bf_lo(w.x); f[1] = bf_hi(w.x); f[2] = bf_lo(w.y); f[3] = bf_hi(w.y); f[4] = bf_lo(w.z); f[5] = bf_hi(w.z); f[6] = bf_lo(w.w); f[7] = bf_hi(w.w); }
;     __device__ __forceinline__ void operator()(f32x4 (&acc)[2][2][4][2], const pg8::Unit& u, int wr, int wc, int fr, int fq) const {
;         const int row0 = u.pm * 256 + wr * 64 + fr, col0 = u.pn * 256 + wc * 32 + 8 * fq;
; #pragma unroll
;         for (int ai = 0; ai < 2; ++ai) {
;             u32x4 rx[4][2];
; #pragma unroll
;             for (int m = 0; m < 4; ++m)
; #pragma unroll
;                 for (int bj = 0; bj < 2; ++bj) rx[m][bj] = *(const u32x4*)(XB + (size_t)(row0 + ai * 128 + m * 16) * 1024 + col0 + bj * 128);
; #pragma unroll
;             for (int m = 0; m < 4; ++m) { const int row = row0 + ai * 128 + m * 16; float s = 0.f;
; #pragma unroll
;                 for (int bj = 0; bj < 2; ++bj) { float f[8]; unpack8(rx[m][bj], f);
;                     const f32x4 v0 = acc[ai][bj][m][0] + (f32x4){f[0], f[1], f[2], f[3]}, v1 = acc[ai][bj][m][1] + (f32x4){f[4], f[5], f[6], f[7]};
;                     s += (v0[0] * v0[0] + v0[1] * v0[1]) + (v0[2] * v0[2] + v0[3] * v0[3]) + (v1[0] * v1[0] + v1[1] * v1[1]) + (v1[2] * v1[2] + v1[3] * v1[3]);
;                     u32x4 w; w.x = pk2(v0[0], v0[1]); w.y = pk2(v0[2], v0[3]); w.z = pk2(v1[0], v1[1]); w.w = pk2(v1[2], v1[3]);
;                     *(u32x4*)(YB + (size_t)row * 1024 + col0 + bj * 128) = w; }
;                 s += __shfl_xor(s, 16); s += __shfl_xor(s, 32); if (fq == 0) SS[(size_t)row * 16 + u.pn * 4 + wc] = s; }
;         }
.LBB0_916:
	v_lshl_or_b32 v170, s8, 8, v190
	v_lshl_add_u32 v174, s51, 8, v188
	v_ashrrev_i32_e32 v171, 31, v170
	v_lshlrev_b64 v[204:205], 1, v[170:171]
	v_ashrrev_i32_e32 v175, 31, v174
	v_lshl_add_u64 v[172:173], s[2:3], 0, v[204:205]
	v_lshlrev_b64 v[206:207], 11, v[174:175]
	v_lshl_add_u64 v[128:129], v[172:173], 0, v[206:207]
	global_load_dwordx4 v[196:199], v[128:129], off
	global_load_dwordx4 v[200:203], v[128:129], off offset:256
	v_or_b32_e32 v184, 16, v174
	v_or_b32_e32 v180, 32, v174
	v_or_b32_e32 v176, 48, v174
	v_ashrrev_i32_e32 v185, 31, v184
	v_ashrrev_i32_e32 v181, 31, v180
	v_ashrrev_i32_e32 v177, 31, v176
	v_lshlrev_b64 v[186:187], 11, v[184:185]
	v_lshlrev_b64 v[182:183], 11, v[180:181]
	v_lshlrev_b64 v[178:179], 11, v[176:177]
	v_lshl_add_u64 v[128:129], v[172:173], 0, v[186:187]
	v_lshl_add_u64 v[130:131], v[172:173], 0, v[182:183]
	v_lshl_add_u64 v[208:209], v[172:173], 0, v[178:179]
	global_load_dwordx4 v[148:151], v[128:129], off
	global_load_dwordx4 v[144:147], v[128:129], off offset:256
	global_load_dwordx4 v[140:143], v[130:131], off
	global_load_dwordx4 v[136:139], v[130:131], off offset:256
	global_load_dwordx4 v[132:135], v[208:209], off
	s_nop 0
	global_load_dwordx4 v[128:131], v[208:209], off offset:256
	v_and_b32_e32 v208, 64, v194
	v_xor_b32_e32 v195, 16, v194
	v_add_u32_e32 v208, 64, v208
	v_xor_b32_e32 v209, 32, v194
	v_cmp_lt_i32_e32 vcc, v195, v208
	v_lshl_add_u64 v[206:207], s[12:13], 0, v[206:207]
	v_lshl_add_u64 v[204:205], v[206:207], 0, v[204:205]
	v_cndmask_b32_e32 v195, v194, v195, vcc
	v_cmp_lt_i32_e32 vcc, v209, v208
	v_lshlrev_b32_e32 v195, 2, v195
	s_lshl_b32 s28, s8, 2
	v_cndmask_b32_e32 v214, v194, v209, vcc
	s_ashr_i32 s29, s28, 31
	s_waitcnt vmcnt(0)
	v_lshlrev_b32_e32 v206, 16, v196
	v_and_b32_e32 v207, 0xffff0000, v196
	v_lshlrev_b32_e32 v196, 16, v197
	v_and_b32_e32 v197, 0xffff0000, v197
	v_lshlrev_b32_e32 v210, 16, v200
	v_and_b32_e32 v211, 0xffff0000, v200
	v_lshlrev_b32_e32 v200, 16, v201
	v_and_b32_e32 v201, 0xffff0000, v201
	v_lshlrev_b32_e32 v208, 16, v198
	v_and_b32_e32 v209, 0xffff0000, v198
	v_lshlrev_b32_e32 v198, 16, v199
	v_and_b32_e32 v199, 0xffff0000, v199
	v_lshlrev_b32_e32 v212, 16, v202
	v_and_b32_e32 v213, 0xffff0000, v202
	v_lshlrev_b32_e32 v202, 16, v203
	v_and_b32_e32 v203, 0xffff0000, v203
	v_pk_add_f32 v[126:127], v[126:127], v[196:197]
	v_pk_add_f32 v[124:125], v[124:125], v[206:207]
	v_pk_add_f32 v[118:119], v[118:119], v[200:201]
	v_pk_add_f32 v[116:117], v[116:117], v[210:211]
	v_pk_add_f32 v[122:123], v[122:123], v[198:199]
	v_pk_add_f32 v[120:121], v[120:121], v[208:209]
	v_pk_add_f32 v[196:197], v[114:115], v[202:203]
	v_pk_add_f32 v[198:199], v[112:113], v[212:213]
	v_mul_f32_e32 v114, v125, v125
	v_mul_f32_e32 v115, v127, v127
	v_cvt_pk_bf16_f32 v112, v124, v125
	v_cvt_pk_bf16_f32 v113, v126, v127
	v_mul_f32_e32 v125, v117, v117
	v_mul_f32_e32 v127, v119, v119
	v_mul_f32_e32 v200, v121, v121
	v_mul_f32_e32 v202, v199, v199
	v_fmac_f32_e32 v114, v124, v124
	v_fmac_f32_e32 v115, v126, v126
	v_fmac_f32_e32 v125, v116, v116
	v_fmac_f32_e32 v127, v118, v118
	v_mul_f32_e32 v201, v123, v123
	v_mul_f32_e32 v203, v197, v197
	v_fmac_f32_e32 v200, v120, v120
	v_fmac_f32_e32 v202, v198, v198
	v_add_f32_e32 v114, v114, v115
	v_add_f32_e32 v115, v125, v127
	v_fmac_f32_e32 v201, v122, v122
	v_fmac_f32_e32 v203, v196, v196
	v_add_f32_e32 v114, v200, v114
	v_add_f32_e32 v115, v202, v115
	v_add_f32_e32 v114, v201, v114
	v_add_f32_e32 v115, v203, v115
	v_add_f32_e32 v124, v114, v115
	ds_bpermute_b32 v125, v195, v124
	v_cvt_pk_bf16_f32 v114, v120, v121
	v_cvt_pk_bf16_f32 v115, v122, v123
	global_store_dwordx4 v[204:205], v[112:115], off nt
	v_cvt_pk_bf16_f32 v116, v116, v117
	v_cvt_pk_bf16_f32 v117, v118, v119
	v_cvt_pk_bf16_f32 v118, v198, v199
	v_cvt_pk_bf16_f32 v119, v196, v197
	global_store_dwordx4 v[204:205], v[116:119], off offset:256 nt
	s_waitcnt lgkmcnt(0)
	v_add_f32_e32 v113, v124, v125
	v_lshlrev_b32_e32 v112, 2, v214
	ds_bpermute_b32 v114, v112, v113
	s_and_saveexec_b64 s[30:31], s[0:1]
	s_cbranch_execz .LBB0_918
	v_lshlrev_b64 v[116:117], 6, v[174:175]
	v_lshl_add_u64 v[116:117], s[20:21], 0, v[116:117]
	v_lshl_add_u64 v[116:117], s[28:29], 2, v[116:117]
	s_lshl_b32 s8, s40, 2
	v_lshl_add_u64 v[116:117], v[116:117], 0, s[8:9]
	s_waitcnt lgkmcnt(0)
	v_add_f32_e32 v113, v113, v114
	global_store_dword v[116:117], v113, off
; __device__ __forceinline__ unsigned pk2(float a, float b) { return pg8::cvt_pk_bf16(a, b); }
; __device__ __forceinline__ void unpack8(const u32x4 w, float (&f)[8]) { f[0] = bf_lo(w.x); f[1] = bf_hi(w.x); f[2] = bf_lo(w.y); f[3] = bf_hi(w.y); f[4] = bf_lo(w.z); f[5] = bf_hi(w.z); f[6] = bf_lo(w.w); f[7] = bf_hi(w.w); }
;     __device__ __forceinline__ void operator()(f32x4 (&acc)[2][2][4][2], const pg8::Unit& u, int wr, int wc, int fr, int fq) const {
;     ...
;             for (int m = 0; m < 4; ++m) { const int row = row0 + ai * 128 + m * 16; float s = 0.f;
; #pragma unroll
;                 for (int bj = 0; bj < 2; ++bj) { float f[8]; unpack8(rx[m][bj], f);
;                     const f32x4 v0 = acc[ai][bj][m][0] + (f32x4){f[0], f[1], f[2], f[3]}, v1 = acc[ai][bj][m][1] + (f32x4){f[4], f[5], f[6], f[7]};
;                     s += (v0[0] * v0[0] + v0[1] * v0[1]) + (v0[2] * v0[2] + v0[3] * v0[3]) + (v1[0] * v1[0] + v1[1] * v1[1]) + (v1[2] * v1[2] + v1[3] * v1[3]);
;                     u32x4 w; w.x = pk2(v0[0], v0[1]); w.y = pk2(v0[2], v0[3]); w.z = pk2(v1[0], v1[1]); w.w = pk2(v1[2], v1[3]);
;                     *(u32x4*)(YB + (size_t)row * 1024 + col0 + bj * 128) = w; }
;                 s += __shfl_xor(s, 16); s += __shfl_xor(s, 32); if (fq == 0) SS[(size_t)row * 16 + u.pn * 4 + wc] = s; }
.LBB0_918:
	s_or_b64 exec, exec, s[30:31]
	s_waitcnt lgkmcnt(0)
	v_lshlrev_b32_e32 v114, 16, v148
	v_and_b32_e32 v115, 0xffff0000, v148
	v_lshlrev_b32_e32 v116, 16, v149
	v_and_b32_e32 v117, 0xffff0000, v149
	v_lshlrev_b32_e32 v118, 16, v150
	v_and_b32_e32 v119, 0xffff0000, v150
	v_lshlrev_b32_e32 v120, 16, v151
	v_and_b32_e32 v121, 0xffff0000, v151
	v_pk_add_f32 v[110:111], v[110:111], v[116:117]
	v_pk_add_f32 v[108:109], v[108:109], v[114:115]
	v_pk_add_f32 v[114:115], v[106:107], v[120:121]
	v_pk_add_f32 v[106:107], v[104:105], v[118:119]
	v_mul_f32_e32 v104, v109, v109
	v_mul_f32_e32 v105, v111, v111
	v_fmac_f32_e32 v104, v108, v108
	v_fmac_f32_e32 v105, v110, v110
	v_add_f32_e32 v104, v104, v105
	v_mul_f32_e32 v105, v107, v107
	v_fmac_f32_e32 v105, v106, v106
	v_add_f32_e32 v104, v105, v104
	v_mul_f32_e32 v105, v115, v115
	v_fmac_f32_e32 v105, v114, v114
	v_add_f32_e32 v113, v105, v104
	v_cvt_pk_bf16_f32 v104, v108, v109
	v_cvt_pk_bf16_f32 v105, v110, v111
	v_lshlrev_b32_e32 v108, 16, v144
	v_and_b32_e32 v109, 0xffff0000, v144
	v_lshlrev_b32_e32 v110, 16, v145
	v_and_b32_e32 v111, 0xffff0000, v145
	v_cvt_pk_bf16_f32 v106, v106, v107
	v_cvt_pk_bf16_f32 v107, v114, v115
	v_lshlrev_b32_e32 v114, 16, v146
	v_and_b32_e32 v115, 0xffff0000, v146
	v_pk_add_f32 v[102:103], v[102:103], v[110:111]
	v_pk_add_f32 v[100:101], v[100:101], v[108:109]
	v_pk_add_f32 v[110:111], v[96:97], v[114:115]
	v_mul_f32_e32 v96, v101, v101
	v_mul_f32_e32 v97, v103, v103
	v_fmac_f32_e32 v96, v100, v100
	v_fmac_f32_e32 v97, v102, v102
	v_lshlrev_b32_e32 v116, 16, v147
	v_and_b32_e32 v117, 0xffff0000, v147
	v_add_f32_e32 v96, v96, v97
	v_mul_f32_e32 v97, v111, v111
	v_pk_add_f32 v[108:109], v[98:99], v[116:117]
	v_fmac_f32_e32 v97, v110, v110
	v_add_f32_e32 v96, v97, v96
	v_mul_f32_e32 v97, v109, v109
	v_fmac_f32_e32 v97, v108, v108
	v_add_f32_e32 v96, v97, v96
	v_add_f32_e32 v99, v113, v96
	ds_bpermute_b32 v113, v195, v99
	v_lshl_add_u64 v[96:97], s[12:13], 0, v[186:187]
	v_lshl_add_u64 v[114:115], v[170:171], 1, v[96:97]
	global_store_dwordx4 v[114:115], v[104:107], off nt
	v_cvt_pk_bf16_f32 v98, v100, v101
	s_waitcnt lgkmcnt(0)
	v_add_f32_e32 v96, v99, v113
	ds_bpermute_b32 v97, v112, v96
	v_cvt_pk_bf16_f32 v99, v102, v103
	v_cvt_pk_bf16_f32 v100, v110, v111
	v_cvt_pk_bf16_f32 v101, v108, v109
	global_store_dwordx4 v[114:115], v[98:101], off offset:256 nt
	s_and_saveexec_b64 s[30:31], s[0:1]
	s_cbranch_execz .LBB0_920
	v_lshlrev_b64 v[98:99], 6, v[184:185]
	v_lshl_add_u64 v[98:99], s[20:21], 0, v[98:99]
	v_lshl_add_u64 v[98:99], s[28:29], 2, v[98:99]
	s_lshl_b32 s8, s40, 2
	v_lshl_add_u64 v[98:99], v[98:99], 0, s[8:9]
	s_waitcnt lgkmcnt(0)
	v_add_f32_e32 v96, v96, v97
	global_store_dword v[98:99], v96, off
.LBB0_920:
	s_or_b64 exec, exec, s[30:31]
	v_lshlrev_b32_e32 v96, 16, v140
	s_waitcnt lgkmcnt(0)
	v_and_b32_e32 v97, 0xffff0000, v140
	v_lshlrev_b32_e32 v98, 16, v141
	v_and_b32_e32 v99, 0xffff0000, v141
	v_lshlrev_b32_e32 v100, 16, v142
	v_and_b32_e32 v101, 0xffff0000, v142
	v_lshlrev_b32_e32 v102, 16, v143
	v_and_b32_e32 v103, 0xffff0000, v143
	v_pk_add_f32 v[94:95], v[94:95], v[98:99]
	v_pk_add_f32 v[92:93], v[92:93], v[96:97]
	v_pk_add_f32 v[96:97], v[90:91], v[102:103]
	v_pk_add_f32 v[90:91], v[88:89], v[100:101]
	v_mul_f32_e32 v88, v93, v93
	v_mul_f32_e32 v89, v95, v95
	v_fmac_f32_e32 v88, v92, v92
	v_fmac_f32_e32 v89, v94, v94
	v_add_f32_e32 v88, v88, v89
	v_mul_f32_e32 v89, v91, v91
	v_fmac_f32_e32 v89, v90, v90
	v_add_f32_e32 v88, v89, v88
	v_mul_f32_e32 v89, v97, v97
	v_fmac_f32_e32 v89, v96, v96
	v_add_f32_e32 v100, v89, v88
	v_cvt_pk_bf16_f32 v88, v92, v93
	v_cvt_pk_bf16_f32 v89, v94, v95
	v_lshlrev_b32_e32 v92, 16, v136
	v_and_b32_e32 v93, 0xffff0000, v136
	v_lshlrev_b32_e32 v94, 16, v137
	v_and_b32_e32 v95, 0xffff0000, v137
	v_cvt_pk_bf16_f32 v90, v90, v91
	v_cvt_pk_bf16_f32 v91, v96, v97
	v_lshlrev_b32_e32 v96, 16, v138
	v_and_b32_e32 v97, 0xffff0000, v138
	v_pk_add_f32 v[86:87], v[86:87], v[94:95]
	v_pk_add_f32 v[84:85], v[84:85], v[92:93]
	v_pk_add_f32 v[94:95], v[80:81], v[96:97]
	v_mul_f32_e32 v80, v85, v85
	v_mul_f32_e32 v81, v87, v87
	v_fmac_f32_e32 v80, v84, v84
	v_fmac_f32_e32 v81, v86, v86
	v_lshlrev_b32_e32 v98, 16, v139
	v_and_b32_e32 v99, 0xffff0000, v139
	v_add_f32_e32 v80, v80, v81
	v_mul_f32_e32 v81, v95, v95
	v_pk_add_f32 v[92:93], v[82:83], v[98:99]
	v_fmac_f32_e32 v81, v94, v94
	v_add_f32_e32 v80, v81, v80
	v_mul_f32_e32 v81, v93, v93
	v_fmac_f32_e32 v81, v92, v92
	v_add_f32_e32 v80, v81, v80
	v_add_f32_e32 v83, v100, v80
	ds_bpermute_b32 v98, v195, v83
	v_lshl_add_u64 v[80:81], s[12:13], 0, v[182:183]
	v_lshl_add_u64 v[96:97], v[170:171], 1, v[80:81]
	global_store_dwordx4 v[96:97], v[88:91], off nt
	v_cvt_pk_bf16_f32 v82, v84, v85
	s_waitcnt lgkmcnt(0)
	v_add_f32_e32 v80, v83, v98
	ds_bpermute_b32 v81, v112, v80
	v_cvt_pk_bf16_f32 v83, v86, v87
	v_cvt_pk_bf16_f32 v84, v94, v95
	v_cvt_pk_bf16_f32 v85, v92, v93
	global_store_dwordx4 v[96:97], v[82:85], off offset:256 nt
	s_and_saveexec_b64 s[30:31], s[0:1]
	s_cbranch_execz .LBB0_922
	v_lshlrev_b64 v[82:83], 6, v[180:181]
	v_lshl_add_u64 v[82:83], s[20:21], 0, v[82:83]
	v_lshl_add_u64 v[82:83], s[28:29], 2, v[82:83]
	s_lshl_b32 s8, s40, 2
	v_lshl_add_u64 v[82:83], v[82:83], 0, s[8:9]
	s_waitcnt lgkmcnt(0)
	v_add_f32_e32 v80, v80, v81
	global_store_dword v[82:83], v80, off
; __device__ __forceinline__ unsigned pk2(float a, float b) { return pg8::cvt_pk_bf16(a, b); }
; __device__ __forceinline__ void unpack8(const u32x4 w, float (&f)[8]) { f[0] = bf_lo(w.x); f[1] = bf_hi(w.x); f[2] = bf_lo(w.y); f[3] = bf_hi(w.y); f[4] = bf_lo(w.z); f[5] = bf_hi(w.z); f[6] = bf_lo(w.w); f[7] = bf_hi(w.w); }
;     __device__ __forceinline__ void operator()(f32x4 (&acc)[2][2][4][2], const pg8::Unit& u, int wr, int wc, int fr, int fq) const {
;     ...
;         for (int ai = 0; ai < 2; ++ai) {
;             u32x4 rx[4][2];
; #pragma unroll
;             for (int m = 0; m < 4; ++m)
; #pragma unroll
;                 for (int bj = 0; bj < 2; ++bj) rx[m][bj] = *(const u32x4*)(XB + (size_t)(row0 + ai * 128 + m * 16) * 1024 + col0 + bj * 128);
; #pragma unroll
;             for (int m = 0; m < 4; ++m) { const int row = row0 + ai * 128 + m * 16; float s = 0.f;
; #pragma unroll
;                 for (int bj = 0; bj < 2; ++bj) { float f[8]; unpack8(rx[m][bj], f);
;                     const f32x4 v0 = acc[ai][bj][m][0] + (f32x4){f[0], f[1], f[2], f[3]}, v1 = acc[ai][bj][m][1] + (f32x4){f[4], f[5], f[6], f[7]};
;                     s += (v0[0] * v0[0] + v0[1] * v0[1]) + (v0[2] * v0[2] + v0[3] * v0[3]) + (v1[0] * v1[0] + v1[1] * v1[1]) + (v1[2] * v1[2] + v1[3] * v1[3]);
;                     u32x4 w; w.x = pk2(v0[0], v0[1]); w.y = pk2(v0[2], v0[3]); w.z = pk2(v1[0], v1[1]); w.w = pk2(v1[2], v1[3]);
;                     *(u32x4*)(YB + (size_t)row * 1024 + col0 + bj * 128) = w; }
;                 s += __shfl_xor(s, 16); s += __shfl_xor(s, 32); if (fq == 0) SS[(size_t)row * 16 + u.pn * 4 + wc] = s; }
.LBB0_922:
	s_or_b64 exec, exec, s[30:31]
	v_lshlrev_b32_e32 v80, 16, v132
	s_waitcnt lgkmcnt(0)
	v_and_b32_e32 v81, 0xffff0000, v132
	v_lshlrev_b32_e32 v82, 16, v133
	v_and_b32_e32 v83, 0xffff0000, v133
	v_lshlrev_b32_e32 v84, 16, v134
	v_and_b32_e32 v85, 0xffff0000, v134
	v_lshlrev_b32_e32 v86, 16, v135
	v_and_b32_e32 v87, 0xffff0000, v135
	v_pk_add_f32 v[78:79], v[78:79], v[82:83]
	v_pk_add_f32 v[76:77], v[76:77], v[80:81]
	v_pk_add_f32 v[80:81], v[74:75], v[86:87]
	v_pk_add_f32 v[74:75], v[72:73], v[84:85]
	v_mul_f32_e32 v72, v77, v77
	v_mul_f32_e32 v73, v79, v79
	v_fmac_f32_e32 v72, v76, v76
	v_fmac_f32_e32 v73, v78, v78
	v_add_f32_e32 v72, v72, v73
	v_mul_f32_e32 v73, v75, v75
	v_fmac_f32_e32 v73, v74, v74
	v_add_f32_e32 v72, v73, v72
	v_mul_f32_e32 v73, v81, v81
	v_fmac_f32_e32 v73, v80, v80
	v_add_f32_e32 v84, v73, v72
	v_cvt_pk_bf16_f32 v72, v76, v77
	v_cvt_pk_bf16_f32 v73, v78, v79
	v_lshlrev_b32_e32 v76, 16, v128
	v_and_b32_e32 v77, 0xffff0000, v128
	v_lshlrev_b32_e32 v78, 16, v129
	v_and_b32_e32 v79, 0xffff0000, v129
	v_cvt_pk_bf16_f32 v74, v74, v75
	v_cvt_pk_bf16_f32 v75, v80, v81
	v_lshlrev_b32_e32 v80, 16, v130
	v_and_b32_e32 v81, 0xffff0000, v130
	v_pk_add_f32 v[70:71], v[70:71], v[78:79]
	v_pk_add_f32 v[68:69], v[68:69], v[76:77]
	v_pk_add_f32 v[78:79], v[64:65], v[80:81]
	v_mul_f32_e32 v64, v69, v69
	v_mul_f32_e32 v65, v71, v71
	v_fmac_f32_e32 v64, v68, v68
	v_fmac_f32_e32 v65, v70, v70
	v_lshlrev_b32_e32 v82, 16, v131
	v_and_b32_e32 v83, 0xffff0000, v131
	v_add_f32_e32 v64, v64, v65
	v_mul_f32_e32 v65, v79, v79
	v_pk_add_f32 v[76:77], v[66:67], v[82:83]
	v_fmac_f32_e32 v65, v78, v78
	v_add_f32_e32 v64, v65, v64
	v_mul_f32_e32 v65, v77, v77
	v_fmac_f32_e32 v65, v76, v76
	v_add_f32_e32 v64, v65, v64
	v_add_f32_e32 v67, v84, v64
	ds_bpermute_b32 v82, v195, v67
	v_lshl_add_u64 v[64:65], s[12:13], 0, v[178:179]
	v_lshl_add_u64 v[80:81], v[170:171], 1, v[64:65]
	global_store_dwordx4 v[80:81], v[72:75], off nt
	v_cvt_pk_bf16_f32 v66, v68, v69
	s_waitcnt lgkmcnt(0)
	v_add_f32_e32 v64, v67, v82
	ds_bpermute_b32 v65, v112, v64
	v_cvt_pk_bf16_f32 v67, v70, v71
	v_cvt_pk_bf16_f32 v68, v78, v79
	v_cvt_pk_bf16_f32 v69, v76, v77
	global_store_dwordx4 v[80:81], v[66:69], off offset:256 nt
	s_and_saveexec_b64 s[30:31], s[0:1]
	s_cbranch_execz .LBB0_924
	v_lshlrev_b64 v[66:67], 6, v[176:177]
	v_lshl_add_u64 v[66:67], s[20:21], 0, v[66:67]
	v_lshl_add_u64 v[66:67], s[28:29], 2, v[66:67]
	s_lshl_b32 s8, s40, 2
	v_lshl_add_u64 v[66:67], v[66:67], 0, s[8:9]
	s_waitcnt lgkmcnt(0)
	v_add_f32_e32 v64, v64, v65
	global_store_dword v[66:67], v64, off
.LBB0_924:
	s_or_b64 exec, exec, s[30:31]
	v_add_u32_e32 v100, 0x80, v174
	v_ashrrev_i32_e32 v101, 31, v100
	v_lshlrev_b64 v[110:111], 11, v[100:101]
	s_waitcnt lgkmcnt(0)
	v_lshl_add_u64 v[64:65], v[172:173], 0, v[110:111]
	global_load_dwordx4 v[102:105], v[64:65], off
	global_load_dwordx4 v[106:109], v[64:65], off offset:256
	v_add_u32_e32 v96, 0x90, v174
	v_add_u32_e32 v92, 0xa0, v174
	v_add_u32_e32 v88, 0xb0, v174
	v_ashrrev_i32_e32 v97, 31, v96
	v_ashrrev_i32_e32 v93, 31, v92
	v_ashrrev_i32_e32 v89, 31, v88
	v_lshlrev_b64 v[98:99], 11, v[96:97]
	v_lshlrev_b64 v[94:95], 11, v[92:93]
	v_lshlrev_b64 v[90:91], 11, v[88:89]
	v_lshl_add_u64 v[64:65], v[172:173], 0, v[98:99]
	v_lshl_add_u64 v[66:67], v[172:173], 0, v[94:95]
	v_lshl_add_u64 v[114:115], v[172:173], 0, v[90:91]
	global_load_dwordx4 v[84:87], v[64:65], off
	global_load_dwordx4 v[80:83], v[64:65], off offset:256
	global_load_dwordx4 v[76:79], v[66:67], off
	global_load_dwordx4 v[72:75], v[66:67], off offset:256
	global_load_dwordx4 v[68:71], v[114:115], off
	s_nop 0
	global_load_dwordx4 v[64:67], v[114:115], off offset:256
	s_waitcnt vmcnt(7)
	v_lshlrev_b32_e32 v114, 16, v102
	v_and_b32_e32 v115, 0xffff0000, v102
	v_lshlrev_b32_e32 v102, 16, v103
	v_and_b32_e32 v103, 0xffff0000, v103
	v_lshlrev_b32_e32 v116, 16, v104
	v_and_b32_e32 v117, 0xffff0000, v104
	v_lshlrev_b32_e32 v104, 16, v105
	v_and_b32_e32 v105, 0xffff0000, v105
	s_waitcnt vmcnt(6)
	v_lshlrev_b32_e32 v118, 16, v106
	v_and_b32_e32 v119, 0xffff0000, v106
	v_lshlrev_b32_e32 v106, 16, v107
	v_and_b32_e32 v107, 0xffff0000, v107
	v_lshlrev_b32_e32 v120, 16, v108
	v_and_b32_e32 v121, 0xffff0000, v108
	v_lshlrev_b32_e32 v108, 16, v109
	v_and_b32_e32 v109, 0xffff0000, v109
	v_pk_add_f32 v[62:63], v[62:63], v[102:103]
	v_pk_add_f32 v[60:61], v[60:61], v[114:115]
	v_pk_add_f32 v[58:59], v[58:59], v[104:105]
	v_pk_add_f32 v[56:57], v[56:57], v[116:117]
	v_pk_add_f32 v[54:55], v[54:55], v[106:107]
	v_pk_add_f32 v[52:53], v[52:53], v[118:119]
	v_pk_add_f32 v[102:103], v[50:51], v[108:109]
	v_pk_add_f32 v[104:105], v[48:49], v[120:121]
	v_mul_f32_e32 v106, v61, v61
	v_mul_f32_e32 v107, v63, v63
	v_mul_f32_e32 v108, v57, v57
	v_mul_f32_e32 v109, v59, v59
	v_cvt_pk_bf16_f32 v48, v60, v61
	v_cvt_pk_bf16_f32 v49, v62, v63
	v_cvt_pk_bf16_f32 v50, v56, v57
	v_cvt_pk_bf16_f32 v51, v58, v59
	v_mul_f32_e32 v57, v53, v53
	v_mul_f32_e32 v59, v55, v55
	v_mul_f32_e32 v61, v105, v105
	v_fmac_f32_e32 v106, v60, v60
	v_fmac_f32_e32 v107, v62, v62
	v_fmac_f32_e32 v57, v52, v52
	v_fmac_f32_e32 v59, v54, v54
	v_mul_f32_e32 v63, v103, v103
	v_fmac_f32_e32 v108, v56, v56
	v_fmac_f32_e32 v61, v104, v104
	v_add_f32_e32 v56, v106, v107
	v_add_f32_e32 v57, v57, v59
	v_fmac_f32_e32 v109, v58, v58
	v_fmac_f32_e32 v63, v102, v102
	v_add_f32_e32 v56, v108, v56
	v_add_f32_e32 v57, v61, v57
	v_add_f32_e32 v56, v109, v56
	v_add_f32_e32 v57, v63, v57
	v_add_f32_e32 v58, v56, v57
	ds_bpermute_b32 v59, v195, v58
	v_lshl_add_u64 v[56:57], s[12:13], 0, v[110:111]
	v_lshl_add_u64 v[56:57], v[170:171], 1, v[56:57]
	global_store_dwordx4 v[56:57], v[48:51], off nt
	s_waitcnt lgkmcnt(0)
	s_nop 0
	v_add_f32_e32 v48, v58, v59
	ds_bpermute_b32 v49, v112, v48
	v_cvt_pk_bf16_f32 v50, v52, v53
	v_cvt_pk_bf16_f32 v51, v54, v55
	v_cvt_pk_bf16_f32 v52, v104, v105
	v_cvt_pk_bf16_f32 v53, v102, v103
	global_store_dwordx4 v[56:57], v[50:53], off offset:256 nt
	s_and_saveexec_b64 s[30:31], s[0:1]
	s_cbranch_execz .LBB0_926
	v_lshlrev_b64 v[50:51], 6, v[100:101]
	v_lshl_add_u64 v[50:51], s[20:21], 0, v[50:51]
	v_lshl_add_u64 v[50:51], s[28:29], 2, v[50:51]
	s_lshl_b32 s8, s40, 2
	v_lshl_add_u64 v[50:51], v[50:51], 0, s[8:9]
	s_waitcnt lgkmcnt(0)
	v_add_f32_e32 v48, v48, v49
	global_store_dword v[50:51], v48, off
; __device__ __forceinline__ unsigned pk2(float a, float b) { return pg8::cvt_pk_bf16(a, b); }
; __device__ __forceinline__ void unpack8(const u32x4 w, float (&f)[8]) { f[0] = bf_lo(w.x); f[1] = bf_hi(w.x); f[2] = bf_lo(w.y); f[3] = bf_hi(w.y); f[4] = bf_lo(w.z); f[5] = bf_hi(w.z); f[6] = bf_lo(w.w); f[7] = bf_hi(w.w); }
;     __device__ __forceinline__ void operator()(f32x4 (&acc)[2][2][4][2], const pg8::Unit& u, int wr, int wc, int fr, int fq) const {
;     ...
;             for (int m = 0; m < 4; ++m) { const int row = row0 + ai * 128 + m * 16; float s = 0.f;
; #pragma unroll
;                 for (int bj = 0; bj < 2; ++bj) { float f[8]; unpack8(rx[m][bj], f);
;                     const f32x4 v0 = acc[ai][bj][m][0] + (f32x4){f[0], f[1], f[2], f[3]}, v1 = acc[ai][bj][m][1] + (f32x4){f[4], f[5], f[6], f[7]};
;                     s += (v0[0] * v0[0] + v0[1] * v0[1]) + (v0[2] * v0[2] + v0[3] * v0[3]) + (v1[0] * v1[0] + v1[1] * v1[1]) + (v1[2] * v1[2] + v1[3] * v1[3]);
;                     u32x4 w; w.x = pk2(v0[0], v0[1]); w.y = pk2(v0[2], v0[3]); w.z = pk2(v1[0], v1[1]); w.w = pk2(v1[2], v1[3]);
;                     *(u32x4*)(YB + (size_t)row * 1024 + col0 + bj * 128) = w; }
;                 s += __shfl_xor(s, 16); s += __shfl_xor(s, 32); if (fq == 0) SS[(size_t)row * 16 + u.pn * 4 + wc] = s; }
.LBB0_926:
	s_or_b64 exec, exec, s[30:31]
	s_waitcnt vmcnt(7)
	v_lshlrev_b32_e32 v48, 16, v84
	s_waitcnt lgkmcnt(0)
	v_and_b32_e32 v49, 0xffff0000, v84
	v_lshlrev_b32_e32 v50, 16, v85
	v_and_b32_e32 v51, 0xffff0000, v85
	v_lshlrev_b32_e32 v52, 16, v86
	v_and_b32_e32 v53, 0xffff0000, v86
	v_lshlrev_b32_e32 v54, 16, v87
	v_and_b32_e32 v55, 0xffff0000, v87
	v_pk_add_f32 v[46:47], v[46:47], v[50:51]
	v_pk_add_f32 v[44:45], v[44:45], v[48:49]
	v_pk_add_f32 v[48:49], v[42:43], v[54:55]
	v_pk_add_f32 v[42:43], v[40:41], v[52:53]
	v_mul_f32_e32 v40, v45, v45
	v_mul_f32_e32 v41, v47, v47
	v_fmac_f32_e32 v40, v44, v44
	v_fmac_f32_e32 v41, v46, v46
	v_add_f32_e32 v40, v40, v41
	v_mul_f32_e32 v41, v43, v43
	v_fmac_f32_e32 v41, v42, v42
	v_add_f32_e32 v40, v41, v40
	v_mul_f32_e32 v41, v49, v49
	v_fmac_f32_e32 v41, v48, v48
	v_add_f32_e32 v52, v41, v40
	v_cvt_pk_bf16_f32 v40, v44, v45
	v_cvt_pk_bf16_f32 v41, v46, v47
	s_waitcnt vmcnt(6)
	v_lshlrev_b32_e32 v44, 16, v80
	v_and_b32_e32 v45, 0xffff0000, v80
	v_lshlrev_b32_e32 v46, 16, v81
	v_and_b32_e32 v47, 0xffff0000, v81
	v_cvt_pk_bf16_f32 v42, v42, v43
	v_cvt_pk_bf16_f32 v43, v48, v49
	v_lshlrev_b32_e32 v48, 16, v82
	v_and_b32_e32 v49, 0xffff0000, v82
	v_pk_add_f32 v[38:39], v[38:39], v[46:47]
	v_pk_add_f32 v[36:37], v[36:37], v[44:45]
	v_pk_add_f32 v[46:47], v[32:33], v[48:49]
	v_mul_f32_e32 v32, v37, v37
	v_mul_f32_e32 v33, v39, v39
	v_fmac_f32_e32 v32, v36, v36
	v_fmac_f32_e32 v33, v38, v38
	v_lshlrev_b32_e32 v50, 16, v83
	v_and_b32_e32 v51, 0xffff0000, v83
	v_add_f32_e32 v32, v32, v33
	v_mul_f32_e32 v33, v47, v47
	v_pk_add_f32 v[44:45], v[34:35], v[50:51]
	v_fmac_f32_e32 v33, v46, v46
	v_add_f32_e32 v32, v33, v32
	v_mul_f32_e32 v33, v45, v45
	v_fmac_f32_e32 v33, v44, v44
	v_add_f32_e32 v32, v33, v32
	v_add_f32_e32 v35, v52, v32
	ds_bpermute_b32 v50, v195, v35
	v_lshl_add_u64 v[32:33], s[12:13], 0, v[98:99]
	v_lshl_add_u64 v[48:49], v[170:171], 1, v[32:33]
	global_store_dwordx4 v[48:49], v[40:43], off nt
	v_cvt_pk_bf16_f32 v34, v36, v37
	s_waitcnt lgkmcnt(0)
	v_add_f32_e32 v32, v35, v50
	ds_bpermute_b32 v33, v112, v32
	v_cvt_pk_bf16_f32 v35, v38, v39
	v_cvt_pk_bf16_f32 v36, v46, v47
	v_cvt_pk_bf16_f32 v37, v44, v45
	global_store_dwordx4 v[48:49], v[34:37], off offset:256 nt
	s_and_saveexec_b64 s[30:31], s[0:1]
	s_cbranch_execz .LBB0_928
	v_lshlrev_b64 v[34:35], 6, v[96:97]
	v_lshl_add_u64 v[34:35], s[20:21], 0, v[34:35]
	v_lshl_add_u64 v[34:35], s[28:29], 2, v[34:35]
	s_lshl_b32 s8, s40, 2
	v_lshl_add_u64 v[34:35], v[34:35], 0, s[8:9]
	s_waitcnt lgkmcnt(0)
	v_add_f32_e32 v32, v32, v33
	global_store_dword v[34:35], v32, off
; __device__ __forceinline__ unsigned pk2(float a, float b) { return pg8::cvt_pk_bf16(a, b); }
; __device__ __forceinline__ void unpack8(const u32x4 w, float (&f)[8]) { f[0] = bf_lo(w.x); f[1] = bf_hi(w.x); f[2] = bf_lo(w.y); f[3] = bf_hi(w.y); f[4] = bf_lo(w.z); f[5] = bf_hi(w.z); f[6] = bf_lo(w.w); f[7] = bf_hi(w.w); }
;     __device__ __forceinline__ void operator()(f32x4 (&acc)[2][2][4][2], const pg8::Unit& u, int wr, int wc, int fr, int fq) const {
;     ...
;             for (int m = 0; m < 4; ++m) { const int row = row0 + ai * 128 + m * 16; float s = 0.f;
; #pragma unroll
;                 for (int bj = 0; bj < 2; ++bj) { float f[8]; unpack8(rx[m][bj], f);
;                     const f32x4 v0 = acc[ai][bj][m][0] + (f32x4){f[0], f[1], f[2], f[3]}, v1 = acc[ai][bj][m][1] + (f32x4){f[4], f[5], f[6], f[7]};
;                     s += (v0[0] * v0[0] + v0[1] * v0[1]) + (v0[2] * v0[2] + v0[3] * v0[3]) + (v1[0] * v1[0] + v1[1] * v1[1]) + (v1[2] * v1[2] + v1[3] * v1[3]);
;                     u32x4 w; w.x = pk2(v0[0], v0[1]); w.y = pk2(v0[2], v0[3]); w.z = pk2(v1[0], v1[1]); w.w = pk2(v1[2], v1[3]);
;                     *(u32x4*)(YB + (size_t)row * 1024 + col0 + bj * 128) = w; }
;                 s += __shfl_xor(s, 16); s += __shfl_xor(s, 32); if (fq == 0) SS[(size_t)row * 16 + u.pn * 4 + wc] = s; }
.LBB0_928:
	s_or_b64 exec, exec, s[30:31]
	s_waitcnt vmcnt(7)
	v_lshlrev_b32_e32 v32, 16, v76
	s_waitcnt lgkmcnt(0)
	v_and_b32_e32 v33, 0xffff0000, v76
	v_lshlrev_b32_e32 v34, 16, v77
	v_and_b32_e32 v35, 0xffff0000, v77
	v_lshlrev_b32_e32 v36, 16, v78
	v_and_b32_e32 v37, 0xffff0000, v78
	v_lshlrev_b32_e32 v38, 16, v79
	v_and_b32_e32 v39, 0xffff0000, v79
	v_pk_add_f32 v[30:31], v[30:31], v[34:35]
	v_pk_add_f32 v[28:29], v[28:29], v[32:33]
	v_pk_add_f32 v[32:33], v[26:27], v[38:39]
	v_pk_add_f32 v[26:27], v[24:25], v[36:37]
	v_mul_f32_e32 v24, v29, v29
	v_mul_f32_e32 v25, v31, v31
	v_fmac_f32_e32 v24, v28, v28
	v_fmac_f32_e32 v25, v30, v30
	v_add_f32_e32 v24, v24, v25
	v_mul_f32_e32 v25, v27, v27
	v_fmac_f32_e32 v25, v26, v26
	v_add_f32_e32 v24, v25, v24
	v_mul_f32_e32 v25, v33, v33
	v_fmac_f32_e32 v25, v32, v32
	v_add_f32_e32 v36, v25, v24
	v_cvt_pk_bf16_f32 v24, v28, v29
	v_cvt_pk_bf16_f32 v25, v30, v31
	s_waitcnt vmcnt(6)
	v_lshlrev_b32_e32 v28, 16, v72
	v_and_b32_e32 v29, 0xffff0000, v72
	v_lshlrev_b32_e32 v30, 16, v73
	v_and_b32_e32 v31, 0xffff0000, v73
	v_cvt_pk_bf16_f32 v26, v26, v27
	v_cvt_pk_bf16_f32 v27, v32, v33
	v_lshlrev_b32_e32 v32, 16, v74
	v_and_b32_e32 v33, 0xffff0000, v74
	v_pk_add_f32 v[22:23], v[22:23], v[30:31]
	v_pk_add_f32 v[20:21], v[20:21], v[28:29]
	v_pk_add_f32 v[30:31], v[16:17], v[32:33]
	v_mul_f32_e32 v16, v21, v21
	v_mul_f32_e32 v17, v23, v23
	v_fmac_f32_e32 v16, v20, v20
	v_fmac_f32_e32 v17, v22, v22
	v_lshlrev_b32_e32 v34, 16, v75
	v_and_b32_e32 v35, 0xffff0000, v75
	v_add_f32_e32 v16, v16, v17
	v_mul_f32_e32 v17, v31, v31
	v_pk_add_f32 v[28:29], v[18:19], v[34:35]
	v_fmac_f32_e32 v17, v30, v30
	v_add_f32_e32 v16, v17, v16
	v_mul_f32_e32 v17, v29, v29
	v_fmac_f32_e32 v17, v28, v28
	v_add_f32_e32 v16, v17, v16
	v_add_f32_e32 v19, v36, v16
	ds_bpermute_b32 v34, v195, v19
	v_lshl_add_u64 v[16:17], s[12:13], 0, v[94:95]
	v_lshl_add_u64 v[32:33], v[170:171], 1, v[16:17]
	global_store_dwordx4 v[32:33], v[24:27], off nt
	v_cvt_pk_bf16_f32 v18, v20, v21
	s_waitcnt lgkmcnt(0)
	v_add_f32_e32 v16, v19, v34
	ds_bpermute_b32 v17, v112, v16
	v_cvt_pk_bf16_f32 v19, v22, v23
	v_cvt_pk_bf16_f32 v20, v30, v31
	v_cvt_pk_bf16_f32 v21, v28, v29
	global_store_dwordx4 v[32:33], v[18:21], off offset:256 nt
	s_and_saveexec_b64 s[30:31], s[0:1]
	s_cbranch_execz .LBB0_930
	v_lshlrev_b64 v[18:19], 6, v[92:93]
	v_lshl_add_u64 v[18:19], s[20:21], 0, v[18:19]
	v_lshl_add_u64 v[18:19], s[28:29], 2, v[18:19]
	s_lshl_b32 s8, s40, 2
	v_lshl_add_u64 v[18:19], v[18:19], 0, s[8:9]
	s_waitcnt lgkmcnt(0)
	v_add_f32_e32 v16, v16, v17
	global_store_dword v[18:19], v16, off
.LBB0_930:
	s_or_b64 exec, exec, s[30:31]
	s_waitcnt vmcnt(7)
	v_lshlrev_b32_e32 v16, 16, v68
	s_waitcnt lgkmcnt(0)
	v_and_b32_e32 v17, 0xffff0000, v68
	v_lshlrev_b32_e32 v18, 16, v69
	v_and_b32_e32 v19, 0xffff0000, v69
	v_lshlrev_b32_e32 v20, 16, v70
	v_and_b32_e32 v21, 0xffff0000, v70
	v_lshlrev_b32_e32 v22, 16, v71
	v_and_b32_e32 v23, 0xffff0000, v71
	v_pk_add_f32 v[14:15], v[14:15], v[18:19]
	v_pk_add_f32 v[12:13], v[12:13], v[16:17]
	v_pk_add_f32 v[16:17], v[10:11], v[22:23]
	v_pk_add_f32 v[10:11], v[8:9], v[20:21]
	v_mul_f32_e32 v8, v13, v13
	v_mul_f32_e32 v9, v15, v15
	v_fmac_f32_e32 v8, v12, v12
	v_fmac_f32_e32 v9, v14, v14
	v_add_f32_e32 v8, v8, v9
	v_mul_f32_e32 v9, v11, v11
	v_fmac_f32_e32 v9, v10, v10
	v_add_f32_e32 v8, v9, v8
	v_mul_f32_e32 v9, v17, v17
	v_fmac_f32_e32 v9, v16, v16
	v_add_f32_e32 v20, v9, v8
	v_cvt_pk_bf16_f32 v8, v12, v13
	v_cvt_pk_bf16_f32 v9, v14, v15
	s_waitcnt vmcnt(6)
	v_lshlrev_b32_e32 v12, 16, v64
	v_and_b32_e32 v13, 0xffff0000, v64
	v_lshlrev_b32_e32 v14, 16, v65
	v_and_b32_e32 v15, 0xffff0000, v65
	v_cvt_pk_bf16_f32 v10, v10, v11
	v_cvt_pk_bf16_f32 v11, v16, v17
	v_lshlrev_b32_e32 v16, 16, v66
	v_and_b32_e32 v17, 0xffff0000, v66
	v_pk_add_f32 v[6:7], v[6:7], v[14:15]
	v_pk_add_f32 v[4:5], v[4:5], v[12:13]
	v_pk_add_f32 v[14:15], v[0:1], v[16:17]
	v_mul_f32_e32 v0, v5, v5
	v_mul_f32_e32 v1, v7, v7
	v_fmac_f32_e32 v0, v4, v4
	v_fmac_f32_e32 v1, v6, v6
	v_lshlrev_b32_e32 v18, 16, v67
	v_and_b32_e32 v19, 0xffff0000, v67
	v_add_f32_e32 v0, v0, v1
	v_mul_f32_e32 v1, v15, v15
	v_pk_add_f32 v[12:13], v[2:3], v[18:19]
	v_fmac_f32_e32 v1, v14, v14
	v_add_f32_e32 v0, v1, v0
	v_mul_f32_e32 v1, v13, v13
	v_fmac_f32_e32 v1, v12, v12
	v_add_f32_e32 v0, v1, v0
	v_add_f32_e32 v3, v20, v0
	ds_bpermute_b32 v18, v195, v3
	v_lshl_add_u64 v[0:1], s[12:13], 0, v[90:91]
	v_lshl_add_u64 v[16:17], v[170:171], 1, v[0:1]
	global_store_dwordx4 v[16:17], v[8:11], off nt
	v_cvt_pk_bf16_f32 v2, v4, v5
	s_waitcnt lgkmcnt(0)
	v_add_f32_e32 v0, v3, v18
	ds_bpermute_b32 v1, v112, v0
	v_cvt_pk_bf16_f32 v3, v6, v7
	v_cvt_pk_bf16_f32 v4, v14, v15
	v_cvt_pk_bf16_f32 v5, v12, v13
	global_store_dwordx4 v[16:17], v[2:5], off offset:256 nt
	s_and_saveexec_b64 s[30:31], s[0:1]
	s_cbranch_execz .LBB0_932
	v_lshlrev_b64 v[2:3], 6, v[88:89]
	v_lshl_add_u64 v[2:3], s[20:21], 0, v[2:3]
	v_lshl_add_u64 v[2:3], s[28:29], 2, v[2:3]
	s_lshl_b32 s8, s40, 2
	v_lshl_add_u64 v[2:3], v[2:3], 0, s[8:9]
	s_waitcnt lgkmcnt(0)
	v_add_f32_e32 v0, v0, v1
	global_store_dword v[2:3], v0, off
